# v35 + residual-add GEMMs: each wave owns 64 contiguous output columns (weight-fragment LDS reads re-based), so the residual epilogue loads/stores touch full 128-byte lines
# speedup vs baseline: 1.0099x; 1.0099x over previous
.LBB0_985:
	v_and_b32_e32 v15, 15, v0
	v_lshlrev_b32_e32 v16, 1, v13
	v_lshlrev_b32_e32 v17, 2, v0
	s_sext_i32_i8 s73, s0
	v_lshl_or_b32 v1, s3, 6, v15
	v_lshl_or_b32 v15, v15, 6, v16
	s_lshl_b32 s0, s3, 13
	v_and_b32_e32 v17, 32, v17
	v_bitop3_b32 v15, v15, s0, v17 bitop3:0xde
	s_lshl_b32 s0, s1, 5
	s_mov_b64 s[8:9], 0x80
	s_and_b32 s3, s0, 0x60
	v_lshlrev_b32_e32 v18, 6, v0
	s_movk_i32 s0, 0x3c0
	s_add_i32 m0, s33, 0x18000
	v_lshl_add_u64 v[8:9], v[8:9], 0, s[8:9]
	v_and_or_b32 v16, v18, s0, v16
	s_lshl_b32 s0, s3, 7
	s_waitcnt vmcnt(2)
	s_barrier
	global_load_lds_dwordx4 v[8:9], off
	v_lshl_add_u64 v[4:5], v[4:5], 0, s[8:9]
	s_add_i32 m0, s33, 0x1a000
	s_add_i32 s60, s33, 0x8000
	s_add_i32 s61, s33, 0xa000
	v_bitop3_b32 v162, s0, v16, v17 bitop3:0xf6
	v_add_u32_e32 v162, s0, v162
	global_load_lds_dwordx4 v[4:5], off
	v_lshl_add_u64 v[2:3], v[2:3], 0, s[8:9]
	s_mov_b32 m0, s60
	s_add_u32 s0, s90, 0x80080
	global_load_lds_dwordx4 v[2:3], off
	v_lshl_add_u64 v[2:3], v[6:7], 0, s[8:9]
	s_mov_b32 m0, s61
	s_addc_u32 s1, s91, 0
	global_load_lds_dwordx4 v[2:3], off
	s_add_i32 m0, s33, 0x1c000
	v_lshl_add_u64 v[2:3], s[0:1], 0, v[132:133]
	global_load_lds_dwordx4 v[2:3], off
	v_lshl_add_u64 v[2:3], s[0:1], 0, v[136:137]
	s_add_i32 m0, s33, 0x1e000
	s_cmpk_lt_u32 s2, 0x100
	global_load_lds_dwordx4 v[2:3], off
	v_lshlrev_b32_e32 v2, 9, v0
	v_and_b32_e32 v2, 0x30000, v2
	v_lshlrev_b32_e32 v3, 12, v12
	v_or3_b32 v2, v10, v2, v3
	v_add_u32_e32 v138, v2, v11
	v_lshlrev_b32_e32 v2, 5, v14
	s_waitcnt vmcnt(6)
	v_and_b32_e32 v2, 0x70000, v2
	s_cselect_b64 s[78:79], -1, 0
	v_or3_b32 v2, v10, v2, v3
	s_add_i32 s71, 0, 0x10000
	s_add_i32 s72, 0, 0x14000
	s_ashr_i32 s70, s11, 31
	v_lshl_or_b32 v163, s3, 1, v13
	v_mov_b32_e32 v139, v133
	v_add_u32_e32 v140, v2, v11
	v_mov_b32_e32 v141, v133
	v_mov_b64_e32 v[142:143], 0x100
	v_mov_b64_e32 v[144:145], 0xff
	v_add_u32_e32 v164, s71, v162
	v_add_u32_e32 v165, 0x11000, v162
	v_add_u32_e32 v166, 0, v15
	s_barrier
	s_branch .LBB0_988

.LBB0_995:
	ds_read_b128 v[146:149], v164
	ds_read_b128 v[150:153], v164 offset:1024
	ds_read_b128 v[154:157], v164 offset:2048
	ds_read_b128 v[158:161], v164 offset:3072
	ds_read_b128 v[168:171], v165
	ds_read_b128 v[172:175], v165 offset:1024
	ds_read_b128 v[176:179], v165 offset:2048
	ds_read_b128 v[180:183], v165 offset:3072
	s_add_u32 s34, s88, 0xfff80080
	s_addc_u32 s35, s89, -1
	s_cmp_eq_u32 s81, 28
	s_cselect_b32 s91, s0, s35
	s_cselect_b32 s90, s1, s34
	s_cselect_b32 s35, s52, s77
	s_cselect_b32 s34, s74, s75
	v_lshl_add_u64 v[218:219], s[88:89], 0, v[138:139]
	s_add_i32 m0, s33, 0xc000
	ds_read_b128 v[184:187], v166
	ds_read_b128 v[188:191], v166 offset:1024
	ds_read_b128 v[192:195], v166 offset:2048
	ds_read_b128 v[196:199], v166 offset:3072
	ds_read_b128 v[200:203], v166 offset:4096
	ds_read_b128 v[204:207], v166 offset:5120
	ds_read_b128 v[208:211], v166 offset:6144
	ds_read_b128 v[212:215], v166 offset:7168
	global_load_lds_dwordx4 v[218:219], off
	v_lshl_add_u64 v[218:219], s[88:89], 0, v[140:141]
	s_add_i32 m0, s33, 0xe000
	s_nop 0
	global_load_lds_dwordx4 v[218:219], off
	s_waitcnt vmcnt(8)
	s_waitcnt lgkmcnt(0)
	s_barrier
	s_setprio 1
	s_waitcnt lgkmcnt(0)
	v_mfma_f32_16x16x32_bf16 v[126:129], v[146:149], v[184:187], v[126:129]
	v_mfma_f32_16x16x32_bf16 v[122:125], v[154:157], v[184:187], v[122:125]
	v_mfma_f32_16x16x32_bf16 v[110:113], v[146:149], v[192:195], v[110:113]
	v_mfma_f32_16x16x32_bf16 v[106:109], v[154:157], v[192:195], v[106:109]
	v_mfma_f32_16x16x32_bf16 v[94:97], v[146:149], v[200:203], v[94:97]
	v_mfma_f32_16x16x32_bf16 v[90:93], v[154:157], v[200:203], v[90:93]
	v_mfma_f32_16x16x32_bf16 v[78:81], v[146:149], v[208:211], v[78:81]
	v_mfma_f32_16x16x32_bf16 v[74:77], v[154:157], v[208:211], v[74:77]
	v_mfma_f32_16x16x32_bf16 v[126:129], v[150:153], v[188:191], v[126:129]
	v_mfma_f32_16x16x32_bf16 v[122:125], v[158:161], v[188:191], v[122:125]
	v_mfma_f32_16x16x32_bf16 v[110:113], v[150:153], v[196:199], v[110:113]
	v_mfma_f32_16x16x32_bf16 v[106:109], v[158:161], v[196:199], v[106:109]
	v_mfma_f32_16x16x32_bf16 v[94:97], v[150:153], v[204:207], v[94:97]
	v_mfma_f32_16x16x32_bf16 v[90:93], v[158:161], v[204:207], v[90:93]
	v_mfma_f32_16x16x32_bf16 v[78:81], v[150:153], v[212:215], v[78:81]
	v_mfma_f32_16x16x32_bf16 v[74:77], v[158:161], v[212:215], v[74:77]
	s_setprio 0
	s_setprio 1
	v_mfma_f32_16x16x32_bf16 v[118:121], v[168:171], v[184:187], v[118:121]
	v_mfma_f32_16x16x32_bf16 v[114:117], v[176:179], v[184:187], v[114:117]
	v_mfma_f32_16x16x32_bf16 v[102:105], v[168:171], v[192:195], v[102:105]
	v_mfma_f32_16x16x32_bf16 v[98:101], v[176:179], v[192:195], v[98:101]
	v_mfma_f32_16x16x32_bf16 v[86:89], v[168:171], v[200:203], v[86:89]
	v_mfma_f32_16x16x32_bf16 v[82:85], v[176:179], v[200:203], v[82:85]
	v_mfma_f32_16x16x32_bf16 v[70:73], v[168:171], v[208:211], v[70:73]
	v_mfma_f32_16x16x32_bf16 v[66:69], v[176:179], v[208:211], v[66:69]
	v_mfma_f32_16x16x32_bf16 v[118:121], v[172:175], v[188:191], v[118:121]
	v_mfma_f32_16x16x32_bf16 v[114:117], v[180:183], v[188:191], v[114:117]
	v_mfma_f32_16x16x32_bf16 v[102:105], v[172:175], v[196:199], v[102:105]
	v_mfma_f32_16x16x32_bf16 v[98:101], v[180:183], v[196:199], v[98:101]
	v_mfma_f32_16x16x32_bf16 v[86:89], v[172:175], v[204:207], v[86:89]
	v_mfma_f32_16x16x32_bf16 v[82:85], v[180:183], v[204:207], v[82:85]
	v_mfma_f32_16x16x32_bf16 v[70:73], v[172:175], v[212:215], v[70:73]
	v_mfma_f32_16x16x32_bf16 v[66:69], v[180:183], v[212:215], v[66:69]
	s_setprio 0
	s_barrier
	s_add_i32 s53, s71, s31
	v_lshl_add_u64 v[218:219], s[34:35], 0, v[132:133]
	s_mov_b32 m0, s53
	ds_read_b128 v[184:187], v166 offset:16384
	ds_read_b128 v[188:191], v166 offset:17408
	ds_read_b128 v[192:195], v166 offset:18432
	ds_read_b128 v[196:199], v166 offset:19456
	ds_read_b128 v[200:203], v166 offset:20480
	ds_read_b128 v[204:207], v166 offset:21504
	ds_read_b128 v[208:211], v166 offset:22528
	ds_read_b128 v[212:215], v166 offset:23552
	global_load_lds_dwordx4 v[218:219], off
	s_add_i32 m0, s53, 0x2000
	s_add_u32 s54, s34, 0x80000
	v_lshl_add_u64 v[220:221], s[34:35], 0, v[136:137]
	s_addc_u32 s55, s35, 0
	s_add_i32 s53, s72, s31
	global_load_lds_dwordx4 v[220:221], off
	v_lshl_add_u64 v[222:223], s[54:55], 0, v[132:133]
	s_mov_b32 m0, s53
	v_lshl_add_u64 v[224:225], s[90:91], 0, v[134:135]
	global_load_lds_dwordx4 v[222:223], off
	v_lshl_add_u64 v[222:223], s[54:55], 0, v[136:137]
	s_add_i32 m0, s53, 0x2000
	s_nop 0
	global_load_lds_dwordx4 v[222:223], off
	v_lshl_add_u64 v[222:223], s[90:91], 0, v[130:131]
	s_mov_b32 m0, s33
	s_nop 0
	global_load_lds_dwordx4 v[222:223], off
	s_mov_b32 m0, s56
	s_nop 0
	global_load_lds_dwordx4 v[224:225], off
	s_waitcnt vmcnt(8)
	s_waitcnt lgkmcnt(0)
	s_barrier
	s_setprio 1
	s_waitcnt lgkmcnt(0)
	v_mfma_f32_16x16x32_bf16 v[62:65], v[146:149], v[184:187], v[62:65]
	v_mfma_f32_16x16x32_bf16 v[58:61], v[154:157], v[184:187], v[58:61]
	v_mfma_f32_16x16x32_bf16 v[46:49], v[146:149], v[192:195], v[46:49]
	v_mfma_f32_16x16x32_bf16 v[42:45], v[154:157], v[192:195], v[42:45]
	v_mfma_f32_16x16x32_bf16 v[30:33], v[146:149], v[200:203], v[30:33]
	v_mfma_f32_16x16x32_bf16 v[26:29], v[154:157], v[200:203], v[26:29]
	v_mfma_f32_16x16x32_bf16 v[14:17], v[146:149], v[208:211], v[14:17]
	v_mfma_f32_16x16x32_bf16 v[10:13], v[154:157], v[208:211], v[10:13]
	v_mfma_f32_16x16x32_bf16 v[62:65], v[150:153], v[188:191], v[62:65]
	v_mfma_f32_16x16x32_bf16 v[58:61], v[158:161], v[188:191], v[58:61]
	v_mfma_f32_16x16x32_bf16 v[46:49], v[150:153], v[196:199], v[46:49]
	v_mfma_f32_16x16x32_bf16 v[42:45], v[158:161], v[196:199], v[42:45]
	v_mfma_f32_16x16x32_bf16 v[30:33], v[150:153], v[204:207], v[30:33]
	v_mfma_f32_16x16x32_bf16 v[26:29], v[158:161], v[204:207], v[26:29]
	v_mfma_f32_16x16x32_bf16 v[14:17], v[150:153], v[212:215], v[14:17]
	v_mfma_f32_16x16x32_bf16 v[10:13], v[158:161], v[212:215], v[10:13]
	s_setprio 0
	s_setprio 1
	v_mfma_f32_16x16x32_bf16 v[54:57], v[168:171], v[184:187], v[54:57]
	v_mfma_f32_16x16x32_bf16 v[50:53], v[176:179], v[184:187], v[50:53]
	v_mfma_f32_16x16x32_bf16 v[38:41], v[168:171], v[192:195], v[38:41]
	v_mfma_f32_16x16x32_bf16 v[34:37], v[176:179], v[192:195], v[34:37]
	v_mfma_f32_16x16x32_bf16 v[22:25], v[168:171], v[200:203], v[22:25]
	v_mfma_f32_16x16x32_bf16 v[18:21], v[176:179], v[200:203], v[18:21]
	v_mfma_f32_16x16x32_bf16 v[6:9], v[168:171], v[208:211], v[6:9]
	v_mfma_f32_16x16x32_bf16 v[2:5], v[176:179], v[208:211], v[2:5]
	v_mfma_f32_16x16x32_bf16 v[54:57], v[172:175], v[188:191], v[54:57]
	v_mfma_f32_16x16x32_bf16 v[50:53], v[180:183], v[188:191], v[50:53]
	v_mfma_f32_16x16x32_bf16 v[38:41], v[172:175], v[196:199], v[38:41]
	v_mfma_f32_16x16x32_bf16 v[34:37], v[180:183], v[196:199], v[34:37]
	v_mfma_f32_16x16x32_bf16 v[22:25], v[172:175], v[204:207], v[22:25]
	v_mfma_f32_16x16x32_bf16 v[18:21], v[180:183], v[204:207], v[18:21]
	v_mfma_f32_16x16x32_bf16 v[6:9], v[172:175], v[212:215], v[6:9]
	v_mfma_f32_16x16x32_bf16 v[2:5], v[180:183], v[212:215], v[2:5]
	s_setprio 0
	s_barrier
	s_add_i32 s53, 0, 0x18000
	s_add_i32 s62, 0, 0x1c000
	v_add_u32_e32 v158, s53, v162
	v_add_u32_e32 v167, 0x19000, v162
	ds_read_b128 v[146:149], v158
	ds_read_b128 v[150:153], v158 offset:1024
	ds_read_b128 v[154:157], v158 offset:2048
	ds_read_b128 v[158:161], v158 offset:3072
	ds_read_b128 v[168:171], v167
	ds_read_b128 v[172:175], v167 offset:1024
	ds_read_b128 v[176:179], v167 offset:2048
	ds_read_b128 v[180:183], v167 offset:3072
	s_add_u32 s54, s90, 0x80000
	s_addc_u32 s55, s91, 0
	s_mov_b32 m0, s57
	v_lshl_add_u64 v[226:227], s[54:55], 0, v[130:131]
	ds_read_b128 v[184:187], v166 offset:32768
	ds_read_b128 v[188:191], v166 offset:33792
	ds_read_b128 v[192:195], v166 offset:34816
	ds_read_b128 v[196:199], v166 offset:35840
	ds_read_b128 v[200:203], v166 offset:36864
	ds_read_b128 v[204:207], v166 offset:37888
	ds_read_b128 v[208:211], v166 offset:38912
	ds_read_b128 v[212:215], v166 offset:39936
	global_load_lds_dwordx4 v[226:227], off
	v_lshl_add_u64 v[226:227], s[54:55], 0, v[134:135]
	s_mov_b32 m0, s58
	s_nop 0
	global_load_lds_dwordx4 v[226:227], off
	s_waitcnt vmcnt(8)
	s_waitcnt lgkmcnt(0)
	s_barrier
	s_setprio 1
	s_waitcnt lgkmcnt(0)
	v_mfma_f32_16x16x32_bf16 v[126:129], v[146:149], v[184:187], v[126:129]
	v_mfma_f32_16x16x32_bf16 v[122:125], v[154:157], v[184:187], v[122:125]
	v_mfma_f32_16x16x32_bf16 v[110:113], v[146:149], v[192:195], v[110:113]
	v_mfma_f32_16x16x32_bf16 v[106:109], v[154:157], v[192:195], v[106:109]
	v_mfma_f32_16x16x32_bf16 v[94:97], v[146:149], v[200:203], v[94:97]
	v_mfma_f32_16x16x32_bf16 v[90:93], v[154:157], v[200:203], v[90:93]
	v_mfma_f32_16x16x32_bf16 v[78:81], v[146:149], v[208:211], v[78:81]
	v_mfma_f32_16x16x32_bf16 v[74:77], v[154:157], v[208:211], v[74:77]
	v_mfma_f32_16x16x32_bf16 v[126:129], v[150:153], v[188:191], v[126:129]
	v_mfma_f32_16x16x32_bf16 v[122:125], v[158:161], v[188:191], v[122:125]
	v_mfma_f32_16x16x32_bf16 v[110:113], v[150:153], v[196:199], v[110:113]
	v_mfma_f32_16x16x32_bf16 v[106:109], v[158:161], v[196:199], v[106:109]
	v_mfma_f32_16x16x32_bf16 v[94:97], v[150:153], v[204:207], v[94:97]
	v_mfma_f32_16x16x32_bf16 v[90:93], v[158:161], v[204:207], v[90:93]
	v_mfma_f32_16x16x32_bf16 v[78:81], v[150:153], v[212:215], v[78:81]
	v_mfma_f32_16x16x32_bf16 v[74:77], v[158:161], v[212:215], v[74:77]
	s_setprio 0
	s_setprio 1
	v_mfma_f32_16x16x32_bf16 v[118:121], v[168:171], v[184:187], v[118:121]
	v_mfma_f32_16x16x32_bf16 v[114:117], v[176:179], v[184:187], v[114:117]
	v_mfma_f32_16x16x32_bf16 v[102:105], v[168:171], v[192:195], v[102:105]
	v_mfma_f32_16x16x32_bf16 v[98:101], v[176:179], v[192:195], v[98:101]
	v_mfma_f32_16x16x32_bf16 v[86:89], v[168:171], v[200:203], v[86:89]
	v_mfma_f32_16x16x32_bf16 v[82:85], v[176:179], v[200:203], v[82:85]
	v_mfma_f32_16x16x32_bf16 v[70:73], v[168:171], v[208:211], v[70:73]
	v_mfma_f32_16x16x32_bf16 v[66:69], v[176:179], v[208:211], v[66:69]
	v_mfma_f32_16x16x32_bf16 v[118:121], v[172:175], v[188:191], v[118:121]
	v_mfma_f32_16x16x32_bf16 v[114:117], v[180:183], v[188:191], v[114:117]
	v_mfma_f32_16x16x32_bf16 v[102:105], v[172:175], v[196:199], v[102:105]
	v_mfma_f32_16x16x32_bf16 v[98:101], v[180:183], v[196:199], v[98:101]
	v_mfma_f32_16x16x32_bf16 v[86:89], v[172:175], v[204:207], v[86:89]
	v_mfma_f32_16x16x32_bf16 v[82:85], v[180:183], v[204:207], v[82:85]
	v_mfma_f32_16x16x32_bf16 v[70:73], v[172:175], v[212:215], v[70:73]
	v_mfma_f32_16x16x32_bf16 v[66:69], v[180:183], v[212:215], v[66:69]
	s_setprio 0
	s_barrier
	s_add_i32 s53, s53, s31
	v_lshl_add_u64 v[218:219], v[218:219], 0, s[8:9]
	s_mov_b32 m0, s53
	ds_read_b128 v[184:187], v166 offset:49152
	ds_read_b128 v[188:191], v166 offset:50176
	ds_read_b128 v[192:195], v166 offset:51200
	ds_read_b128 v[196:199], v166 offset:52224
	ds_read_b128 v[200:203], v166 offset:53248
	ds_read_b128 v[204:207], v166 offset:54272
	ds_read_b128 v[208:211], v166 offset:55296
	ds_read_b128 v[212:215], v166 offset:56320
	global_load_lds_dwordx4 v[218:219], off
	s_add_i32 m0, s53, 0x2000
	s_add_u32 s34, s34, 0x80080
	v_lshl_add_u64 v[218:219], v[220:221], 0, s[8:9]
	s_addc_u32 s35, s35, 0
	s_add_i32 s53, s62, s31
	global_load_lds_dwordx4 v[218:219], off
	v_lshl_add_u64 v[218:219], s[34:35], 0, v[132:133]
	s_mov_b32 m0, s53
	s_nop 0
	global_load_lds_dwordx4 v[218:219], off
	v_lshl_add_u64 v[218:219], s[34:35], 0, v[136:137]
	s_add_i32 m0, s53, 0x2000
	s_nop 0
	global_load_lds_dwordx4 v[218:219], off
	v_lshl_add_u64 v[218:219], v[222:223], 0, s[8:9]
	s_mov_b32 m0, s60
	s_nop 0
	global_load_lds_dwordx4 v[218:219], off
	v_lshl_add_u64 v[218:219], v[224:225], 0, s[8:9]
	s_mov_b32 m0, s61
	s_nop 0
	global_load_lds_dwordx4 v[218:219], off
	s_waitcnt vmcnt(8)
	s_waitcnt lgkmcnt(0)
	s_barrier
	s_setprio 1
	s_waitcnt lgkmcnt(0)
	v_mfma_f32_16x16x32_bf16 v[62:65], v[146:149], v[184:187], v[62:65]
	v_mfma_f32_16x16x32_bf16 v[58:61], v[154:157], v[184:187], v[58:61]
	v_mfma_f32_16x16x32_bf16 v[46:49], v[146:149], v[192:195], v[46:49]
	v_mfma_f32_16x16x32_bf16 v[42:45], v[154:157], v[192:195], v[42:45]
	v_mfma_f32_16x16x32_bf16 v[30:33], v[146:149], v[200:203], v[30:33]
	v_mfma_f32_16x16x32_bf16 v[26:29], v[154:157], v[200:203], v[26:29]
	v_mfma_f32_16x16x32_bf16 v[14:17], v[146:149], v[208:211], v[14:17]
	v_mfma_f32_16x16x32_bf16 v[10:13], v[154:157], v[208:211], v[10:13]
	v_mfma_f32_16x16x32_bf16 v[62:65], v[150:153], v[188:191], v[62:65]
	v_mfma_f32_16x16x32_bf16 v[58:61], v[158:161], v[188:191], v[58:61]
	v_mfma_f32_16x16x32_bf16 v[46:49], v[150:153], v[196:199], v[46:49]
	v_mfma_f32_16x16x32_bf16 v[42:45], v[158:161], v[196:199], v[42:45]
	v_mfma_f32_16x16x32_bf16 v[30:33], v[150:153], v[204:207], v[30:33]
	v_mfma_f32_16x16x32_bf16 v[26:29], v[158:161], v[204:207], v[26:29]
	v_mfma_f32_16x16x32_bf16 v[14:17], v[150:153], v[212:215], v[14:17]
	v_mfma_f32_16x16x32_bf16 v[10:13], v[158:161], v[212:215], v[10:13]
	s_setprio 0
	s_setprio 1
	v_mfma_f32_16x16x32_bf16 v[54:57], v[168:171], v[184:187], v[54:57]
	v_mfma_f32_16x16x32_bf16 v[50:53], v[176:179], v[184:187], v[50:53]
	v_mfma_f32_16x16x32_bf16 v[38:41], v[168:171], v[192:195], v[38:41]
	v_mfma_f32_16x16x32_bf16 v[34:37], v[176:179], v[192:195], v[34:37]
	v_mfma_f32_16x16x32_bf16 v[22:25], v[168:171], v[200:203], v[22:25]
	v_mfma_f32_16x16x32_bf16 v[18:21], v[176:179], v[200:203], v[18:21]
	v_mfma_f32_16x16x32_bf16 v[6:9], v[168:171], v[208:211], v[6:9]
	v_mfma_f32_16x16x32_bf16 v[2:5], v[176:179], v[208:211], v[2:5]
	v_mfma_f32_16x16x32_bf16 v[54:57], v[172:175], v[188:191], v[54:57]
	v_mfma_f32_16x16x32_bf16 v[50:53], v[180:183], v[188:191], v[50:53]
	v_mfma_f32_16x16x32_bf16 v[38:41], v[172:175], v[196:199], v[38:41]
	v_mfma_f32_16x16x32_bf16 v[34:37], v[180:183], v[196:199], v[34:37]
	v_mfma_f32_16x16x32_bf16 v[22:25], v[172:175], v[204:207], v[22:25]
	v_mfma_f32_16x16x32_bf16 v[18:21], v[180:183], v[204:207], v[18:21]
	v_mfma_f32_16x16x32_bf16 v[6:9], v[172:175], v[212:215], v[6:9]
	v_mfma_f32_16x16x32_bf16 v[2:5], v[180:183], v[212:215], v[2:5]
	s_setprio 0
	s_barrier
	s_add_i32 s81, s81, 2
	s_add_u32 s88, s88, 0x100
	s_addc_u32 s89, s89, 0
	s_add_u32 s75, s75, 0x100
	s_addc_u32 s77, s77, 0
	s_cmp_gt_u32 s81, 29
	s_cbranch_scc0 .LBB0_995
	s_and_b64 vcc, exec, s[78:79]
	s_cbranch_vccz .LBB0_998
	s_barrier
.LBB0_998:
	v_lshl_add_u32 v146, s76, 8, v1
	v_lshl_or_b32 v148, s73, 8, v163
	v_ashrrev_i32_e32 v147, 31, v146
	v_ashrrev_i32_e32 v149, 31, v148
	v_lshlrev_b64 v[150:151], 12, v[146:147]
	v_lshl_add_u64 v[150:151], s[64:65], 0, v[150:151]
	v_lshlrev_b64 v[148:149], 1, v[148:149]
	v_lshl_add_u64 v[150:151], v[150:151], 0, v[148:149]
	global_load_dwordx4 v[152:155], v[150:151], off
	s_mov_b64 s[0:1], 0x80000
	s_waitcnt vmcnt(0)
	v_cvt_f32_f16_e32 v172, v152
	v_cvt_f32_f16_sdwa v173, v152 dst_sel:DWORD dst_unused:UNUSED_PAD src0_sel:WORD_1
	v_cvt_f32_f16_e32 v174, v153
	v_cvt_f32_f16_sdwa v175, v153 dst_sel:DWORD dst_unused:UNUSED_PAD src0_sel:WORD_1
	v_cvt_f32_f16_e32 v176, v154
	v_cvt_f32_f16_sdwa v177, v154 dst_sel:DWORD dst_unused:UNUSED_PAD src0_sel:WORD_1
	v_cvt_f32_f16_e32 v178, v155
	v_cvt_f32_f16_sdwa v179, v155 dst_sel:DWORD dst_unused:UNUSED_PAD src0_sel:WORD_1
	global_load_dwordx4 v[152:155], v[150:151], off offset:64
	v_pk_add_f32 v[128:129], v[128:129], v[174:175]
	v_pk_add_f32 v[126:127], v[126:127], v[172:173]
	v_pk_add_f32 v[124:125], v[124:125], v[178:179]
	v_pk_add_f32 v[122:123], v[122:123], v[176:177]
	v_cvt_pk_f16_f32 v125, v124, v125
	v_cvt_pk_f16_f32 v124, v122, v123
	v_cvt_pk_f16_f32 v123, v128, v129
	v_cvt_pk_f16_f32 v122, v126, v127
	global_store_dwordx4 v[150:151], v[122:125], off
	s_waitcnt vmcnt(1)
	v_cvt_f32_f16_e32 v180, v152
	v_cvt_f32_f16_sdwa v181, v152 dst_sel:DWORD dst_unused:UNUSED_PAD src0_sel:WORD_1
	v_cvt_f32_f16_e32 v182, v153
	v_cvt_f32_f16_sdwa v183, v153 dst_sel:DWORD dst_unused:UNUSED_PAD src0_sel:WORD_1
	v_cvt_f32_f16_e32 v184, v154
	v_cvt_f32_f16_sdwa v185, v154 dst_sel:DWORD dst_unused:UNUSED_PAD src0_sel:WORD_1
	v_cvt_f32_f16_e32 v186, v155
	v_cvt_f32_f16_sdwa v187, v155 dst_sel:DWORD dst_unused:UNUSED_PAD src0_sel:WORD_1
	v_pk_add_f32 v[120:121], v[120:121], v[182:183]
	v_pk_add_f32 v[118:119], v[118:119], v[180:181]
	v_pk_add_f32 v[114:115], v[114:115], v[184:185]
	v_pk_add_f32 v[116:117], v[116:117], v[186:187]
	v_or_b32_e32 v152, 16, v146
	v_cvt_pk_f16_f32 v117, v116, v117
	v_cvt_pk_f16_f32 v116, v114, v115
	v_cvt_pk_f16_f32 v115, v120, v121
	v_cvt_pk_f16_f32 v114, v118, v119
	global_store_dwordx4 v[150:151], v[114:117], off offset:64
	v_ashrrev_i32_e32 v153, 31, v152
	v_lshlrev_b64 v[152:153], 12, v[152:153]
	v_or_b32_e32 v114, 32, v146
	v_ashrrev_i32_e32 v115, 31, v114
	v_lshlrev_b64 v[114:115], 12, v[114:115]
	v_lshl_add_u64 v[152:153], s[64:65], 0, v[152:153]
	v_lshl_add_u64 v[114:115], s[64:65], 0, v[114:115]
	v_lshl_add_u64 v[152:153], v[152:153], 0, v[148:149]
	v_lshl_add_u64 v[120:121], v[114:115], 0, v[148:149]
	global_load_dwordx4 v[158:161], v[152:153], off
	global_load_dwordx4 v[114:117], v[120:121], off
	global_load_dwordx4 v[168:171], v[152:153], off offset:64
	s_waitcnt vmcnt(2)
	v_cvt_f32_f16_e32 v154, v158
	s_waitcnt vmcnt(1)
	v_cvt_f32_f16_e32 v122, v114
	v_cvt_f32_f16_sdwa v123, v114 dst_sel:DWORD dst_unused:UNUSED_PAD src0_sel:WORD_1
	v_cvt_f32_f16_e32 v124, v115
	v_cvt_f32_f16_sdwa v125, v115 dst_sel:DWORD dst_unused:UNUSED_PAD src0_sel:WORD_1
	v_cvt_f32_f16_e32 v126, v116
	v_cvt_f32_f16_sdwa v127, v116 dst_sel:DWORD dst_unused:UNUSED_PAD src0_sel:WORD_1
	v_cvt_f32_f16_e32 v128, v117
	v_cvt_f32_f16_sdwa v129, v117 dst_sel:DWORD dst_unused:UNUSED_PAD src0_sel:WORD_1
	global_load_dwordx4 v[114:117], v[120:121], off offset:64
	s_waitcnt vmcnt(1)
	v_cvt_f32_f16_e32 v188, v168
	v_cvt_f32_f16_sdwa v189, v168 dst_sel:DWORD dst_unused:UNUSED_PAD src0_sel:WORD_1
	v_cvt_f32_f16_e32 v168, v169
	v_cvt_f32_f16_sdwa v169, v169 dst_sel:DWORD dst_unused:UNUSED_PAD src0_sel:WORD_1
	v_cvt_f32_f16_e32 v190, v170
	v_cvt_f32_f16_sdwa v191, v170 dst_sel:DWORD dst_unused:UNUSED_PAD src0_sel:WORD_1
	v_cvt_f32_f16_e32 v170, v171
	v_cvt_f32_f16_sdwa v171, v171 dst_sel:DWORD dst_unused:UNUSED_PAD src0_sel:WORD_1
	v_pk_add_f32 v[104:105], v[104:105], v[168:169]
	v_pk_add_f32 v[102:103], v[102:103], v[188:189]
	v_pk_add_f32 v[98:99], v[98:99], v[190:191]
	v_pk_add_f32 v[100:101], v[100:101], v[170:171]
	v_cvt_f32_f16_sdwa v155, v158 dst_sel:DWORD dst_unused:UNUSED_PAD src0_sel:WORD_1
	v_cvt_f32_f16_e32 v158, v159
	v_cvt_f32_f16_sdwa v159, v159 dst_sel:DWORD dst_unused:UNUSED_PAD src0_sel:WORD_1
	v_cvt_f32_f16_e32 v156, v160
	v_cvt_f32_f16_sdwa v157, v160 dst_sel:DWORD dst_unused:UNUSED_PAD src0_sel:WORD_1
	v_cvt_f32_f16_e32 v160, v161
	v_cvt_f32_f16_sdwa v161, v161 dst_sel:DWORD dst_unused:UNUSED_PAD src0_sel:WORD_1
	v_cvt_pk_f16_f32 v101, v100, v101
	v_cvt_pk_f16_f32 v100, v98, v99
	v_cvt_pk_f16_f32 v99, v104, v105
	v_cvt_pk_f16_f32 v98, v102, v103
	global_store_dwordx4 v[152:153], v[98:101], off offset:64
	v_pk_add_f32 v[112:113], v[112:113], v[158:159]
	v_pk_add_f32 v[110:111], v[110:111], v[154:155]
	v_or_b32_e32 v98, 48, v146
	v_ashrrev_i32_e32 v99, 31, v98
	v_lshlrev_b64 v[98:99], 12, v[98:99]
	v_pk_add_f32 v[108:109], v[108:109], v[160:161]
	v_pk_add_f32 v[106:107], v[106:107], v[156:157]
	v_lshl_add_u64 v[98:99], s[64:65], 0, v[98:99]
	v_cvt_pk_f16_f32 v109, v108, v109
	v_cvt_pk_f16_f32 v108, v106, v107
	v_cvt_pk_f16_f32 v107, v112, v113
	v_cvt_pk_f16_f32 v106, v110, v111
	v_lshl_add_u64 v[98:99], v[98:99], 0, v[148:149]
	global_store_dwordx4 v[152:153], v[106:109], off
	global_load_dwordx4 v[106:109], v[98:99], off
	v_pk_add_f32 v[96:97], v[96:97], v[124:125]
	v_pk_add_f32 v[94:95], v[94:95], v[122:123]
	v_pk_add_f32 v[92:93], v[92:93], v[128:129]
	v_pk_add_f32 v[90:91], v[90:91], v[126:127]
	v_cvt_pk_f16_f32 v93, v92, v93
	v_cvt_pk_f16_f32 v92, v90, v91
	v_cvt_pk_f16_f32 v91, v96, v97
	v_cvt_pk_f16_f32 v90, v94, v95
	global_store_dwordx4 v[120:121], v[90:93], off
	s_waitcnt vmcnt(4)
	v_cvt_f32_f16_e32 v176, v116
	v_cvt_f32_f16_sdwa v177, v116 dst_sel:DWORD dst_unused:UNUSED_PAD src0_sel:WORD_1
	v_cvt_f32_f16_e32 v178, v117
	v_cvt_f32_f16_sdwa v179, v117 dst_sel:DWORD dst_unused:UNUSED_PAD src0_sel:WORD_1
	global_load_dwordx4 v[116:119], v[98:99], off offset:64
	v_cvt_f32_f16_e32 v172, v114
	v_cvt_f32_f16_sdwa v173, v114 dst_sel:DWORD dst_unused:UNUSED_PAD src0_sel:WORD_1
	v_cvt_f32_f16_e32 v174, v115
	v_cvt_f32_f16_sdwa v175, v115 dst_sel:DWORD dst_unused:UNUSED_PAD src0_sel:WORD_1
	v_pk_add_f32 v[84:85], v[84:85], v[178:179]
	v_pk_add_f32 v[86:87], v[86:87], v[172:173]
	v_pk_add_f32 v[82:83], v[82:83], v[176:177]
	v_pk_add_f32 v[88:89], v[88:89], v[174:175]
	v_cvt_pk_f16_f32 v85, v84, v85
	v_cvt_pk_f16_f32 v84, v82, v83
	v_cvt_pk_f16_f32 v83, v88, v89
	v_cvt_pk_f16_f32 v82, v86, v87
	global_store_dwordx4 v[120:121], v[82:85], off offset:64
	s_waitcnt vmcnt(3)
	v_cvt_f32_f16_e32 v102, v106
	v_cvt_f32_f16_sdwa v103, v106 dst_sel:DWORD dst_unused:UNUSED_PAD src0_sel:WORD_1
	v_cvt_f32_f16_e32 v110, v107
	v_cvt_f32_f16_sdwa v111, v107 dst_sel:DWORD dst_unused:UNUSED_PAD src0_sel:WORD_1
	v_cvt_f32_f16_e32 v106, v108
	v_cvt_f32_f16_sdwa v107, v108 dst_sel:DWORD dst_unused:UNUSED_PAD src0_sel:WORD_1
	v_cvt_f32_f16_e32 v114, v109
	v_cvt_f32_f16_sdwa v115, v109 dst_sel:DWORD dst_unused:UNUSED_PAD src0_sel:WORD_1
	v_lshl_add_u64 v[82:83], v[150:151], 0, s[0:1]
	s_mov_b32 s0, 0x80000
	v_add_co_u32_e32 v84, vcc, s0, v150
	v_pk_add_f32 v[80:81], v[80:81], v[110:111]
	s_nop 0
	v_addc_co_u32_e32 v85, vcc, 0, v151, vcc
	global_load_dwordx4 v[90:93], v[84:85], off
	v_pk_add_f32 v[78:79], v[78:79], v[102:103]
	v_pk_add_f32 v[76:77], v[76:77], v[114:115]
	v_pk_add_f32 v[74:75], v[74:75], v[106:107]
	v_cvt_pk_f16_f32 v77, v76, v77
	v_cvt_pk_f16_f32 v76, v74, v75
	v_cvt_pk_f16_f32 v75, v80, v81
	v_cvt_pk_f16_f32 v74, v78, v79
	global_store_dwordx4 v[98:99], v[74:77], off
	s_mov_b64 s[0:1], -1
	s_andn2_b64 vcc, exec, s[2:3]
	s_waitcnt vmcnt(3)
	v_cvt_f32_f16_e32 v100, v116
	v_cvt_f32_f16_sdwa v101, v116 dst_sel:DWORD dst_unused:UNUSED_PAD src0_sel:WORD_1
	v_cvt_f32_f16_e32 v108, v117
	v_cvt_f32_f16_sdwa v109, v117 dst_sel:DWORD dst_unused:UNUSED_PAD src0_sel:WORD_1
	v_cvt_f32_f16_e32 v104, v118
	v_cvt_f32_f16_sdwa v105, v118 dst_sel:DWORD dst_unused:UNUSED_PAD src0_sel:WORD_1
	v_cvt_f32_f16_e32 v112, v119
	v_cvt_f32_f16_sdwa v113, v119 dst_sel:DWORD dst_unused:UNUSED_PAD src0_sel:WORD_1
	v_pk_add_f32 v[72:73], v[72:73], v[108:109]
	v_pk_add_f32 v[70:71], v[70:71], v[100:101]
	v_pk_add_f32 v[66:67], v[66:67], v[104:105]
	v_pk_add_f32 v[68:69], v[68:69], v[112:113]
	global_load_dwordx4 v[116:119], v[82:83], off offset:64
	v_cvt_pk_f16_f32 v69, v68, v69
	v_cvt_pk_f16_f32 v68, v66, v67
	v_cvt_pk_f16_f32 v67, v72, v73
	v_cvt_pk_f16_f32 v66, v70, v71
	global_store_dwordx4 v[98:99], v[66:69], off offset:64
	s_waitcnt vmcnt(3)
	v_cvt_f32_f16_e32 v86, v90
	v_add_u32_e32 v66, 0x90, v146
	v_ashrrev_i32_e32 v67, 31, v66
	v_lshlrev_b64 v[66:67], 12, v[66:67]
	v_lshl_add_u64 v[66:67], s[64:65], 0, v[66:67]
	v_lshl_add_u64 v[68:69], v[66:67], 0, v[148:149]
	global_load_dwordx4 v[74:77], v[68:69], off
	global_load_dwordx4 v[98:101], v[68:69], off offset:64
	v_cvt_f32_f16_sdwa v87, v90 dst_sel:DWORD dst_unused:UNUSED_PAD src0_sel:WORD_1
	v_cvt_f32_f16_e32 v90, v91
	v_cvt_f32_f16_sdwa v91, v91 dst_sel:DWORD dst_unused:UNUSED_PAD src0_sel:WORD_1
	v_cvt_f32_f16_e32 v88, v92
	v_cvt_f32_f16_sdwa v89, v92 dst_sel:DWORD dst_unused:UNUSED_PAD src0_sel:WORD_1
	v_cvt_f32_f16_e32 v92, v93
	v_cvt_f32_f16_sdwa v93, v93 dst_sel:DWORD dst_unused:UNUSED_PAD src0_sel:WORD_1
	v_pk_add_f32 v[64:65], v[64:65], v[90:91]
	v_pk_add_f32 v[62:63], v[62:63], v[86:87]
	v_pk_add_f32 v[58:59], v[58:59], v[88:89]
	v_pk_add_f32 v[60:61], v[60:61], v[92:93]
	s_waitcnt vmcnt(3)
	v_cvt_f32_f16_e32 v94, v116
	v_cvt_f32_f16_sdwa v95, v116 dst_sel:DWORD dst_unused:UNUSED_PAD src0_sel:WORD_1
	v_cvt_f32_f16_e32 v116, v117
	v_cvt_f32_f16_sdwa v117, v117 dst_sel:DWORD dst_unused:UNUSED_PAD src0_sel:WORD_1
	v_cvt_f32_f16_e32 v96, v118
	v_cvt_f32_f16_sdwa v97, v118 dst_sel:DWORD dst_unused:UNUSED_PAD src0_sel:WORD_1
	v_cvt_f32_f16_e32 v118, v119
	v_cvt_f32_f16_sdwa v119, v119 dst_sel:DWORD dst_unused:UNUSED_PAD src0_sel:WORD_1
	v_pk_add_f32 v[56:57], v[56:57], v[116:117]
	v_pk_add_f32 v[54:55], v[54:55], v[94:95]
	v_pk_add_f32 v[50:51], v[50:51], v[96:97]
	v_pk_add_f32 v[52:53], v[52:53], v[118:119]
	v_cvt_pk_f16_f32 v61, v60, v61
	v_cvt_pk_f16_f32 v53, v52, v53
	v_cvt_pk_f16_f32 v52, v50, v51
	v_cvt_pk_f16_f32 v51, v56, v57
	v_cvt_pk_f16_f32 v50, v54, v55
	global_store_dwordx4 v[82:83], v[50:53], off offset:64
	v_cvt_pk_f16_f32 v60, v58, v59
	v_cvt_pk_f16_f32 v59, v64, v65
	v_add_u32_e32 v50, 0xa0, v146
	v_ashrrev_i32_e32 v51, 31, v50
	v_lshlrev_b64 v[50:51], 12, v[50:51]
	v_lshl_add_u64 v[50:51], s[64:65], 0, v[50:51]
	v_cvt_pk_f16_f32 v58, v62, v63
	v_lshl_add_u64 v[50:51], v[50:51], 0, v[148:149]
	global_store_dwordx4 v[84:85], v[58:61], off
	global_load_dwordx4 v[58:61], v[50:51], off
	s_waitcnt vmcnt(4)
	v_cvt_f32_f16_e32 v70, v74
	s_waitcnt vmcnt(3)
	v_cvt_f32_f16_e32 v78, v98
	v_cvt_f32_f16_sdwa v79, v98 dst_sel:DWORD dst_unused:UNUSED_PAD src0_sel:WORD_1
	v_cvt_f32_f16_e32 v98, v99
	v_cvt_f32_f16_sdwa v99, v99 dst_sel:DWORD dst_unused:UNUSED_PAD src0_sel:WORD_1
	v_cvt_f32_f16_e32 v80, v100
	v_cvt_f32_f16_sdwa v81, v100 dst_sel:DWORD dst_unused:UNUSED_PAD src0_sel:WORD_1
	v_cvt_f32_f16_e32 v100, v101
	v_cvt_f32_f16_sdwa v101, v101 dst_sel:DWORD dst_unused:UNUSED_PAD src0_sel:WORD_1
	v_cvt_f32_f16_sdwa v71, v74 dst_sel:DWORD dst_unused:UNUSED_PAD src0_sel:WORD_1
	v_cvt_f32_f16_e32 v74, v75
	v_cvt_f32_f16_sdwa v75, v75 dst_sel:DWORD dst_unused:UNUSED_PAD src0_sel:WORD_1
	v_cvt_f32_f16_e32 v72, v76
	v_cvt_f32_f16_sdwa v73, v76 dst_sel:DWORD dst_unused:UNUSED_PAD src0_sel:WORD_1
	v_cvt_f32_f16_e32 v76, v77
	v_cvt_f32_f16_sdwa v77, v77 dst_sel:DWORD dst_unused:UNUSED_PAD src0_sel:WORD_1
	v_pk_add_f32 v[40:41], v[40:41], v[98:99]
	v_pk_add_f32 v[38:39], v[38:39], v[78:79]
	v_pk_add_f32 v[36:37], v[36:37], v[100:101]
	v_pk_add_f32 v[34:35], v[34:35], v[80:81]
	global_load_dwordx4 v[82:85], v[50:51], off offset:64
	v_cvt_pk_f16_f32 v37, v36, v37
	v_cvt_pk_f16_f32 v36, v34, v35
	v_cvt_pk_f16_f32 v35, v40, v41
	v_cvt_pk_f16_f32 v34, v38, v39
	global_store_dwordx4 v[68:69], v[34:37], off offset:64
	v_pk_add_f32 v[48:49], v[48:49], v[74:75]
	v_pk_add_f32 v[46:47], v[46:47], v[70:71]
	v_add_u32_e32 v34, 0xb0, v146
	v_ashrrev_i32_e32 v35, 31, v34
	v_pk_add_f32 v[44:45], v[44:45], v[76:77]
	v_pk_add_f32 v[42:43], v[42:43], v[72:73]
	v_lshlrev_b64 v[34:35], 12, v[34:35]
	v_cvt_pk_f16_f32 v45, v44, v45
	v_cvt_pk_f16_f32 v44, v42, v43
	v_cvt_pk_f16_f32 v43, v48, v49
	v_cvt_pk_f16_f32 v42, v46, v47
	v_lshl_add_u64 v[34:35], s[64:65], 0, v[34:35]
	global_store_dwordx4 v[68:69], v[42:45], off
	s_waitcnt vmcnt(3)
	v_cvt_f32_f16_e32 v54, v58
	v_lshl_add_u64 v[42:43], v[34:35], 0, v[148:149]
	global_load_dwordx4 v[34:37], v[42:43], off
	global_load_dwordx4 v[38:41], v[42:43], off offset:64
	v_cvt_f32_f16_sdwa v55, v58 dst_sel:DWORD dst_unused:UNUSED_PAD src0_sel:WORD_1
	v_cvt_f32_f16_e32 v58, v59
	v_cvt_f32_f16_sdwa v59, v59 dst_sel:DWORD dst_unused:UNUSED_PAD src0_sel:WORD_1
	v_cvt_f32_f16_e32 v52, v60
	v_cvt_f32_f16_sdwa v53, v60 dst_sel:DWORD dst_unused:UNUSED_PAD src0_sel:WORD_1
	v_cvt_f32_f16_e32 v56, v61
	v_cvt_f32_f16_sdwa v57, v61 dst_sel:DWORD dst_unused:UNUSED_PAD src0_sel:WORD_1
	v_pk_add_f32 v[32:33], v[32:33], v[58:59]
	v_pk_add_f32 v[30:31], v[30:31], v[54:55]
	v_pk_add_f32 v[26:27], v[26:27], v[52:53]
	v_pk_add_f32 v[28:29], v[28:29], v[56:57]
	s_waitcnt vmcnt(4)
	v_cvt_f32_f16_e32 v62, v82
	v_cvt_f32_f16_sdwa v63, v82 dst_sel:DWORD dst_unused:UNUSED_PAD src0_sel:WORD_1
	v_cvt_f32_f16_e32 v66, v83
	v_cvt_f32_f16_sdwa v67, v83 dst_sel:DWORD dst_unused:UNUSED_PAD src0_sel:WORD_1
	v_cvt_f32_f16_e32 v60, v84
	v_cvt_f32_f16_sdwa v61, v84 dst_sel:DWORD dst_unused:UNUSED_PAD src0_sel:WORD_1
	v_cvt_f32_f16_e32 v64, v85
	v_cvt_f32_f16_sdwa v65, v85 dst_sel:DWORD dst_unused:UNUSED_PAD src0_sel:WORD_1
	v_pk_add_f32 v[24:25], v[24:25], v[66:67]
	v_pk_add_f32 v[22:23], v[22:23], v[62:63]
	v_pk_add_f32 v[18:19], v[18:19], v[60:61]
	v_pk_add_f32 v[20:21], v[20:21], v[64:65]
	v_cvt_pk_f16_f32 v29, v28, v29
	v_cvt_pk_f16_f32 v28, v26, v27
	v_cvt_pk_f16_f32 v27, v32, v33
	v_cvt_pk_f16_f32 v26, v30, v31
	v_cvt_pk_f16_f32 v21, v20, v21
	v_cvt_pk_f16_f32 v20, v18, v19
	v_cvt_pk_f16_f32 v19, v24, v25
	v_cvt_pk_f16_f32 v18, v22, v23
	global_store_dwordx4 v[50:51], v[26:29], off
	global_store_dwordx4 v[50:51], v[18:21], off offset:64
	s_waitcnt vmcnt(3)
	v_cvt_f32_f16_e32 v30, v34
	s_waitcnt vmcnt(2)
	v_cvt_f32_f16_e32 v18, v40
	v_cvt_f32_f16_sdwa v19, v40 dst_sel:DWORD dst_unused:UNUSED_PAD src0_sel:WORD_1
	v_cvt_f32_f16_e32 v20, v41
	v_cvt_f32_f16_sdwa v21, v41 dst_sel:DWORD dst_unused:UNUSED_PAD src0_sel:WORD_1
	v_cvt_f32_f16_e32 v22, v38
	v_cvt_f32_f16_sdwa v23, v38 dst_sel:DWORD dst_unused:UNUSED_PAD src0_sel:WORD_1
	v_cvt_f32_f16_e32 v24, v39
	v_cvt_f32_f16_sdwa v25, v39 dst_sel:DWORD dst_unused:UNUSED_PAD src0_sel:WORD_1
	v_cvt_f32_f16_e32 v26, v36
	v_cvt_f32_f16_sdwa v27, v36 dst_sel:DWORD dst_unused:UNUSED_PAD src0_sel:WORD_1
	v_cvt_f32_f16_e32 v28, v37
	v_cvt_f32_f16_sdwa v29, v37 dst_sel:DWORD dst_unused:UNUSED_PAD src0_sel:WORD_1
	v_cvt_f32_f16_sdwa v31, v34 dst_sel:DWORD dst_unused:UNUSED_PAD src0_sel:WORD_1
	v_cvt_f32_f16_e32 v32, v35
	v_cvt_f32_f16_sdwa v33, v35 dst_sel:DWORD dst_unused:UNUSED_PAD src0_sel:WORD_1
	v_pk_add_f32 v[12:13], v[12:13], v[28:29]
	v_pk_add_f32 v[14:15], v[14:15], v[30:31]
	v_pk_add_f32 v[10:11], v[10:11], v[26:27]
	v_pk_add_f32 v[16:17], v[16:17], v[32:33]
	v_pk_add_f32 v[8:9], v[8:9], v[24:25]
	v_pk_add_f32 v[6:7], v[6:7], v[22:23]
	v_pk_add_f32 v[4:5], v[4:5], v[20:21]
	v_pk_add_f32 v[2:3], v[2:3], v[18:19]
	v_cvt_pk_f16_f32 v13, v12, v13
	v_cvt_pk_f16_f32 v12, v10, v11
	v_cvt_pk_f16_f32 v11, v16, v17
	v_cvt_pk_f16_f32 v10, v14, v15
	v_cvt_pk_f16_f32 v5, v4, v5
	v_cvt_pk_f16_f32 v4, v2, v3
	v_cvt_pk_f16_f32 v3, v8, v9
	v_cvt_pk_f16_f32 v2, v6, v7
	global_store_dwordx4 v[42:43], v[10:13], off
	global_store_dwordx4 v[42:43], v[2:5], off offset:64
	s_cbranch_vccnz .LBB0_987
	s_andn2_b64 vcc, exec, s[6:7]
	s_cbranch_vccnz .LBB0_986
	s_barrier
	s_branch .LBB0_986

.LBB0_1223:
	s_lshl_b32 s0, s0, 5
	s_mov_b64 s[78:79], 0x80
	s_sext_i32_i8 s86, s3
	v_and_b32_e32 v15, 15, v0
	v_lshlrev_b32_e32 v16, 1, v12
	v_lshlrev_b32_e32 v17, 2, v0
	s_and_b32 s3, s0, 0x60
	v_lshlrev_b32_e32 v18, 6, v0
	s_movk_i32 s0, 0x3c0
	s_add_i32 m0, s33, 0x18000
	v_lshl_add_u64 v[8:9], v[8:9], 0, s[78:79]
	v_lshl_or_b32 v1, s1, 6, v15
	v_lshl_or_b32 v15, v15, 6, v16
	s_lshl_b32 s1, s1, 13
	v_and_b32_e32 v17, 32, v17
	v_and_or_b32 v16, v18, s0, v16
	s_lshl_b32 s0, s3, 7
	s_waitcnt vmcnt(2)
	s_barrier
	global_load_lds_dwordx4 v[8:9], off
	v_lshl_add_u64 v[6:7], v[6:7], 0, s[78:79]
	s_add_i32 m0, s33, 0x1a000
	s_add_i32 s60, s33, 0x8000
	s_add_i32 s61, s33, 0xa000
	v_bitop3_b32 v162, s0, v16, v17 bitop3:0xf6
	v_add_u32_e32 v162, s0, v162
	global_load_lds_dwordx4 v[6:7], off
	v_lshl_add_u64 v[2:3], v[2:3], 0, s[78:79]
	s_mov_b32 m0, s60
	s_add_u32 s0, s84, 0x160080
	v_bitop3_b32 v15, v15, s1, v17 bitop3:0xde
	global_load_lds_dwordx4 v[2:3], off
	v_lshl_add_u64 v[2:3], v[4:5], 0, s[78:79]
	s_mov_b32 m0, s61
	s_addc_u32 s1, s85, 0
	global_load_lds_dwordx4 v[2:3], off
	s_add_i32 m0, s33, 0x1c000
	v_lshl_add_u64 v[2:3], s[0:1], 0, v[132:133]
	global_load_lds_dwordx4 v[2:3], off
	v_lshl_add_u64 v[2:3], s[0:1], 0, v[136:137]
	s_add_i32 m0, s33, 0x1e000
	s_cmpk_lt_u32 s2, 0x100
	global_load_lds_dwordx4 v[2:3], off
	s_waitcnt vmcnt(6)
	v_add_u16_e32 v2, v10, v11
	s_cselect_b64 s[80:81], -1, 0
	v_lshrrev_b16_e32 v2, 1, v2
	s_add_i32 s71, 0, 0x10000
	s_add_i32 s72, 0, 0x14000
	s_ashr_i32 s70, s11, 31
	v_lshl_or_b32 v163, s3, 1, v12
	v_add_lshl_u32 v138, v13, v2, 1
	v_mov_b32_e32 v139, v133
	v_add_lshl_u32 v140, v14, v2, 1
	v_mov_b32_e32 v141, v133
	v_mov_b64_e32 v[142:143], 0x100
	v_mov_b64_e32 v[144:145], 0xff
	v_add_u32_e32 v164, s71, v162
	v_add_u32_e32 v165, 0x11000, v162
	v_add_u32_e32 v166, 0, v15
	s_barrier
	s_branch .LBB0_1226

.LBB0_1237:
	ds_read_b128 v[146:149], v164
	ds_read_b128 v[150:153], v164 offset:1024
	ds_read_b128 v[154:157], v164 offset:2048
	ds_read_b128 v[158:161], v164 offset:3072
	ds_read_b128 v[168:171], v165
	ds_read_b128 v[172:175], v165 offset:1024
	ds_read_b128 v[176:179], v165 offset:2048
	ds_read_b128 v[180:183], v165 offset:3072
	s_add_u32 s34, s76, 0xffea0080
	s_addc_u32 s35, s77, -1
	s_cmpk_eq_i32 s52, 0x54
	s_cselect_b32 s85, s5, s35
	s_cselect_b32 s84, s4, s34
	s_cselect_b32 s35, s83, s1
	s_cselect_b32 s34, s82, s0
	v_lshl_add_u64 v[218:219], s[76:77], 0, v[138:139]
	s_add_i32 m0, s33, 0xc000
	ds_read_b128 v[184:187], v166
	ds_read_b128 v[188:191], v166 offset:1024
	ds_read_b128 v[192:195], v166 offset:2048
	ds_read_b128 v[196:199], v166 offset:3072
	ds_read_b128 v[200:203], v166 offset:4096
	ds_read_b128 v[204:207], v166 offset:5120
	ds_read_b128 v[208:211], v166 offset:6144
	ds_read_b128 v[212:215], v166 offset:7168
	global_load_lds_dwordx4 v[218:219], off
	v_lshl_add_u64 v[218:219], s[76:77], 0, v[140:141]
	s_add_i32 m0, s33, 0xe000
	s_nop 0
	global_load_lds_dwordx4 v[218:219], off
	s_waitcnt vmcnt(8)
	s_waitcnt lgkmcnt(0)
	s_barrier
	s_setprio 1
	s_waitcnt lgkmcnt(0)
	v_mfma_f32_16x16x32_bf16 v[126:129], v[146:149], v[184:187], v[126:129]
	v_mfma_f32_16x16x32_bf16 v[122:125], v[154:157], v[184:187], v[122:125]
	v_mfma_f32_16x16x32_bf16 v[110:113], v[146:149], v[192:195], v[110:113]
	v_mfma_f32_16x16x32_bf16 v[106:109], v[154:157], v[192:195], v[106:109]
	v_mfma_f32_16x16x32_bf16 v[94:97], v[146:149], v[200:203], v[94:97]
	v_mfma_f32_16x16x32_bf16 v[90:93], v[154:157], v[200:203], v[90:93]
	v_mfma_f32_16x16x32_bf16 v[78:81], v[146:149], v[208:211], v[78:81]
	v_mfma_f32_16x16x32_bf16 v[74:77], v[154:157], v[208:211], v[74:77]
	v_mfma_f32_16x16x32_bf16 v[126:129], v[150:153], v[188:191], v[126:129]
	v_mfma_f32_16x16x32_bf16 v[122:125], v[158:161], v[188:191], v[122:125]
	v_mfma_f32_16x16x32_bf16 v[110:113], v[150:153], v[196:199], v[110:113]
	v_mfma_f32_16x16x32_bf16 v[106:109], v[158:161], v[196:199], v[106:109]
	v_mfma_f32_16x16x32_bf16 v[94:97], v[150:153], v[204:207], v[94:97]
	v_mfma_f32_16x16x32_bf16 v[90:93], v[158:161], v[204:207], v[90:93]
	v_mfma_f32_16x16x32_bf16 v[78:81], v[150:153], v[212:215], v[78:81]
	v_mfma_f32_16x16x32_bf16 v[74:77], v[158:161], v[212:215], v[74:77]
	s_setprio 0
	s_setprio 1
	v_mfma_f32_16x16x32_bf16 v[118:121], v[168:171], v[184:187], v[118:121]
	v_mfma_f32_16x16x32_bf16 v[114:117], v[176:179], v[184:187], v[114:117]
	v_mfma_f32_16x16x32_bf16 v[102:105], v[168:171], v[192:195], v[102:105]
	v_mfma_f32_16x16x32_bf16 v[98:101], v[176:179], v[192:195], v[98:101]
	v_mfma_f32_16x16x32_bf16 v[86:89], v[168:171], v[200:203], v[86:89]
	v_mfma_f32_16x16x32_bf16 v[82:85], v[176:179], v[200:203], v[82:85]
	v_mfma_f32_16x16x32_bf16 v[70:73], v[168:171], v[208:211], v[70:73]
	v_mfma_f32_16x16x32_bf16 v[66:69], v[176:179], v[208:211], v[66:69]
	v_mfma_f32_16x16x32_bf16 v[118:121], v[172:175], v[188:191], v[118:121]
	v_mfma_f32_16x16x32_bf16 v[114:117], v[180:183], v[188:191], v[114:117]
	v_mfma_f32_16x16x32_bf16 v[102:105], v[172:175], v[196:199], v[102:105]
	v_mfma_f32_16x16x32_bf16 v[98:101], v[180:183], v[196:199], v[98:101]
	v_mfma_f32_16x16x32_bf16 v[86:89], v[172:175], v[204:207], v[86:89]
	v_mfma_f32_16x16x32_bf16 v[82:85], v[180:183], v[204:207], v[82:85]
	v_mfma_f32_16x16x32_bf16 v[70:73], v[172:175], v[212:215], v[70:73]
	v_mfma_f32_16x16x32_bf16 v[66:69], v[180:183], v[212:215], v[66:69]
	s_setprio 0
	s_barrier
	s_add_i32 s53, s71, s31
	v_lshl_add_u64 v[218:219], s[34:35], 0, v[132:133]
	s_mov_b32 m0, s53
	ds_read_b128 v[184:187], v166 offset:16384
	ds_read_b128 v[188:191], v166 offset:17408
	ds_read_b128 v[192:195], v166 offset:18432
	ds_read_b128 v[196:199], v166 offset:19456
	ds_read_b128 v[200:203], v166 offset:20480
	ds_read_b128 v[204:207], v166 offset:21504
	ds_read_b128 v[208:211], v166 offset:22528
	ds_read_b128 v[212:215], v166 offset:23552
	global_load_lds_dwordx4 v[218:219], off
	s_add_i32 m0, s53, 0x2000
	s_add_u32 s54, s34, 0x160000
	v_lshl_add_u64 v[220:221], s[34:35], 0, v[136:137]
	s_addc_u32 s55, s35, 0
	s_add_i32 s53, s72, s31
	global_load_lds_dwordx4 v[220:221], off
	v_lshl_add_u64 v[222:223], s[54:55], 0, v[132:133]
	s_mov_b32 m0, s53
	v_lshl_add_u64 v[224:225], s[84:85], 0, v[134:135]
	global_load_lds_dwordx4 v[222:223], off
	v_lshl_add_u64 v[222:223], s[54:55], 0, v[136:137]
	s_add_i32 m0, s53, 0x2000
	s_nop 0
	global_load_lds_dwordx4 v[222:223], off
	v_lshl_add_u64 v[222:223], s[84:85], 0, v[130:131]
	s_mov_b32 m0, s33
	s_nop 0
	global_load_lds_dwordx4 v[222:223], off
	s_mov_b32 m0, s56
	s_nop 0
	global_load_lds_dwordx4 v[224:225], off
	s_waitcnt vmcnt(8)
	s_waitcnt lgkmcnt(0)
	s_barrier
	s_setprio 1
	s_waitcnt lgkmcnt(0)
	v_mfma_f32_16x16x32_bf16 v[62:65], v[146:149], v[184:187], v[62:65]
	v_mfma_f32_16x16x32_bf16 v[58:61], v[154:157], v[184:187], v[58:61]
	v_mfma_f32_16x16x32_bf16 v[46:49], v[146:149], v[192:195], v[46:49]
	v_mfma_f32_16x16x32_bf16 v[42:45], v[154:157], v[192:195], v[42:45]
	v_mfma_f32_16x16x32_bf16 v[30:33], v[146:149], v[200:203], v[30:33]
	v_mfma_f32_16x16x32_bf16 v[26:29], v[154:157], v[200:203], v[26:29]
	v_mfma_f32_16x16x32_bf16 v[14:17], v[146:149], v[208:211], v[14:17]
	v_mfma_f32_16x16x32_bf16 v[10:13], v[154:157], v[208:211], v[10:13]
	v_mfma_f32_16x16x32_bf16 v[62:65], v[150:153], v[188:191], v[62:65]
	v_mfma_f32_16x16x32_bf16 v[58:61], v[158:161], v[188:191], v[58:61]
	v_mfma_f32_16x16x32_bf16 v[46:49], v[150:153], v[196:199], v[46:49]
	v_mfma_f32_16x16x32_bf16 v[42:45], v[158:161], v[196:199], v[42:45]
	v_mfma_f32_16x16x32_bf16 v[30:33], v[150:153], v[204:207], v[30:33]
	v_mfma_f32_16x16x32_bf16 v[26:29], v[158:161], v[204:207], v[26:29]
	v_mfma_f32_16x16x32_bf16 v[14:17], v[150:153], v[212:215], v[14:17]
	v_mfma_f32_16x16x32_bf16 v[10:13], v[158:161], v[212:215], v[10:13]
	s_setprio 0
	s_setprio 1
	v_mfma_f32_16x16x32_bf16 v[54:57], v[168:171], v[184:187], v[54:57]
	v_mfma_f32_16x16x32_bf16 v[50:53], v[176:179], v[184:187], v[50:53]
	v_mfma_f32_16x16x32_bf16 v[38:41], v[168:171], v[192:195], v[38:41]
	v_mfma_f32_16x16x32_bf16 v[34:37], v[176:179], v[192:195], v[34:37]
	v_mfma_f32_16x16x32_bf16 v[22:25], v[168:171], v[200:203], v[22:25]
	v_mfma_f32_16x16x32_bf16 v[18:21], v[176:179], v[200:203], v[18:21]
	v_mfma_f32_16x16x32_bf16 v[6:9], v[168:171], v[208:211], v[6:9]
	v_mfma_f32_16x16x32_bf16 v[2:5], v[176:179], v[208:211], v[2:5]
	v_mfma_f32_16x16x32_bf16 v[54:57], v[172:175], v[188:191], v[54:57]
	v_mfma_f32_16x16x32_bf16 v[50:53], v[180:183], v[188:191], v[50:53]
	v_mfma_f32_16x16x32_bf16 v[38:41], v[172:175], v[196:199], v[38:41]
	v_mfma_f32_16x16x32_bf16 v[34:37], v[180:183], v[196:199], v[34:37]
	v_mfma_f32_16x16x32_bf16 v[22:25], v[172:175], v[204:207], v[22:25]
	v_mfma_f32_16x16x32_bf16 v[18:21], v[180:183], v[204:207], v[18:21]
	v_mfma_f32_16x16x32_bf16 v[6:9], v[172:175], v[212:215], v[6:9]
	v_mfma_f32_16x16x32_bf16 v[2:5], v[180:183], v[212:215], v[2:5]
	s_setprio 0
	s_barrier
	s_add_i32 s53, 0, 0x18000
	s_add_i32 s62, 0, 0x1c000
	v_add_u32_e32 v158, s53, v162
	v_add_u32_e32 v167, 0x19000, v162
	ds_read_b128 v[146:149], v158
	ds_read_b128 v[150:153], v158 offset:1024
	ds_read_b128 v[154:157], v158 offset:2048
	ds_read_b128 v[158:161], v158 offset:3072
	ds_read_b128 v[168:171], v167
	ds_read_b128 v[172:175], v167 offset:1024
	ds_read_b128 v[176:179], v167 offset:2048
	ds_read_b128 v[180:183], v167 offset:3072
	s_add_u32 s54, s84, 0x160000
	s_addc_u32 s55, s85, 0
	s_mov_b32 m0, s57
	v_lshl_add_u64 v[226:227], s[54:55], 0, v[130:131]
	ds_read_b128 v[184:187], v166 offset:32768
	ds_read_b128 v[188:191], v166 offset:33792
	ds_read_b128 v[192:195], v166 offset:34816
	ds_read_b128 v[196:199], v166 offset:35840
	ds_read_b128 v[200:203], v166 offset:36864
	ds_read_b128 v[204:207], v166 offset:37888
	ds_read_b128 v[208:211], v166 offset:38912
	ds_read_b128 v[212:215], v166 offset:39936
	global_load_lds_dwordx4 v[226:227], off
	v_lshl_add_u64 v[226:227], s[54:55], 0, v[134:135]
	s_mov_b32 m0, s58
	s_nop 0
	global_load_lds_dwordx4 v[226:227], off
	s_waitcnt vmcnt(8)
	s_waitcnt lgkmcnt(0)
	s_barrier
	s_setprio 1
	s_waitcnt lgkmcnt(0)
	v_mfma_f32_16x16x32_bf16 v[126:129], v[146:149], v[184:187], v[126:129]
	v_mfma_f32_16x16x32_bf16 v[122:125], v[154:157], v[184:187], v[122:125]
	v_mfma_f32_16x16x32_bf16 v[110:113], v[146:149], v[192:195], v[110:113]
	v_mfma_f32_16x16x32_bf16 v[106:109], v[154:157], v[192:195], v[106:109]
	v_mfma_f32_16x16x32_bf16 v[94:97], v[146:149], v[200:203], v[94:97]
	v_mfma_f32_16x16x32_bf16 v[90:93], v[154:157], v[200:203], v[90:93]
	v_mfma_f32_16x16x32_bf16 v[78:81], v[146:149], v[208:211], v[78:81]
	v_mfma_f32_16x16x32_bf16 v[74:77], v[154:157], v[208:211], v[74:77]
	v_mfma_f32_16x16x32_bf16 v[126:129], v[150:153], v[188:191], v[126:129]
	v_mfma_f32_16x16x32_bf16 v[122:125], v[158:161], v[188:191], v[122:125]
	v_mfma_f32_16x16x32_bf16 v[110:113], v[150:153], v[196:199], v[110:113]
	v_mfma_f32_16x16x32_bf16 v[106:109], v[158:161], v[196:199], v[106:109]
	v_mfma_f32_16x16x32_bf16 v[94:97], v[150:153], v[204:207], v[94:97]
	v_mfma_f32_16x16x32_bf16 v[90:93], v[158:161], v[204:207], v[90:93]
	v_mfma_f32_16x16x32_bf16 v[78:81], v[150:153], v[212:215], v[78:81]
	v_mfma_f32_16x16x32_bf16 v[74:77], v[158:161], v[212:215], v[74:77]
	s_setprio 0
	s_setprio 1
	v_mfma_f32_16x16x32_bf16 v[118:121], v[168:171], v[184:187], v[118:121]
	v_mfma_f32_16x16x32_bf16 v[114:117], v[176:179], v[184:187], v[114:117]
	v_mfma_f32_16x16x32_bf16 v[102:105], v[168:171], v[192:195], v[102:105]
	v_mfma_f32_16x16x32_bf16 v[98:101], v[176:179], v[192:195], v[98:101]
	v_mfma_f32_16x16x32_bf16 v[86:89], v[168:171], v[200:203], v[86:89]
	v_mfma_f32_16x16x32_bf16 v[82:85], v[176:179], v[200:203], v[82:85]
	v_mfma_f32_16x16x32_bf16 v[70:73], v[168:171], v[208:211], v[70:73]
	v_mfma_f32_16x16x32_bf16 v[66:69], v[176:179], v[208:211], v[66:69]
	v_mfma_f32_16x16x32_bf16 v[118:121], v[172:175], v[188:191], v[118:121]
	v_mfma_f32_16x16x32_bf16 v[114:117], v[180:183], v[188:191], v[114:117]
	v_mfma_f32_16x16x32_bf16 v[102:105], v[172:175], v[196:199], v[102:105]
	v_mfma_f32_16x16x32_bf16 v[98:101], v[180:183], v[196:199], v[98:101]
	v_mfma_f32_16x16x32_bf16 v[86:89], v[172:175], v[204:207], v[86:89]
	v_mfma_f32_16x16x32_bf16 v[82:85], v[180:183], v[204:207], v[82:85]
	v_mfma_f32_16x16x32_bf16 v[70:73], v[172:175], v[212:215], v[70:73]
	v_mfma_f32_16x16x32_bf16 v[66:69], v[180:183], v[212:215], v[66:69]
	s_setprio 0
	s_barrier
	s_add_i32 s53, s53, s31
	v_lshl_add_u64 v[218:219], v[218:219], 0, s[78:79]
	s_mov_b32 m0, s53
	ds_read_b128 v[184:187], v166 offset:49152
	ds_read_b128 v[188:191], v166 offset:50176
	ds_read_b128 v[192:195], v166 offset:51200
	ds_read_b128 v[196:199], v166 offset:52224
	ds_read_b128 v[200:203], v166 offset:53248
	ds_read_b128 v[204:207], v166 offset:54272
	ds_read_b128 v[208:211], v166 offset:55296
	ds_read_b128 v[212:215], v166 offset:56320
	global_load_lds_dwordx4 v[218:219], off
	s_add_i32 m0, s53, 0x2000
	s_add_u32 s34, s34, 0x160080
	v_lshl_add_u64 v[218:219], v[220:221], 0, s[78:79]
	s_addc_u32 s35, s35, 0
	s_add_i32 s53, s62, s31
	global_load_lds_dwordx4 v[218:219], off
	v_lshl_add_u64 v[218:219], s[34:35], 0, v[132:133]
	s_mov_b32 m0, s53
	s_nop 0
	global_load_lds_dwordx4 v[218:219], off
	v_lshl_add_u64 v[218:219], s[34:35], 0, v[136:137]
	s_add_i32 m0, s53, 0x2000
	s_nop 0
	global_load_lds_dwordx4 v[218:219], off
	v_lshl_add_u64 v[218:219], v[222:223], 0, s[78:79]
	s_mov_b32 m0, s60
	s_nop 0
	global_load_lds_dwordx4 v[218:219], off
	v_lshl_add_u64 v[218:219], v[224:225], 0, s[78:79]
	s_mov_b32 m0, s61
	s_nop 0
	global_load_lds_dwordx4 v[218:219], off
	s_waitcnt vmcnt(8)
	s_waitcnt lgkmcnt(0)
	s_barrier
	s_setprio 1
	s_waitcnt lgkmcnt(0)
	v_mfma_f32_16x16x32_bf16 v[62:65], v[146:149], v[184:187], v[62:65]
	v_mfma_f32_16x16x32_bf16 v[58:61], v[154:157], v[184:187], v[58:61]
	v_mfma_f32_16x16x32_bf16 v[46:49], v[146:149], v[192:195], v[46:49]
	v_mfma_f32_16x16x32_bf16 v[42:45], v[154:157], v[192:195], v[42:45]
	v_mfma_f32_16x16x32_bf16 v[30:33], v[146:149], v[200:203], v[30:33]
	v_mfma_f32_16x16x32_bf16 v[26:29], v[154:157], v[200:203], v[26:29]
	v_mfma_f32_16x16x32_bf16 v[14:17], v[146:149], v[208:211], v[14:17]
	v_mfma_f32_16x16x32_bf16 v[10:13], v[154:157], v[208:211], v[10:13]
	v_mfma_f32_16x16x32_bf16 v[62:65], v[150:153], v[188:191], v[62:65]
	v_mfma_f32_16x16x32_bf16 v[58:61], v[158:161], v[188:191], v[58:61]
	v_mfma_f32_16x16x32_bf16 v[46:49], v[150:153], v[196:199], v[46:49]
	v_mfma_f32_16x16x32_bf16 v[42:45], v[158:161], v[196:199], v[42:45]
	v_mfma_f32_16x16x32_bf16 v[30:33], v[150:153], v[204:207], v[30:33]
	v_mfma_f32_16x16x32_bf16 v[26:29], v[158:161], v[204:207], v[26:29]
	v_mfma_f32_16x16x32_bf16 v[14:17], v[150:153], v[212:215], v[14:17]
	v_mfma_f32_16x16x32_bf16 v[10:13], v[158:161], v[212:215], v[10:13]
	s_setprio 0
	s_setprio 1
	v_mfma_f32_16x16x32_bf16 v[54:57], v[168:171], v[184:187], v[54:57]
	v_mfma_f32_16x16x32_bf16 v[50:53], v[176:179], v[184:187], v[50:53]
	v_mfma_f32_16x16x32_bf16 v[38:41], v[168:171], v[192:195], v[38:41]
	v_mfma_f32_16x16x32_bf16 v[34:37], v[176:179], v[192:195], v[34:37]
	v_mfma_f32_16x16x32_bf16 v[22:25], v[168:171], v[200:203], v[22:25]
	v_mfma_f32_16x16x32_bf16 v[18:21], v[176:179], v[200:203], v[18:21]
	v_mfma_f32_16x16x32_bf16 v[6:9], v[168:171], v[208:211], v[6:9]
	v_mfma_f32_16x16x32_bf16 v[2:5], v[176:179], v[208:211], v[2:5]
	v_mfma_f32_16x16x32_bf16 v[54:57], v[172:175], v[188:191], v[54:57]
	v_mfma_f32_16x16x32_bf16 v[50:53], v[180:183], v[188:191], v[50:53]
	v_mfma_f32_16x16x32_bf16 v[38:41], v[172:175], v[196:199], v[38:41]
	v_mfma_f32_16x16x32_bf16 v[34:37], v[180:183], v[196:199], v[34:37]
	v_mfma_f32_16x16x32_bf16 v[22:25], v[172:175], v[204:207], v[22:25]
	v_mfma_f32_16x16x32_bf16 v[18:21], v[180:183], v[204:207], v[18:21]
	v_mfma_f32_16x16x32_bf16 v[6:9], v[172:175], v[212:215], v[6:9]
	v_mfma_f32_16x16x32_bf16 v[2:5], v[180:183], v[212:215], v[2:5]
	s_setprio 0
	s_barrier
	s_add_i32 s52, s52, 2
	s_add_u32 s76, s76, 0x100
	s_addc_u32 s77, s77, 0
	s_add_u32 s0, s0, 0x100
	s_addc_u32 s1, s1, 0
	s_cmpk_gt_u32 s52, 0x55
	s_cbranch_scc0 .LBB0_1237
	s_and_b64 vcc, exec, s[80:81]
	s_cbranch_vccz .LBB0_1240
	s_barrier
.LBB0_1240:
	v_lshl_add_u32 v146, s75, 8, v1
	v_lshl_or_b32 v148, s86, 8, v163
	v_ashrrev_i32_e32 v147, 31, v146
	v_ashrrev_i32_e32 v149, 31, v148
	v_lshlrev_b64 v[150:151], 12, v[146:147]
	v_lshl_add_u64 v[150:151], s[64:65], 0, v[150:151]
	v_lshlrev_b64 v[148:149], 1, v[148:149]
	v_lshl_add_u64 v[150:151], v[150:151], 0, v[148:149]
	global_load_dwordx4 v[152:155], v[150:151], off
	s_mov_b64 s[0:1], 0x80000
	s_waitcnt vmcnt(0)
	v_cvt_f32_f16_e32 v172, v152
	v_cvt_f32_f16_sdwa v173, v152 dst_sel:DWORD dst_unused:UNUSED_PAD src0_sel:WORD_1
	v_cvt_f32_f16_e32 v174, v153
	v_cvt_f32_f16_sdwa v175, v153 dst_sel:DWORD dst_unused:UNUSED_PAD src0_sel:WORD_1
	v_cvt_f32_f16_e32 v176, v154
	v_cvt_f32_f16_sdwa v177, v154 dst_sel:DWORD dst_unused:UNUSED_PAD src0_sel:WORD_1
	v_cvt_f32_f16_e32 v178, v155
	v_cvt_f32_f16_sdwa v179, v155 dst_sel:DWORD dst_unused:UNUSED_PAD src0_sel:WORD_1
	global_load_dwordx4 v[152:155], v[150:151], off offset:64
	v_pk_fma_f32 v[128:129], v[128:129], 0.5, v[174:175] op_sel_hi:[1,0,1]
	v_pk_fma_f32 v[126:127], v[126:127], 0.5, v[172:173] op_sel_hi:[1,0,1]
	v_pk_fma_f32 v[124:125], v[124:125], 0.5, v[178:179] op_sel_hi:[1,0,1]
	v_pk_fma_f32 v[122:123], v[122:123], 0.5, v[176:177] op_sel_hi:[1,0,1]
	v_cvt_pk_f16_f32 v125, v124, v125
	v_cvt_pk_f16_f32 v124, v122, v123
	v_cvt_pk_f16_f32 v123, v128, v129
	v_cvt_pk_f16_f32 v122, v126, v127
	global_store_dwordx4 v[150:151], v[122:125], off
	s_waitcnt vmcnt(1)
	v_cvt_f32_f16_e32 v180, v152
	v_cvt_f32_f16_sdwa v181, v152 dst_sel:DWORD dst_unused:UNUSED_PAD src0_sel:WORD_1
	v_cvt_f32_f16_e32 v182, v153
	v_cvt_f32_f16_sdwa v183, v153 dst_sel:DWORD dst_unused:UNUSED_PAD src0_sel:WORD_1
	v_cvt_f32_f16_e32 v184, v154
	v_cvt_f32_f16_sdwa v185, v154 dst_sel:DWORD dst_unused:UNUSED_PAD src0_sel:WORD_1
	v_cvt_f32_f16_e32 v186, v155
	v_cvt_f32_f16_sdwa v187, v155 dst_sel:DWORD dst_unused:UNUSED_PAD src0_sel:WORD_1
	v_pk_fma_f32 v[120:121], v[120:121], 0.5, v[182:183] op_sel_hi:[1,0,1]
	v_pk_fma_f32 v[118:119], v[118:119], 0.5, v[180:181] op_sel_hi:[1,0,1]
	v_pk_fma_f32 v[114:115], v[114:115], 0.5, v[184:185] op_sel_hi:[1,0,1]
	v_pk_fma_f32 v[116:117], v[116:117], 0.5, v[186:187] op_sel_hi:[1,0,1]
	v_or_b32_e32 v152, 16, v146
	v_cvt_pk_f16_f32 v117, v116, v117
	v_cvt_pk_f16_f32 v116, v114, v115
	v_cvt_pk_f16_f32 v115, v120, v121
	v_cvt_pk_f16_f32 v114, v118, v119
	global_store_dwordx4 v[150:151], v[114:117], off offset:64
	v_ashrrev_i32_e32 v153, 31, v152
	v_lshlrev_b64 v[152:153], 12, v[152:153]
	v_or_b32_e32 v114, 32, v146
	v_ashrrev_i32_e32 v115, 31, v114
	v_lshlrev_b64 v[114:115], 12, v[114:115]
	v_lshl_add_u64 v[152:153], s[64:65], 0, v[152:153]
	v_lshl_add_u64 v[114:115], s[64:65], 0, v[114:115]
	v_lshl_add_u64 v[152:153], v[152:153], 0, v[148:149]
	v_lshl_add_u64 v[120:121], v[114:115], 0, v[148:149]
	global_load_dwordx4 v[158:161], v[152:153], off
	global_load_dwordx4 v[114:117], v[120:121], off
	global_load_dwordx4 v[168:171], v[152:153], off offset:64
	s_waitcnt vmcnt(2)
	v_cvt_f32_f16_e32 v154, v158
	s_waitcnt vmcnt(1)
	v_cvt_f32_f16_e32 v122, v114
	v_cvt_f32_f16_sdwa v123, v114 dst_sel:DWORD dst_unused:UNUSED_PAD src0_sel:WORD_1
	v_cvt_f32_f16_e32 v124, v115
	v_cvt_f32_f16_sdwa v125, v115 dst_sel:DWORD dst_unused:UNUSED_PAD src0_sel:WORD_1
	v_cvt_f32_f16_e32 v126, v116
	v_cvt_f32_f16_sdwa v127, v116 dst_sel:DWORD dst_unused:UNUSED_PAD src0_sel:WORD_1
	v_cvt_f32_f16_e32 v128, v117
	v_cvt_f32_f16_sdwa v129, v117 dst_sel:DWORD dst_unused:UNUSED_PAD src0_sel:WORD_1
	global_load_dwordx4 v[114:117], v[120:121], off offset:64
	s_waitcnt vmcnt(1)
	v_cvt_f32_f16_e32 v188, v168
	v_cvt_f32_f16_sdwa v189, v168 dst_sel:DWORD dst_unused:UNUSED_PAD src0_sel:WORD_1
	v_cvt_f32_f16_e32 v168, v169
	v_cvt_f32_f16_sdwa v169, v169 dst_sel:DWORD dst_unused:UNUSED_PAD src0_sel:WORD_1
	v_cvt_f32_f16_e32 v190, v170
	v_cvt_f32_f16_sdwa v191, v170 dst_sel:DWORD dst_unused:UNUSED_PAD src0_sel:WORD_1
	v_cvt_f32_f16_e32 v170, v171
	v_cvt_f32_f16_sdwa v171, v171 dst_sel:DWORD dst_unused:UNUSED_PAD src0_sel:WORD_1
	v_pk_fma_f32 v[104:105], v[104:105], 0.5, v[168:169] op_sel_hi:[1,0,1]
	v_pk_fma_f32 v[102:103], v[102:103], 0.5, v[188:189] op_sel_hi:[1,0,1]
	v_pk_fma_f32 v[98:99], v[98:99], 0.5, v[190:191] op_sel_hi:[1,0,1]
	v_pk_fma_f32 v[100:101], v[100:101], 0.5, v[170:171] op_sel_hi:[1,0,1]
	v_cvt_f32_f16_sdwa v155, v158 dst_sel:DWORD dst_unused:UNUSED_PAD src0_sel:WORD_1
	v_cvt_f32_f16_e32 v158, v159
	v_cvt_f32_f16_sdwa v159, v159 dst_sel:DWORD dst_unused:UNUSED_PAD src0_sel:WORD_1
	v_cvt_f32_f16_e32 v156, v160
	v_cvt_f32_f16_sdwa v157, v160 dst_sel:DWORD dst_unused:UNUSED_PAD src0_sel:WORD_1
	v_cvt_f32_f16_e32 v160, v161
	v_cvt_f32_f16_sdwa v161, v161 dst_sel:DWORD dst_unused:UNUSED_PAD src0_sel:WORD_1
	v_cvt_pk_f16_f32 v101, v100, v101
	v_cvt_pk_f16_f32 v100, v98, v99
	v_cvt_pk_f16_f32 v99, v104, v105
	v_cvt_pk_f16_f32 v98, v102, v103
	global_store_dwordx4 v[152:153], v[98:101], off offset:64
	v_pk_fma_f32 v[112:113], v[112:113], 0.5, v[158:159] op_sel_hi:[1,0,1]
	v_pk_fma_f32 v[110:111], v[110:111], 0.5, v[154:155] op_sel_hi:[1,0,1]
	v_or_b32_e32 v98, 48, v146
	v_ashrrev_i32_e32 v99, 31, v98
	v_lshlrev_b64 v[98:99], 12, v[98:99]
	v_pk_fma_f32 v[108:109], v[108:109], 0.5, v[160:161] op_sel_hi:[1,0,1]
	v_pk_fma_f32 v[106:107], v[106:107], 0.5, v[156:157] op_sel_hi:[1,0,1]
	v_lshl_add_u64 v[98:99], s[64:65], 0, v[98:99]
	v_cvt_pk_f16_f32 v109, v108, v109
	v_cvt_pk_f16_f32 v108, v106, v107
	v_cvt_pk_f16_f32 v107, v112, v113
	v_cvt_pk_f16_f32 v106, v110, v111
	v_lshl_add_u64 v[98:99], v[98:99], 0, v[148:149]
	global_store_dwordx4 v[152:153], v[106:109], off
	global_load_dwordx4 v[106:109], v[98:99], off
	v_pk_fma_f32 v[96:97], v[96:97], 0.5, v[124:125] op_sel_hi:[1,0,1]
	v_pk_fma_f32 v[94:95], v[94:95], 0.5, v[122:123] op_sel_hi:[1,0,1]
	v_pk_fma_f32 v[92:93], v[92:93], 0.5, v[128:129] op_sel_hi:[1,0,1]
	v_pk_fma_f32 v[90:91], v[90:91], 0.5, v[126:127] op_sel_hi:[1,0,1]
	v_cvt_pk_f16_f32 v93, v92, v93
	v_cvt_pk_f16_f32 v92, v90, v91
	v_cvt_pk_f16_f32 v91, v96, v97
	v_cvt_pk_f16_f32 v90, v94, v95
	global_store_dwordx4 v[120:121], v[90:93], off
	s_waitcnt vmcnt(4)
	v_cvt_f32_f16_e32 v176, v116
	v_cvt_f32_f16_sdwa v177, v116 dst_sel:DWORD dst_unused:UNUSED_PAD src0_sel:WORD_1
	v_cvt_f32_f16_e32 v178, v117
	v_cvt_f32_f16_sdwa v179, v117 dst_sel:DWORD dst_unused:UNUSED_PAD src0_sel:WORD_1
	global_load_dwordx4 v[116:119], v[98:99], off offset:64
	v_cvt_f32_f16_e32 v172, v114
	v_cvt_f32_f16_sdwa v173, v114 dst_sel:DWORD dst_unused:UNUSED_PAD src0_sel:WORD_1
	v_cvt_f32_f16_e32 v174, v115
	v_cvt_f32_f16_sdwa v175, v115 dst_sel:DWORD dst_unused:UNUSED_PAD src0_sel:WORD_1
	v_pk_fma_f32 v[84:85], v[84:85], 0.5, v[178:179] op_sel_hi:[1,0,1]
	v_pk_fma_f32 v[86:87], v[86:87], 0.5, v[172:173] op_sel_hi:[1,0,1]
	v_pk_fma_f32 v[82:83], v[82:83], 0.5, v[176:177] op_sel_hi:[1,0,1]
	v_pk_fma_f32 v[88:89], v[88:89], 0.5, v[174:175] op_sel_hi:[1,0,1]
	v_cvt_pk_f16_f32 v85, v84, v85
	v_cvt_pk_f16_f32 v84, v82, v83
	v_cvt_pk_f16_f32 v83, v88, v89
	v_cvt_pk_f16_f32 v82, v86, v87
	global_store_dwordx4 v[120:121], v[82:85], off offset:64
	s_waitcnt vmcnt(3)
	v_cvt_f32_f16_e32 v102, v106
	v_cvt_f32_f16_sdwa v103, v106 dst_sel:DWORD dst_unused:UNUSED_PAD src0_sel:WORD_1
	v_cvt_f32_f16_e32 v110, v107
	v_cvt_f32_f16_sdwa v111, v107 dst_sel:DWORD dst_unused:UNUSED_PAD src0_sel:WORD_1
	v_cvt_f32_f16_e32 v106, v108
	v_cvt_f32_f16_sdwa v107, v108 dst_sel:DWORD dst_unused:UNUSED_PAD src0_sel:WORD_1
	v_cvt_f32_f16_e32 v114, v109
	v_cvt_f32_f16_sdwa v115, v109 dst_sel:DWORD dst_unused:UNUSED_PAD src0_sel:WORD_1
	v_lshl_add_u64 v[82:83], v[150:151], 0, s[0:1]
	s_mov_b32 s0, 0x80000
	v_add_co_u32_e32 v84, vcc, s0, v150
	v_pk_fma_f32 v[80:81], v[80:81], 0.5, v[110:111] op_sel_hi:[1,0,1]
	s_nop 0
	v_addc_co_u32_e32 v85, vcc, 0, v151, vcc
	global_load_dwordx4 v[90:93], v[84:85], off
	v_pk_fma_f32 v[78:79], v[78:79], 0.5, v[102:103] op_sel_hi:[1,0,1]
	v_pk_fma_f32 v[76:77], v[76:77], 0.5, v[114:115] op_sel_hi:[1,0,1]
	v_pk_fma_f32 v[74:75], v[74:75], 0.5, v[106:107] op_sel_hi:[1,0,1]
	v_cvt_pk_f16_f32 v77, v76, v77
	v_cvt_pk_f16_f32 v76, v74, v75
	v_cvt_pk_f16_f32 v75, v80, v81
	v_cvt_pk_f16_f32 v74, v78, v79
	global_store_dwordx4 v[98:99], v[74:77], off
	s_mov_b64 s[0:1], -1
	s_and_b64 vcc, exec, s[2:3]
	s_waitcnt vmcnt(3)
	v_cvt_f32_f16_e32 v100, v116
	v_cvt_f32_f16_sdwa v101, v116 dst_sel:DWORD dst_unused:UNUSED_PAD src0_sel:WORD_1
	v_cvt_f32_f16_e32 v108, v117
	v_cvt_f32_f16_sdwa v109, v117 dst_sel:DWORD dst_unused:UNUSED_PAD src0_sel:WORD_1
	v_cvt_f32_f16_e32 v104, v118
	v_cvt_f32_f16_sdwa v105, v118 dst_sel:DWORD dst_unused:UNUSED_PAD src0_sel:WORD_1
	v_cvt_f32_f16_e32 v112, v119
	v_cvt_f32_f16_sdwa v113, v119 dst_sel:DWORD dst_unused:UNUSED_PAD src0_sel:WORD_1
	v_pk_fma_f32 v[72:73], v[72:73], 0.5, v[108:109] op_sel_hi:[1,0,1]
	v_pk_fma_f32 v[70:71], v[70:71], 0.5, v[100:101] op_sel_hi:[1,0,1]
	v_pk_fma_f32 v[66:67], v[66:67], 0.5, v[104:105] op_sel_hi:[1,0,1]
	v_pk_fma_f32 v[68:69], v[68:69], 0.5, v[112:113] op_sel_hi:[1,0,1]
	global_load_dwordx4 v[116:119], v[82:83], off offset:64
	v_cvt_pk_f16_f32 v69, v68, v69
	v_cvt_pk_f16_f32 v68, v66, v67
	v_cvt_pk_f16_f32 v67, v72, v73
	v_cvt_pk_f16_f32 v66, v70, v71
	global_store_dwordx4 v[98:99], v[66:69], off offset:64
	s_waitcnt vmcnt(3)
	v_cvt_f32_f16_e32 v86, v90
	v_add_u32_e32 v66, 0x90, v146
	v_ashrrev_i32_e32 v67, 31, v66
	v_lshlrev_b64 v[66:67], 12, v[66:67]
	v_lshl_add_u64 v[66:67], s[64:65], 0, v[66:67]
	v_lshl_add_u64 v[68:69], v[66:67], 0, v[148:149]
	global_load_dwordx4 v[74:77], v[68:69], off
	global_load_dwordx4 v[98:101], v[68:69], off offset:64
	v_cvt_f32_f16_sdwa v87, v90 dst_sel:DWORD dst_unused:UNUSED_PAD src0_sel:WORD_1
	v_cvt_f32_f16_e32 v90, v91
	v_cvt_f32_f16_sdwa v91, v91 dst_sel:DWORD dst_unused:UNUSED_PAD src0_sel:WORD_1
	v_cvt_f32_f16_e32 v88, v92
	v_cvt_f32_f16_sdwa v89, v92 dst_sel:DWORD dst_unused:UNUSED_PAD src0_sel:WORD_1
	v_cvt_f32_f16_e32 v92, v93
	v_cvt_f32_f16_sdwa v93, v93 dst_sel:DWORD dst_unused:UNUSED_PAD src0_sel:WORD_1
	v_pk_fma_f32 v[64:65], v[64:65], 0.5, v[90:91] op_sel_hi:[1,0,1]
	v_pk_fma_f32 v[62:63], v[62:63], 0.5, v[86:87] op_sel_hi:[1,0,1]
	v_pk_fma_f32 v[58:59], v[58:59], 0.5, v[88:89] op_sel_hi:[1,0,1]
	v_pk_fma_f32 v[60:61], v[60:61], 0.5, v[92:93] op_sel_hi:[1,0,1]
	s_waitcnt vmcnt(3)
	v_cvt_f32_f16_e32 v94, v116
	v_cvt_f32_f16_sdwa v95, v116 dst_sel:DWORD dst_unused:UNUSED_PAD src0_sel:WORD_1
	v_cvt_f32_f16_e32 v116, v117
	v_cvt_f32_f16_sdwa v117, v117 dst_sel:DWORD dst_unused:UNUSED_PAD src0_sel:WORD_1
	v_cvt_f32_f16_e32 v96, v118
	v_cvt_f32_f16_sdwa v97, v118 dst_sel:DWORD dst_unused:UNUSED_PAD src0_sel:WORD_1
	v_cvt_f32_f16_e32 v118, v119
	v_cvt_f32_f16_sdwa v119, v119 dst_sel:DWORD dst_unused:UNUSED_PAD src0_sel:WORD_1
	v_pk_fma_f32 v[56:57], v[56:57], 0.5, v[116:117] op_sel_hi:[1,0,1]
	v_pk_fma_f32 v[54:55], v[54:55], 0.5, v[94:95] op_sel_hi:[1,0,1]
	v_pk_fma_f32 v[50:51], v[50:51], 0.5, v[96:97] op_sel_hi:[1,0,1]
	v_pk_fma_f32 v[52:53], v[52:53], 0.5, v[118:119] op_sel_hi:[1,0,1]
	v_cvt_pk_f16_f32 v61, v60, v61
	v_cvt_pk_f16_f32 v53, v52, v53
	v_cvt_pk_f16_f32 v52, v50, v51
	v_cvt_pk_f16_f32 v51, v56, v57
	v_cvt_pk_f16_f32 v50, v54, v55
	global_store_dwordx4 v[82:83], v[50:53], off offset:64
	v_cvt_pk_f16_f32 v60, v58, v59
	v_cvt_pk_f16_f32 v59, v64, v65
	v_add_u32_e32 v50, 0xa0, v146
	v_ashrrev_i32_e32 v51, 31, v50
	v_lshlrev_b64 v[50:51], 12, v[50:51]
	v_lshl_add_u64 v[50:51], s[64:65], 0, v[50:51]
	v_cvt_pk_f16_f32 v58, v62, v63
	v_lshl_add_u64 v[50:51], v[50:51], 0, v[148:149]
	global_store_dwordx4 v[84:85], v[58:61], off
	global_load_dwordx4 v[58:61], v[50:51], off
	s_waitcnt vmcnt(4)
	v_cvt_f32_f16_e32 v70, v74
	s_waitcnt vmcnt(3)
	v_cvt_f32_f16_e32 v78, v98
	v_cvt_f32_f16_sdwa v79, v98 dst_sel:DWORD dst_unused:UNUSED_PAD src0_sel:WORD_1
	v_cvt_f32_f16_e32 v98, v99
	v_cvt_f32_f16_sdwa v99, v99 dst_sel:DWORD dst_unused:UNUSED_PAD src0_sel:WORD_1
	v_cvt_f32_f16_e32 v80, v100
	v_cvt_f32_f16_sdwa v81, v100 dst_sel:DWORD dst_unused:UNUSED_PAD src0_sel:WORD_1
	v_cvt_f32_f16_e32 v100, v101
	v_cvt_f32_f16_sdwa v101, v101 dst_sel:DWORD dst_unused:UNUSED_PAD src0_sel:WORD_1
	v_cvt_f32_f16_sdwa v71, v74 dst_sel:DWORD dst_unused:UNUSED_PAD src0_sel:WORD_1
	v_cvt_f32_f16_e32 v74, v75
	v_cvt_f32_f16_sdwa v75, v75 dst_sel:DWORD dst_unused:UNUSED_PAD src0_sel:WORD_1
	v_cvt_f32_f16_e32 v72, v76
	v_cvt_f32_f16_sdwa v73, v76 dst_sel:DWORD dst_unused:UNUSED_PAD src0_sel:WORD_1
	v_cvt_f32_f16_e32 v76, v77
	v_cvt_f32_f16_sdwa v77, v77 dst_sel:DWORD dst_unused:UNUSED_PAD src0_sel:WORD_1
	v_pk_fma_f32 v[40:41], v[40:41], 0.5, v[98:99] op_sel_hi:[1,0,1]
	v_pk_fma_f32 v[38:39], v[38:39], 0.5, v[78:79] op_sel_hi:[1,0,1]
	v_pk_fma_f32 v[36:37], v[36:37], 0.5, v[100:101] op_sel_hi:[1,0,1]
	v_pk_fma_f32 v[34:35], v[34:35], 0.5, v[80:81] op_sel_hi:[1,0,1]
	global_load_dwordx4 v[82:85], v[50:51], off offset:64
	v_cvt_pk_f16_f32 v37, v36, v37
	v_cvt_pk_f16_f32 v36, v34, v35
	v_cvt_pk_f16_f32 v35, v40, v41
	v_cvt_pk_f16_f32 v34, v38, v39
	global_store_dwordx4 v[68:69], v[34:37], off offset:64
	v_pk_fma_f32 v[48:49], v[48:49], 0.5, v[74:75] op_sel_hi:[1,0,1]
	v_pk_fma_f32 v[46:47], v[46:47], 0.5, v[70:71] op_sel_hi:[1,0,1]
	v_add_u32_e32 v34, 0xb0, v146
	v_ashrrev_i32_e32 v35, 31, v34
	v_pk_fma_f32 v[44:45], v[44:45], 0.5, v[76:77] op_sel_hi:[1,0,1]
	v_pk_fma_f32 v[42:43], v[42:43], 0.5, v[72:73] op_sel_hi:[1,0,1]
	v_lshlrev_b64 v[34:35], 12, v[34:35]
	v_cvt_pk_f16_f32 v45, v44, v45
	v_cvt_pk_f16_f32 v44, v42, v43
	v_cvt_pk_f16_f32 v43, v48, v49
	v_cvt_pk_f16_f32 v42, v46, v47
	v_lshl_add_u64 v[34:35], s[64:65], 0, v[34:35]
	global_store_dwordx4 v[68:69], v[42:45], off
	s_waitcnt vmcnt(3)
	v_cvt_f32_f16_e32 v54, v58
	v_lshl_add_u64 v[42:43], v[34:35], 0, v[148:149]
	global_load_dwordx4 v[34:37], v[42:43], off
	global_load_dwordx4 v[38:41], v[42:43], off offset:64
	v_cvt_f32_f16_sdwa v55, v58 dst_sel:DWORD dst_unused:UNUSED_PAD src0_sel:WORD_1
	v_cvt_f32_f16_e32 v58, v59
	v_cvt_f32_f16_sdwa v59, v59 dst_sel:DWORD dst_unused:UNUSED_PAD src0_sel:WORD_1
	v_cvt_f32_f16_e32 v52, v60
	v_cvt_f32_f16_sdwa v53, v60 dst_sel:DWORD dst_unused:UNUSED_PAD src0_sel:WORD_1
	v_cvt_f32_f16_e32 v56, v61
	v_cvt_f32_f16_sdwa v57, v61 dst_sel:DWORD dst_unused:UNUSED_PAD src0_sel:WORD_1
	v_pk_fma_f32 v[32:33], v[32:33], 0.5, v[58:59] op_sel_hi:[1,0,1]
	v_pk_fma_f32 v[30:31], v[30:31], 0.5, v[54:55] op_sel_hi:[1,0,1]
	v_pk_fma_f32 v[26:27], v[26:27], 0.5, v[52:53] op_sel_hi:[1,0,1]
	v_pk_fma_f32 v[28:29], v[28:29], 0.5, v[56:57] op_sel_hi:[1,0,1]
	s_waitcnt vmcnt(4)
	v_cvt_f32_f16_e32 v62, v82
	v_cvt_f32_f16_sdwa v63, v82 dst_sel:DWORD dst_unused:UNUSED_PAD src0_sel:WORD_1
	v_cvt_f32_f16_e32 v66, v83
	v_cvt_f32_f16_sdwa v67, v83 dst_sel:DWORD dst_unused:UNUSED_PAD src0_sel:WORD_1
	v_cvt_f32_f16_e32 v60, v84
	v_cvt_f32_f16_sdwa v61, v84 dst_sel:DWORD dst_unused:UNUSED_PAD src0_sel:WORD_1
	v_cvt_f32_f16_e32 v64, v85
	v_cvt_f32_f16_sdwa v65, v85 dst_sel:DWORD dst_unused:UNUSED_PAD src0_sel:WORD_1
	v_pk_fma_f32 v[24:25], v[24:25], 0.5, v[66:67] op_sel_hi:[1,0,1]
	v_pk_fma_f32 v[22:23], v[22:23], 0.5, v[62:63] op_sel_hi:[1,0,1]
	v_pk_fma_f32 v[18:19], v[18:19], 0.5, v[60:61] op_sel_hi:[1,0,1]
	v_pk_fma_f32 v[20:21], v[20:21], 0.5, v[64:65] op_sel_hi:[1,0,1]
	v_cvt_pk_f16_f32 v29, v28, v29
	v_cvt_pk_f16_f32 v28, v26, v27
	v_cvt_pk_f16_f32 v27, v32, v33
	v_cvt_pk_f16_f32 v26, v30, v31
	v_cvt_pk_f16_f32 v21, v20, v21
	v_cvt_pk_f16_f32 v20, v18, v19
	v_cvt_pk_f16_f32 v19, v24, v25
	v_cvt_pk_f16_f32 v18, v22, v23
	global_store_dwordx4 v[50:51], v[26:29], off
	global_store_dwordx4 v[50:51], v[18:21], off offset:64
	s_waitcnt vmcnt(3)
	v_cvt_f32_f16_e32 v30, v34
	s_waitcnt vmcnt(2)
	v_cvt_f32_f16_e32 v18, v40
	v_cvt_f32_f16_sdwa v19, v40 dst_sel:DWORD dst_unused:UNUSED_PAD src0_sel:WORD_1
	v_cvt_f32_f16_e32 v20, v41
	v_cvt_f32_f16_sdwa v21, v41 dst_sel:DWORD dst_unused:UNUSED_PAD src0_sel:WORD_1
	v_cvt_f32_f16_e32 v22, v38
	v_cvt_f32_f16_sdwa v23, v38 dst_sel:DWORD dst_unused:UNUSED_PAD src0_sel:WORD_1
	v_cvt_f32_f16_e32 v24, v39
	v_cvt_f32_f16_sdwa v25, v39 dst_sel:DWORD dst_unused:UNUSED_PAD src0_sel:WORD_1
	v_cvt_f32_f16_e32 v26, v36
	v_cvt_f32_f16_sdwa v27, v36 dst_sel:DWORD dst_unused:UNUSED_PAD src0_sel:WORD_1
	v_cvt_f32_f16_e32 v28, v37
	v_cvt_f32_f16_sdwa v29, v37 dst_sel:DWORD dst_unused:UNUSED_PAD src0_sel:WORD_1
	v_cvt_f32_f16_sdwa v31, v34 dst_sel:DWORD dst_unused:UNUSED_PAD src0_sel:WORD_1
	v_cvt_f32_f16_e32 v32, v35
	v_cvt_f32_f16_sdwa v33, v35 dst_sel:DWORD dst_unused:UNUSED_PAD src0_sel:WORD_1
	v_pk_fma_f32 v[12:13], v[12:13], 0.5, v[28:29] op_sel_hi:[1,0,1]
	v_pk_fma_f32 v[14:15], v[14:15], 0.5, v[30:31] op_sel_hi:[1,0,1]
	v_pk_fma_f32 v[10:11], v[10:11], 0.5, v[26:27] op_sel_hi:[1,0,1]
	v_pk_fma_f32 v[16:17], v[16:17], 0.5, v[32:33] op_sel_hi:[1,0,1]
	v_pk_fma_f32 v[8:9], v[8:9], 0.5, v[24:25] op_sel_hi:[1,0,1]
	v_pk_fma_f32 v[6:7], v[6:7], 0.5, v[22:23] op_sel_hi:[1,0,1]
	v_pk_fma_f32 v[4:5], v[4:5], 0.5, v[20:21] op_sel_hi:[1,0,1]
	v_pk_fma_f32 v[2:3], v[2:3], 0.5, v[18:19] op_sel_hi:[1,0,1]
	v_cvt_pk_f16_f32 v13, v12, v13
	v_cvt_pk_f16_f32 v12, v10, v11
	v_cvt_pk_f16_f32 v11, v16, v17
	v_cvt_pk_f16_f32 v10, v14, v15
	v_cvt_pk_f16_f32 v5, v4, v5
	v_cvt_pk_f16_f32 v4, v2, v3
	v_cvt_pk_f16_f32 v3, v8, v9
	v_cvt_pk_f16_f32 v2, v6, v7
	global_store_dwordx4 v[42:43], v[10:13], off
	global_store_dwordx4 v[42:43], v[2:5], off offset:64
	s_cbranch_vccnz .LBB0_1225
	s_andn2_b64 vcc, exec, s[8:9]
	s_cbranch_vccnz .LBB0_1224
	s_barrier
	s_branch .LBB0_1224

.LBB0_2075:
	s_lshl_b32 s1, s1, 5
	s_mov_b64 s[24:25], 0x80
	s_and_b32 s1, s1, 0x60
	s_add_i32 m0, s33, 0x18000
	v_lshl_add_u64 v[8:9], v[8:9], 0, s[24:25]
	s_lshl_b32 s26, s0, 13
	s_lshl_b32 s27, s1, 7
	s_waitcnt vmcnt(2)
	s_barrier
	global_load_lds_dwordx4 v[8:9], off
	v_lshl_add_u64 v[6:7], v[6:7], 0, s[24:25]
	s_add_i32 m0, s33, 0x1a000
	s_add_i32 s58, s33, 0x8000
	s_add_i32 s59, s33, 0xa000
	global_load_lds_dwordx4 v[6:7], off
	v_lshl_add_u64 v[2:3], v[2:3], 0, s[24:25]
	s_mov_b32 m0, s58
	s_add_u32 s4, s40, 0x160080
	global_load_lds_dwordx4 v[2:3], off
	v_lshl_add_u64 v[2:3], v[4:5], 0, s[24:25]
	s_mov_b32 m0, s59
	s_addc_u32 s5, s41, 0
	global_load_lds_dwordx4 v[2:3], off
	s_add_i32 m0, s33, 0x1c000
	v_lshl_add_u64 v[2:3], s[4:5], 0, v[148:149]
	global_load_lds_dwordx4 v[2:3], off
	v_lshl_add_u64 v[2:3], s[4:5], 0, v[152:153]
	s_add_i32 m0, s33, 0x1e000
	v_lshlrev_b32_e32 v4, 2, v0
	global_load_lds_dwordx4 v[2:3], off
	v_and_b32_e32 v2, 15, v0
	v_lshl_or_b32 v1, s0, 6, v2
	v_lshlrev_b32_e32 v3, 1, v12
	v_lshlrev_b32_e32 v5, 6, v0
	s_movk_i32 s0, 0x3c0
	v_lshl_or_b32 v2, v2, 6, v3
	v_and_b32_e32 v4, 32, v4
	v_and_or_b32 v3, v5, s0, v3
	v_bitop3_b32 v176, s27, v3, v4 bitop3:0xf6
	v_add_u32_e32 v176, s27, v176
	s_waitcnt vmcnt(6)
	s_cmpk_lt_u32 s2, 0x100
	v_add_u16_e32 v3, v10, v11
	v_bitop3_b32 v2, v2, s26, v4 bitop3:0xde
	s_cselect_b64 s[26:27], -1, 0
	v_lshrrev_b16_e32 v3, 1, v3
	s_add_i32 s61, 0, 0x10000
	s_add_i32 s70, 0, 0x14000
	s_sext_i32_i8 s74, s3
	s_ashr_i32 s60, s11, 31
	v_lshl_or_b32 v177, s1, 1, v12
	v_add_lshl_u32 v154, v13, v3, 1
	v_mov_b32_e32 v155, v149
	v_add_lshl_u32 v156, v14, v3, 1
	v_mov_b32_e32 v157, v149
	v_mov_b64_e32 v[158:159], 0x100
	v_mov_b64_e32 v[160:161], 0xff
	v_add_u32_e32 v178, s61, v176
	v_add_u32_e32 v179, 0x11000, v176
	v_add_u32_e32 v180, 0, v2
	s_barrier
	s_branch .LBB0_2078

.LBB0_2089:
	ds_read_b128 v[130:133], v178
	ds_read_b128 v[134:137], v178 offset:1024
	ds_read_b128 v[138:141], v178 offset:2048
	ds_read_b128 v[142:145], v178 offset:3072
	ds_read_b128 v[162:165], v179
	ds_read_b128 v[166:169], v179 offset:1024
	ds_read_b128 v[170:173], v179 offset:2048
	ds_read_b128 v[182:185], v179 offset:3072
	s_add_u32 s34, s38, 0xffea0080
	s_addc_u32 s35, s39, -1
	s_cmpk_eq_i32 s52, 0x54
	s_cselect_b32 s41, s5, s35
	s_cselect_b32 s40, s4, s34
	s_cselect_b32 s35, s37, s1
	s_cselect_b32 s34, s36, s0
	v_lshl_add_u64 v[174:175], s[38:39], 0, v[154:155]
	s_add_i32 m0, s33, 0xc000
	ds_read_b128 v[186:189], v180
	ds_read_b128 v[190:193], v180 offset:1024
	ds_read_b128 v[194:197], v180 offset:2048
	ds_read_b128 v[198:201], v180 offset:3072
	ds_read_b128 v[202:205], v180 offset:4096
	ds_read_b128 v[206:209], v180 offset:5120
	ds_read_b128 v[210:213], v180 offset:6144
	ds_read_b128 v[218:221], v180 offset:7168
	global_load_lds_dwordx4 v[174:175], off
	v_lshl_add_u64 v[174:175], s[38:39], 0, v[156:157]
	s_add_i32 m0, s33, 0xe000
	s_nop 0
	global_load_lds_dwordx4 v[174:175], off
	s_waitcnt vmcnt(8)
	s_waitcnt lgkmcnt(0)
	s_barrier
	s_setprio 1
	s_waitcnt lgkmcnt(0)
	v_mfma_f32_16x16x32_bf16 v[126:129], v[130:133], v[186:189], v[126:129]
	v_mfma_f32_16x16x32_bf16 v[122:125], v[138:141], v[186:189], v[122:125]
	v_mfma_f32_16x16x32_bf16 v[110:113], v[130:133], v[194:197], v[110:113]
	v_mfma_f32_16x16x32_bf16 v[106:109], v[138:141], v[194:197], v[106:109]
	v_mfma_f32_16x16x32_bf16 v[94:97], v[130:133], v[202:205], v[94:97]
	v_mfma_f32_16x16x32_bf16 v[90:93], v[138:141], v[202:205], v[90:93]
	v_mfma_f32_16x16x32_bf16 v[78:81], v[130:133], v[210:213], v[78:81]
	v_mfma_f32_16x16x32_bf16 v[74:77], v[138:141], v[210:213], v[74:77]
	v_mfma_f32_16x16x32_bf16 v[126:129], v[134:137], v[190:193], v[126:129]
	v_mfma_f32_16x16x32_bf16 v[122:125], v[142:145], v[190:193], v[122:125]
	v_mfma_f32_16x16x32_bf16 v[110:113], v[134:137], v[198:201], v[110:113]
	v_mfma_f32_16x16x32_bf16 v[106:109], v[142:145], v[198:201], v[106:109]
	v_mfma_f32_16x16x32_bf16 v[94:97], v[134:137], v[206:209], v[94:97]
	v_mfma_f32_16x16x32_bf16 v[90:93], v[142:145], v[206:209], v[90:93]
	v_mfma_f32_16x16x32_bf16 v[78:81], v[134:137], v[218:221], v[78:81]
	v_mfma_f32_16x16x32_bf16 v[74:77], v[142:145], v[218:221], v[74:77]
	s_setprio 0
	s_setprio 1
	v_mfma_f32_16x16x32_bf16 v[118:121], v[162:165], v[186:189], v[118:121]
	v_mfma_f32_16x16x32_bf16 v[114:117], v[170:173], v[186:189], v[114:117]
	v_mfma_f32_16x16x32_bf16 v[102:105], v[162:165], v[194:197], v[102:105]
	v_mfma_f32_16x16x32_bf16 v[98:101], v[170:173], v[194:197], v[98:101]
	v_mfma_f32_16x16x32_bf16 v[86:89], v[162:165], v[202:205], v[86:89]
	v_mfma_f32_16x16x32_bf16 v[82:85], v[170:173], v[202:205], v[82:85]
	v_mfma_f32_16x16x32_bf16 v[70:73], v[162:165], v[210:213], v[70:73]
	v_mfma_f32_16x16x32_bf16 v[66:69], v[170:173], v[210:213], v[66:69]
	v_mfma_f32_16x16x32_bf16 v[118:121], v[166:169], v[190:193], v[118:121]
	v_mfma_f32_16x16x32_bf16 v[114:117], v[182:185], v[190:193], v[114:117]
	v_mfma_f32_16x16x32_bf16 v[102:105], v[166:169], v[198:201], v[102:105]
	v_mfma_f32_16x16x32_bf16 v[98:101], v[182:185], v[198:201], v[98:101]
	v_mfma_f32_16x16x32_bf16 v[86:89], v[166:169], v[206:209], v[86:89]
	v_mfma_f32_16x16x32_bf16 v[82:85], v[182:185], v[206:209], v[82:85]
	v_mfma_f32_16x16x32_bf16 v[70:73], v[166:169], v[218:221], v[70:73]
	v_mfma_f32_16x16x32_bf16 v[66:69], v[182:185], v[218:221], v[66:69]
	s_setprio 0
	s_barrier
	s_add_i32 s53, s61, s31
	v_lshl_add_u64 v[174:175], s[34:35], 0, v[148:149]
	s_mov_b32 m0, s53
	ds_read_b128 v[186:189], v180 offset:16384
	ds_read_b128 v[190:193], v180 offset:17408
	ds_read_b128 v[194:197], v180 offset:18432
	ds_read_b128 v[198:201], v180 offset:19456
	ds_read_b128 v[202:205], v180 offset:20480
	ds_read_b128 v[206:209], v180 offset:21504
	ds_read_b128 v[210:213], v180 offset:22528
	ds_read_b128 v[218:221], v180 offset:23552
	global_load_lds_dwordx4 v[174:175], off
	s_add_i32 m0, s53, 0x2000
	s_add_u32 s54, s34, 0x160000
	v_lshl_add_u64 v[214:215], s[34:35], 0, v[152:153]
	s_addc_u32 s55, s35, 0
	s_add_i32 s53, s70, s31
	global_load_lds_dwordx4 v[214:215], off
	v_lshl_add_u64 v[222:223], s[54:55], 0, v[148:149]
	s_mov_b32 m0, s53
	v_lshl_add_u64 v[224:225], s[40:41], 0, v[150:151]
	global_load_lds_dwordx4 v[222:223], off
	v_lshl_add_u64 v[222:223], s[54:55], 0, v[152:153]
	s_add_i32 m0, s53, 0x2000
	s_nop 0
	global_load_lds_dwordx4 v[222:223], off
	v_lshl_add_u64 v[222:223], s[40:41], 0, v[146:147]
	s_mov_b32 m0, s33
	s_nop 0
	global_load_lds_dwordx4 v[222:223], off
	s_mov_b32 m0, s46
	s_nop 0
	global_load_lds_dwordx4 v[224:225], off
	s_waitcnt vmcnt(8)
	s_waitcnt lgkmcnt(0)
	s_barrier
	s_setprio 1
	s_waitcnt lgkmcnt(0)
	v_mfma_f32_16x16x32_bf16 v[62:65], v[130:133], v[186:189], v[62:65]
	v_mfma_f32_16x16x32_bf16 v[58:61], v[138:141], v[186:189], v[58:61]
	v_mfma_f32_16x16x32_bf16 v[50:53], v[130:133], v[194:197], v[50:53]
	v_mfma_f32_16x16x32_bf16 v[42:45], v[138:141], v[194:197], v[42:45]
	v_mfma_f32_16x16x32_bf16 v[38:41], v[130:133], v[202:205], v[38:41]
	v_mfma_f32_16x16x32_bf16 v[34:37], v[138:141], v[202:205], v[34:37]
	v_mfma_f32_16x16x32_bf16 v[14:17], v[130:133], v[210:213], v[14:17]
	v_mfma_f32_16x16x32_bf16 v[10:13], v[138:141], v[210:213], v[10:13]
	v_mfma_f32_16x16x32_bf16 v[62:65], v[134:137], v[190:193], v[62:65]
	v_mfma_f32_16x16x32_bf16 v[58:61], v[142:145], v[190:193], v[58:61]
	v_mfma_f32_16x16x32_bf16 v[50:53], v[134:137], v[198:201], v[50:53]
	v_mfma_f32_16x16x32_bf16 v[42:45], v[142:145], v[198:201], v[42:45]
	v_mfma_f32_16x16x32_bf16 v[38:41], v[134:137], v[206:209], v[38:41]
	v_mfma_f32_16x16x32_bf16 v[34:37], v[142:145], v[206:209], v[34:37]
	v_mfma_f32_16x16x32_bf16 v[14:17], v[134:137], v[218:221], v[14:17]
	v_mfma_f32_16x16x32_bf16 v[10:13], v[142:145], v[218:221], v[10:13]
	s_setprio 0
	s_setprio 1
	v_mfma_f32_16x16x32_bf16 v[54:57], v[162:165], v[186:189], v[54:57]
	v_mfma_f32_16x16x32_bf16 v[46:49], v[170:173], v[186:189], v[46:49]
	v_mfma_f32_16x16x32_bf16 v[30:33], v[162:165], v[194:197], v[30:33]
	v_mfma_f32_16x16x32_bf16 v[26:29], v[170:173], v[194:197], v[26:29]
	v_mfma_f32_16x16x32_bf16 v[22:25], v[162:165], v[202:205], v[22:25]
	v_mfma_f32_16x16x32_bf16 v[18:21], v[170:173], v[202:205], v[18:21]
	v_mfma_f32_16x16x32_bf16 v[6:9], v[162:165], v[210:213], v[6:9]
	v_mfma_f32_16x16x32_bf16 v[2:5], v[170:173], v[210:213], v[2:5]
	v_mfma_f32_16x16x32_bf16 v[54:57], v[166:169], v[190:193], v[54:57]
	v_mfma_f32_16x16x32_bf16 v[46:49], v[182:185], v[190:193], v[46:49]
	v_mfma_f32_16x16x32_bf16 v[30:33], v[166:169], v[198:201], v[30:33]
	v_mfma_f32_16x16x32_bf16 v[26:29], v[182:185], v[198:201], v[26:29]
	v_mfma_f32_16x16x32_bf16 v[22:25], v[166:169], v[206:209], v[22:25]
	v_mfma_f32_16x16x32_bf16 v[18:21], v[182:185], v[206:209], v[18:21]
	v_mfma_f32_16x16x32_bf16 v[6:9], v[166:169], v[218:221], v[6:9]
	v_mfma_f32_16x16x32_bf16 v[2:5], v[182:185], v[218:221], v[2:5]
	s_setprio 0
	s_barrier
	s_add_i32 s53, 0, 0x18000
	s_add_i32 s54, 0, 0x1c000
	v_add_u32_e32 v142, s53, v176
	v_add_u32_e32 v181, 0x19000, v176
	ds_read_b128 v[130:133], v142
	ds_read_b128 v[134:137], v142 offset:1024
	ds_read_b128 v[138:141], v142 offset:2048
	ds_read_b128 v[142:145], v142 offset:3072
	ds_read_b128 v[162:165], v181
	ds_read_b128 v[166:169], v181 offset:1024
	ds_read_b128 v[170:173], v181 offset:2048
	ds_read_b128 v[182:185], v181 offset:3072
	s_add_u32 s40, s40, 0x160000
	s_addc_u32 s41, s41, 0
	s_mov_b32 m0, s47
	v_lshl_add_u64 v[226:227], s[40:41], 0, v[146:147]
	ds_read_b128 v[186:189], v180 offset:32768
	ds_read_b128 v[190:193], v180 offset:33792
	ds_read_b128 v[194:197], v180 offset:34816
	ds_read_b128 v[198:201], v180 offset:35840
	ds_read_b128 v[202:205], v180 offset:36864
	ds_read_b128 v[206:209], v180 offset:37888
	ds_read_b128 v[210:213], v180 offset:38912
	ds_read_b128 v[218:221], v180 offset:39936
	global_load_lds_dwordx4 v[226:227], off
	v_lshl_add_u64 v[226:227], s[40:41], 0, v[150:151]
	s_mov_b32 m0, s56
	s_nop 0
	global_load_lds_dwordx4 v[226:227], off
	s_waitcnt vmcnt(8)
	s_waitcnt lgkmcnt(0)
	s_barrier
	s_setprio 1
	s_waitcnt lgkmcnt(0)
	v_mfma_f32_16x16x32_bf16 v[126:129], v[130:133], v[186:189], v[126:129]
	v_mfma_f32_16x16x32_bf16 v[122:125], v[138:141], v[186:189], v[122:125]
	v_mfma_f32_16x16x32_bf16 v[110:113], v[130:133], v[194:197], v[110:113]
	v_mfma_f32_16x16x32_bf16 v[106:109], v[138:141], v[194:197], v[106:109]
	v_mfma_f32_16x16x32_bf16 v[94:97], v[130:133], v[202:205], v[94:97]
	v_mfma_f32_16x16x32_bf16 v[90:93], v[138:141], v[202:205], v[90:93]
	v_mfma_f32_16x16x32_bf16 v[78:81], v[130:133], v[210:213], v[78:81]
	v_mfma_f32_16x16x32_bf16 v[74:77], v[138:141], v[210:213], v[74:77]
	v_mfma_f32_16x16x32_bf16 v[126:129], v[134:137], v[190:193], v[126:129]
	v_mfma_f32_16x16x32_bf16 v[122:125], v[142:145], v[190:193], v[122:125]
	v_mfma_f32_16x16x32_bf16 v[110:113], v[134:137], v[198:201], v[110:113]
	v_mfma_f32_16x16x32_bf16 v[106:109], v[142:145], v[198:201], v[106:109]
	v_mfma_f32_16x16x32_bf16 v[94:97], v[134:137], v[206:209], v[94:97]
	v_mfma_f32_16x16x32_bf16 v[90:93], v[142:145], v[206:209], v[90:93]
	v_mfma_f32_16x16x32_bf16 v[78:81], v[134:137], v[218:221], v[78:81]
	v_mfma_f32_16x16x32_bf16 v[74:77], v[142:145], v[218:221], v[74:77]
	s_setprio 0
	s_setprio 1
	v_mfma_f32_16x16x32_bf16 v[118:121], v[162:165], v[186:189], v[118:121]
	v_mfma_f32_16x16x32_bf16 v[114:117], v[170:173], v[186:189], v[114:117]
	v_mfma_f32_16x16x32_bf16 v[102:105], v[162:165], v[194:197], v[102:105]
	v_mfma_f32_16x16x32_bf16 v[98:101], v[170:173], v[194:197], v[98:101]
	v_mfma_f32_16x16x32_bf16 v[86:89], v[162:165], v[202:205], v[86:89]
	v_mfma_f32_16x16x32_bf16 v[82:85], v[170:173], v[202:205], v[82:85]
	v_mfma_f32_16x16x32_bf16 v[70:73], v[162:165], v[210:213], v[70:73]
	v_mfma_f32_16x16x32_bf16 v[66:69], v[170:173], v[210:213], v[66:69]
	v_mfma_f32_16x16x32_bf16 v[118:121], v[166:169], v[190:193], v[118:121]
	v_mfma_f32_16x16x32_bf16 v[114:117], v[182:185], v[190:193], v[114:117]
	v_mfma_f32_16x16x32_bf16 v[102:105], v[166:169], v[198:201], v[102:105]
	v_mfma_f32_16x16x32_bf16 v[98:101], v[182:185], v[198:201], v[98:101]
	v_mfma_f32_16x16x32_bf16 v[86:89], v[166:169], v[206:209], v[86:89]
	v_mfma_f32_16x16x32_bf16 v[82:85], v[182:185], v[206:209], v[82:85]
	v_mfma_f32_16x16x32_bf16 v[70:73], v[166:169], v[218:221], v[70:73]
	v_mfma_f32_16x16x32_bf16 v[66:69], v[182:185], v[218:221], v[66:69]
	s_setprio 0
	s_barrier
	s_add_i32 s40, s53, s31
	v_lshl_add_u64 v[174:175], v[174:175], 0, s[24:25]
	s_mov_b32 m0, s40
	ds_read_b128 v[186:189], v180 offset:49152
	ds_read_b128 v[190:193], v180 offset:50176
	ds_read_b128 v[194:197], v180 offset:51200
	ds_read_b128 v[198:201], v180 offset:52224
	ds_read_b128 v[202:205], v180 offset:53248
	ds_read_b128 v[206:209], v180 offset:54272
	ds_read_b128 v[210:213], v180 offset:55296
	ds_read_b128 v[218:221], v180 offset:56320
	global_load_lds_dwordx4 v[174:175], off
	s_add_i32 m0, s40, 0x2000
	s_add_u32 s34, s34, 0x160080
	v_lshl_add_u64 v[174:175], v[214:215], 0, s[24:25]
	s_addc_u32 s35, s35, 0
	s_add_i32 s40, s54, s31
	global_load_lds_dwordx4 v[174:175], off
	v_lshl_add_u64 v[174:175], s[34:35], 0, v[148:149]
	s_mov_b32 m0, s40
	s_nop 0
	global_load_lds_dwordx4 v[174:175], off
	v_lshl_add_u64 v[174:175], s[34:35], 0, v[152:153]
	s_add_i32 m0, s40, 0x2000
	s_nop 0
	global_load_lds_dwordx4 v[174:175], off
	v_lshl_add_u64 v[174:175], v[222:223], 0, s[24:25]
	s_mov_b32 m0, s58
	s_nop 0
	global_load_lds_dwordx4 v[174:175], off
	v_lshl_add_u64 v[174:175], v[224:225], 0, s[24:25]
	s_mov_b32 m0, s59
	s_nop 0
	global_load_lds_dwordx4 v[174:175], off
	s_waitcnt vmcnt(8)
	s_waitcnt lgkmcnt(0)
	s_barrier
	s_setprio 1
	s_waitcnt lgkmcnt(0)
	v_mfma_f32_16x16x32_bf16 v[62:65], v[130:133], v[186:189], v[62:65]
	v_mfma_f32_16x16x32_bf16 v[58:61], v[138:141], v[186:189], v[58:61]
	v_mfma_f32_16x16x32_bf16 v[50:53], v[130:133], v[194:197], v[50:53]
	v_mfma_f32_16x16x32_bf16 v[42:45], v[138:141], v[194:197], v[42:45]
	v_mfma_f32_16x16x32_bf16 v[38:41], v[130:133], v[202:205], v[38:41]
	v_mfma_f32_16x16x32_bf16 v[34:37], v[138:141], v[202:205], v[34:37]
	v_mfma_f32_16x16x32_bf16 v[14:17], v[130:133], v[210:213], v[14:17]
	v_mfma_f32_16x16x32_bf16 v[10:13], v[138:141], v[210:213], v[10:13]
	v_mfma_f32_16x16x32_bf16 v[62:65], v[134:137], v[190:193], v[62:65]
	v_mfma_f32_16x16x32_bf16 v[58:61], v[142:145], v[190:193], v[58:61]
	v_mfma_f32_16x16x32_bf16 v[50:53], v[134:137], v[198:201], v[50:53]
	v_mfma_f32_16x16x32_bf16 v[42:45], v[142:145], v[198:201], v[42:45]
	v_mfma_f32_16x16x32_bf16 v[38:41], v[134:137], v[206:209], v[38:41]
	v_mfma_f32_16x16x32_bf16 v[34:37], v[142:145], v[206:209], v[34:37]
	v_mfma_f32_16x16x32_bf16 v[14:17], v[134:137], v[218:221], v[14:17]
	v_mfma_f32_16x16x32_bf16 v[10:13], v[142:145], v[218:221], v[10:13]
	s_setprio 0
	s_setprio 1
	v_mfma_f32_16x16x32_bf16 v[54:57], v[162:165], v[186:189], v[54:57]
	v_mfma_f32_16x16x32_bf16 v[46:49], v[170:173], v[186:189], v[46:49]
	v_mfma_f32_16x16x32_bf16 v[30:33], v[162:165], v[194:197], v[30:33]
	v_mfma_f32_16x16x32_bf16 v[26:29], v[170:173], v[194:197], v[26:29]
	v_mfma_f32_16x16x32_bf16 v[22:25], v[162:165], v[202:205], v[22:25]
	v_mfma_f32_16x16x32_bf16 v[18:21], v[170:173], v[202:205], v[18:21]
	v_mfma_f32_16x16x32_bf16 v[6:9], v[162:165], v[210:213], v[6:9]
	v_mfma_f32_16x16x32_bf16 v[2:5], v[170:173], v[210:213], v[2:5]
	v_mfma_f32_16x16x32_bf16 v[54:57], v[166:169], v[190:193], v[54:57]
	v_mfma_f32_16x16x32_bf16 v[46:49], v[182:185], v[190:193], v[46:49]
	v_mfma_f32_16x16x32_bf16 v[30:33], v[166:169], v[198:201], v[30:33]
	v_mfma_f32_16x16x32_bf16 v[26:29], v[182:185], v[198:201], v[26:29]
	v_mfma_f32_16x16x32_bf16 v[22:25], v[166:169], v[206:209], v[22:25]
	v_mfma_f32_16x16x32_bf16 v[18:21], v[182:185], v[206:209], v[18:21]
	v_mfma_f32_16x16x32_bf16 v[6:9], v[166:169], v[218:221], v[6:9]
	v_mfma_f32_16x16x32_bf16 v[2:5], v[182:185], v[218:221], v[2:5]
	s_setprio 0
	s_barrier
	s_add_i32 s52, s52, 2
	s_add_u32 s38, s38, 0x100
	s_addc_u32 s39, s39, 0
	s_add_u32 s0, s0, 0x100
	s_addc_u32 s1, s1, 0
	s_cmpk_gt_u32 s52, 0x55
	s_cbranch_scc0 .LBB0_2089
	s_and_b64 vcc, exec, s[26:27]
	s_cbranch_vccz .LBB0_2092
	s_barrier
.LBB0_2092:
	v_lshl_or_b32 v130, s74, 8, v177
	v_lshl_add_u32 v162, s73, 8, v1
	v_ashrrev_i32_e32 v131, 31, v130
	v_lshlrev_b64 v[164:165], 1, v[130:131]
	v_or_b32_e32 v130, 16, v162
	v_ashrrev_i32_e32 v163, 31, v162
	v_ashrrev_i32_e32 v131, 31, v130
	v_lshlrev_b64 v[132:133], 12, v[162:163]
	v_lshlrev_b64 v[130:131], 12, v[130:131]
	v_lshl_add_u64 v[132:133], s[64:65], 0, v[132:133]
	v_lshl_add_u64 v[130:131], s[64:65], 0, v[130:131]
	v_lshl_add_u64 v[174:175], v[132:133], 0, v[164:165]
	v_lshl_add_u64 v[172:173], v[130:131], 0, v[164:165]
	global_load_dwordx4 v[134:137], v[174:175], off
	global_load_dwordx4 v[138:141], v[174:175], off offset:64
	global_load_dwordx4 v[142:145], v[172:173], off
	global_load_dwordx4 v[182:185], v[172:173], off offset:64
	v_or_b32_e32 v130, 32, v162
	v_ashrrev_i32_e32 v131, 31, v130
	v_lshlrev_b64 v[130:131], 12, v[130:131]
	v_lshl_add_u64 v[130:131], s[64:65], 0, v[130:131]
	v_lshl_add_u64 v[166:167], v[130:131], 0, v[164:165]
	global_load_dwordx4 v[186:189], v[166:167], off
	global_load_dwordx4 v[190:193], v[166:167], off offset:64
	v_or_b32_e32 v130, 48, v162
	v_ashrrev_i32_e32 v131, 31, v130
	v_lshlrev_b64 v[130:131], 12, v[130:131]
	s_mov_b32 s0, 0x80000
	v_lshl_add_u64 v[130:131], s[64:65], 0, v[130:131]
	v_lshl_add_u64 v[170:171], v[130:131], 0, v[164:165]
	v_add_co_u32_e32 v168, vcc, s0, v174
	s_mov_b64 s[0:1], 0x80000
	s_nop 0
	v_addc_co_u32_e32 v169, vcc, 0, v175, vcc
	global_load_dwordx4 v[194:197], v[170:171], off
	global_load_dwordx4 v[198:201], v[170:171], off offset:64
	global_load_dwordx4 v[130:133], v[168:169], off
	s_and_b64 vcc, exec, s[2:3]
	s_waitcnt vmcnt(0)
	v_cvt_f32_f16_e32 v202, v134
	v_cvt_f32_f16_e32 v210, v142
	v_cvt_f32_f16_sdwa v211, v142 dst_sel:DWORD dst_unused:UNUSED_PAD src0_sel:WORD_1
	v_cvt_f32_f16_e32 v212, v144
	v_cvt_f32_f16_sdwa v213, v144 dst_sel:DWORD dst_unused:UNUSED_PAD src0_sel:WORD_1
	v_cvt_f32_f16_e32 v144, v145
	v_cvt_f32_f16_sdwa v145, v145 dst_sel:DWORD dst_unused:UNUSED_PAD src0_sel:WORD_1
	v_cvt_f32_f16_e32 v218, v184
	v_cvt_f32_f16_sdwa v219, v184 dst_sel:DWORD dst_unused:UNUSED_PAD src0_sel:WORD_1
	v_cvt_f32_f16_e32 v214, v182
	v_cvt_f32_f16_sdwa v215, v182 dst_sel:DWORD dst_unused:UNUSED_PAD src0_sel:WORD_1
	v_cvt_f32_f16_sdwa v203, v134 dst_sel:DWORD dst_unused:UNUSED_PAD src0_sel:WORD_1
	v_cvt_f32_f16_e32 v134, v135
	v_cvt_f32_f16_sdwa v135, v135 dst_sel:DWORD dst_unused:UNUSED_PAD src0_sel:WORD_1
	v_cvt_f32_f16_e32 v204, v136
	v_cvt_f32_f16_sdwa v205, v136 dst_sel:DWORD dst_unused:UNUSED_PAD src0_sel:WORD_1
	v_cvt_f32_f16_e32 v136, v137
	v_cvt_f32_f16_sdwa v137, v137 dst_sel:DWORD dst_unused:UNUSED_PAD src0_sel:WORD_1
	v_cvt_f32_f16_e32 v206, v138
	v_cvt_f32_f16_sdwa v207, v138 dst_sel:DWORD dst_unused:UNUSED_PAD src0_sel:WORD_1
	v_cvt_f32_f16_e32 v138, v139
	v_cvt_f32_f16_sdwa v139, v139 dst_sel:DWORD dst_unused:UNUSED_PAD src0_sel:WORD_1
	v_cvt_f32_f16_e32 v208, v140
	v_cvt_f32_f16_sdwa v209, v140 dst_sel:DWORD dst_unused:UNUSED_PAD src0_sel:WORD_1
	v_cvt_f32_f16_e32 v140, v141
	v_cvt_f32_f16_sdwa v141, v141 dst_sel:DWORD dst_unused:UNUSED_PAD src0_sel:WORD_1
	v_cvt_f32_f16_e32 v142, v143
	v_cvt_f32_f16_sdwa v143, v143 dst_sel:DWORD dst_unused:UNUSED_PAD src0_sel:WORD_1
	v_pk_fma_f32 v[110:111], v[110:111], 0.5, v[210:211] op_sel_hi:[1,0,1]
	v_pk_fma_f32 v[108:109], v[108:109], 0.5, v[144:145] op_sel_hi:[1,0,1]
	v_pk_fma_f32 v[106:107], v[106:107], 0.5, v[212:213] op_sel_hi:[1,0,1]
	v_pk_fma_f32 v[98:99], v[98:99], 0.5, v[218:219] op_sel_hi:[1,0,1]
	v_cvt_pk_f16_f32 v109, v108, v109
	v_cvt_pk_f16_f32 v108, v106, v107
	v_cvt_pk_f16_f32 v106, v110, v111
	v_pk_fma_f32 v[110:111], v[102:103], 0.5, v[214:215] op_sel_hi:[1,0,1]
	v_cvt_pk_f16_f32 v102, v98, v99
	v_add_u32_e32 v98, 0x90, v162
	v_cvt_f32_f16_e32 v182, v183
	v_cvt_f32_f16_sdwa v183, v183 dst_sel:DWORD dst_unused:UNUSED_PAD src0_sel:WORD_1
	v_ashrrev_i32_e32 v99, 31, v98
	v_pk_fma_f32 v[128:129], v[128:129], 0.5, v[134:135] op_sel_hi:[1,0,1]
	v_pk_fma_f32 v[126:127], v[126:127], 0.5, v[202:203] op_sel_hi:[1,0,1]
	v_pk_fma_f32 v[124:125], v[124:125], 0.5, v[136:137] op_sel_hi:[1,0,1]
	v_pk_fma_f32 v[122:123], v[122:123], 0.5, v[204:205] op_sel_hi:[1,0,1]
	v_lshlrev_b64 v[98:99], 12, v[98:99]
	v_pk_fma_f32 v[134:135], v[120:121], 0.5, v[138:139] op_sel_hi:[1,0,1]
	v_pk_fma_f32 v[136:137], v[118:119], 0.5, v[206:207] op_sel_hi:[1,0,1]
	v_pk_fma_f32 v[118:119], v[116:117], 0.5, v[140:141] op_sel_hi:[1,0,1]
	v_pk_fma_f32 v[138:139], v[114:115], 0.5, v[208:209] op_sel_hi:[1,0,1]
	v_cvt_pk_f16_f32 v117, v124, v125
	v_cvt_pk_f16_f32 v116, v122, v123
	v_cvt_pk_f16_f32 v115, v128, v129
	v_cvt_pk_f16_f32 v114, v126, v127
	v_pk_fma_f32 v[112:113], v[112:113], 0.5, v[142:143] op_sel_hi:[1,0,1]
	v_lshl_add_u64 v[98:99], s[64:65], 0, v[98:99]
	v_cvt_pk_f16_f32 v121, v118, v119
	v_cvt_pk_f16_f32 v120, v138, v139
	v_cvt_pk_f16_f32 v119, v134, v135
	v_cvt_pk_f16_f32 v118, v136, v137
	global_store_dwordx4 v[174:175], v[114:117], off
	global_store_dwordx4 v[174:175], v[118:121], off offset:64
	v_cvt_pk_f16_f32 v107, v112, v113
	v_lshl_add_u64 v[98:99], v[98:99], 0, v[164:165]
	global_store_dwordx4 v[172:173], v[106:109], off
	v_cvt_f32_f16_e32 v126, v192
	v_cvt_f32_f16_sdwa v127, v192 dst_sel:DWORD dst_unused:UNUSED_PAD src0_sel:WORD_1
	v_pk_fma_f32 v[108:109], v[104:105], 0.5, v[182:183] op_sel_hi:[1,0,1]
	global_load_dwordx4 v[104:107], v[98:99], off
	v_cvt_f32_f16_e32 v128, v193
	v_cvt_f32_f16_sdwa v129, v193 dst_sel:DWORD dst_unused:UNUSED_PAD src0_sel:WORD_1
	v_cvt_f32_f16_e32 v184, v185
	v_cvt_f32_f16_sdwa v185, v185 dst_sel:DWORD dst_unused:UNUSED_PAD src0_sel:WORD_1
	v_cvt_f32_f16_e32 v220, v186
	v_cvt_f32_f16_sdwa v221, v186 dst_sel:DWORD dst_unused:UNUSED_PAD src0_sel:WORD_1
	v_cvt_f32_f16_e32 v186, v187
	v_cvt_f32_f16_sdwa v187, v187 dst_sel:DWORD dst_unused:UNUSED_PAD src0_sel:WORD_1
	v_cvt_f32_f16_e32 v222, v188
	v_cvt_f32_f16_sdwa v223, v188 dst_sel:DWORD dst_unused:UNUSED_PAD src0_sel:WORD_1
	v_cvt_f32_f16_e32 v120, v189
	v_cvt_f32_f16_sdwa v121, v189 dst_sel:DWORD dst_unused:UNUSED_PAD src0_sel:WORD_1
	v_lshl_add_u64 v[114:115], v[174:175], 0, s[0:1]
	v_cvt_f32_f16_e32 v122, v190
	v_cvt_f32_f16_sdwa v123, v190 dst_sel:DWORD dst_unused:UNUSED_PAD src0_sel:WORD_1
	v_cvt_f32_f16_e32 v124, v191
	global_load_dwordx4 v[116:119], v[114:115], off offset:64
	v_cvt_f32_f16_sdwa v125, v191 dst_sel:DWORD dst_unused:UNUSED_PAD src0_sel:WORD_1
	v_pk_fma_f32 v[84:85], v[84:85], 0.5, v[128:129] op_sel_hi:[1,0,1]
	v_pk_fma_f32 v[82:83], v[82:83], 0.5, v[126:127] op_sel_hi:[1,0,1]
	v_cvt_f32_f16_e32 v136, v198
	v_cvt_f32_f16_sdwa v137, v198 dst_sel:DWORD dst_unused:UNUSED_PAD src0_sel:WORD_1
	v_cvt_f32_f16_e32 v138, v199
	v_cvt_f32_f16_sdwa v139, v199 dst_sel:DWORD dst_unused:UNUSED_PAD src0_sel:WORD_1
	v_cvt_f32_f16_e32 v140, v200
	v_cvt_f32_f16_sdwa v141, v200 dst_sel:DWORD dst_unused:UNUSED_PAD src0_sel:WORD_1
	v_cvt_f32_f16_e32 v142, v201
	v_cvt_f32_f16_sdwa v143, v201 dst_sel:DWORD dst_unused:UNUSED_PAD src0_sel:WORD_1
	v_cvt_pk_f16_f32 v85, v84, v85
	v_cvt_pk_f16_f32 v84, v82, v83
	v_add_u32_e32 v82, 0xa0, v162
	v_pk_fma_f32 v[100:101], v[100:101], 0.5, v[184:185] op_sel_hi:[1,0,1]
	v_pk_fma_f32 v[96:97], v[96:97], 0.5, v[186:187] op_sel_hi:[1,0,1]
	v_pk_fma_f32 v[94:95], v[94:95], 0.5, v[220:221] op_sel_hi:[1,0,1]
	v_pk_fma_f32 v[92:93], v[92:93], 0.5, v[120:121] op_sel_hi:[1,0,1]
	v_pk_fma_f32 v[90:91], v[90:91], 0.5, v[222:223] op_sel_hi:[1,0,1]
	v_ashrrev_i32_e32 v83, 31, v82
	v_cvt_pk_f16_f32 v103, v100, v101
	v_cvt_pk_f16_f32 v101, v108, v109
	v_cvt_pk_f16_f32 v100, v110, v111
	v_cvt_pk_f16_f32 v93, v92, v93
	v_cvt_pk_f16_f32 v92, v90, v91
	v_cvt_pk_f16_f32 v91, v96, v97
	v_cvt_pk_f16_f32 v90, v94, v95
	v_lshlrev_b64 v[82:83], 12, v[82:83]
	global_store_dwordx4 v[172:173], v[100:103], off offset:64
	global_load_dwordx4 v[100:103], v[98:99], off offset:64
	v_lshl_add_u64 v[82:83], s[64:65], 0, v[82:83]
	global_store_dwordx4 v[166:167], v[90:93], off
	v_cvt_f32_f16_e32 v108, v194
	v_cvt_f32_f16_sdwa v109, v194 dst_sel:DWORD dst_unused:UNUSED_PAD src0_sel:WORD_1
	v_pk_fma_f32 v[90:91], v[88:89], 0.5, v[124:125] op_sel_hi:[1,0,1]
	v_pk_fma_f32 v[92:93], v[86:87], 0.5, v[122:123] op_sel_hi:[1,0,1]
	v_cvt_f32_f16_e32 v110, v195
	v_cvt_f32_f16_sdwa v111, v195 dst_sel:DWORD dst_unused:UNUSED_PAD src0_sel:WORD_1
	v_cvt_f32_f16_e32 v112, v196
	v_cvt_f32_f16_sdwa v113, v196 dst_sel:DWORD dst_unused:UNUSED_PAD src0_sel:WORD_1
	v_cvt_f32_f16_e32 v134, v197
	v_cvt_f32_f16_sdwa v135, v197 dst_sel:DWORD dst_unused:UNUSED_PAD src0_sel:WORD_1
	v_lshl_add_u64 v[94:95], v[82:83], 0, v[164:165]
	v_cvt_pk_f16_f32 v83, v90, v91
	v_cvt_pk_f16_f32 v82, v92, v93
	v_pk_fma_f32 v[72:73], v[72:73], 0.5, v[138:139] op_sel_hi:[1,0,1]
	v_pk_fma_f32 v[70:71], v[70:71], 0.5, v[136:137] op_sel_hi:[1,0,1]
	v_pk_fma_f32 v[68:69], v[68:69], 0.5, v[142:143] op_sel_hi:[1,0,1]
	v_pk_fma_f32 v[66:67], v[66:67], 0.5, v[140:141] op_sel_hi:[1,0,1]
	global_load_dwordx4 v[86:89], v[94:95], off
	v_cvt_pk_f16_f32 v69, v68, v69
	global_store_dwordx4 v[166:167], v[82:85], off offset:64
	global_load_dwordx4 v[82:85], v[94:95], off offset:64
	v_cvt_pk_f16_f32 v68, v66, v67
	v_cvt_pk_f16_f32 v67, v72, v73
	v_cvt_pk_f16_f32 v66, v70, v71
	global_store_dwordx4 v[170:171], v[66:69], off offset:64
	v_pk_fma_f32 v[80:81], v[80:81], 0.5, v[110:111] op_sel_hi:[1,0,1]
	v_pk_fma_f32 v[78:79], v[78:79], 0.5, v[108:109] op_sel_hi:[1,0,1]
	v_add_u32_e32 v66, 0xb0, v162
	v_ashrrev_i32_e32 v67, 31, v66
	v_pk_fma_f32 v[76:77], v[76:77], 0.5, v[134:135] op_sel_hi:[1,0,1]
	v_pk_fma_f32 v[74:75], v[74:75], 0.5, v[112:113] op_sel_hi:[1,0,1]
	v_lshlrev_b64 v[66:67], 12, v[66:67]
	v_cvt_pk_f16_f32 v77, v76, v77
	v_cvt_pk_f16_f32 v76, v74, v75
	v_cvt_pk_f16_f32 v75, v80, v81
	v_cvt_pk_f16_f32 v74, v78, v79
	v_lshl_add_u64 v[66:67], s[64:65], 0, v[66:67]
	global_store_dwordx4 v[170:171], v[74:77], off
	v_cvt_f32_f16_e32 v90, v130
	v_cvt_f32_f16_sdwa v91, v130 dst_sel:DWORD dst_unused:UNUSED_PAD src0_sel:WORD_1
	s_waitcnt vmcnt(9)
	v_cvt_f32_f16_e32 v74, v104
	v_cvt_f32_f16_sdwa v75, v104 dst_sel:DWORD dst_unused:UNUSED_PAD src0_sel:WORD_1
	v_cvt_f32_f16_e32 v76, v105
	v_cvt_f32_f16_sdwa v77, v105 dst_sel:DWORD dst_unused:UNUSED_PAD src0_sel:WORD_1
	v_lshl_add_u64 v[104:105], v[66:67], 0, v[164:165]
	global_load_dwordx4 v[66:69], v[104:105], off
	global_load_dwordx4 v[70:73], v[104:105], off offset:64
	v_cvt_f32_f16_e32 v92, v131
	v_cvt_f32_f16_sdwa v93, v131 dst_sel:DWORD dst_unused:UNUSED_PAD src0_sel:WORD_1
	v_cvt_f32_f16_e32 v96, v132
	v_cvt_f32_f16_sdwa v97, v132 dst_sel:DWORD dst_unused:UNUSED_PAD src0_sel:WORD_1
	v_cvt_f32_f16_e32 v120, v133
	v_cvt_f32_f16_sdwa v121, v133 dst_sel:DWORD dst_unused:UNUSED_PAD src0_sel:WORD_1
	s_waitcnt vmcnt(10)
	v_cvt_f32_f16_e32 v122, v116
	v_cvt_f32_f16_sdwa v123, v116 dst_sel:DWORD dst_unused:UNUSED_PAD src0_sel:WORD_1
	v_cvt_f32_f16_e32 v116, v117
	v_cvt_f32_f16_sdwa v117, v117 dst_sel:DWORD dst_unused:UNUSED_PAD src0_sel:WORD_1
	v_cvt_f32_f16_e32 v124, v118
	v_cvt_f32_f16_sdwa v125, v118 dst_sel:DWORD dst_unused:UNUSED_PAD src0_sel:WORD_1
	v_cvt_f32_f16_e32 v118, v119
	v_cvt_f32_f16_sdwa v119, v119 dst_sel:DWORD dst_unused:UNUSED_PAD src0_sel:WORD_1
	v_cvt_f32_f16_e32 v78, v106
	v_cvt_f32_f16_sdwa v79, v106 dst_sel:DWORD dst_unused:UNUSED_PAD src0_sel:WORD_1
	v_cvt_f32_f16_e32 v80, v107
	v_cvt_f32_f16_sdwa v81, v107 dst_sel:DWORD dst_unused:UNUSED_PAD src0_sel:WORD_1
	v_pk_fma_f32 v[64:65], v[64:65], 0.5, v[92:93] op_sel_hi:[1,0,1]
	v_pk_fma_f32 v[62:63], v[62:63], 0.5, v[90:91] op_sel_hi:[1,0,1]
	v_pk_fma_f32 v[60:61], v[60:61], 0.5, v[120:121] op_sel_hi:[1,0,1]
	v_pk_fma_f32 v[58:59], v[58:59], 0.5, v[96:97] op_sel_hi:[1,0,1]
	v_pk_fma_f32 v[56:57], v[56:57], 0.5, v[116:117] op_sel_hi:[1,0,1]
	v_pk_fma_f32 v[54:55], v[54:55], 0.5, v[122:123] op_sel_hi:[1,0,1]
	v_pk_fma_f32 v[48:49], v[48:49], 0.5, v[118:119] op_sel_hi:[1,0,1]
	v_pk_fma_f32 v[46:47], v[46:47], 0.5, v[124:125] op_sel_hi:[1,0,1]
	v_cvt_pk_f16_f32 v61, v60, v61
	v_cvt_pk_f16_f32 v60, v58, v59
	v_cvt_pk_f16_f32 v59, v64, v65
	v_cvt_pk_f16_f32 v58, v62, v63
	v_cvt_pk_f16_f32 v49, v48, v49
	s_waitcnt vmcnt(8)
	v_cvt_f32_f16_e32 v106, v100
	v_cvt_f32_f16_sdwa v107, v100 dst_sel:DWORD dst_unused:UNUSED_PAD src0_sel:WORD_1
	v_cvt_f32_f16_e32 v100, v101
	v_cvt_f32_f16_sdwa v101, v101 dst_sel:DWORD dst_unused:UNUSED_PAD src0_sel:WORD_1
	v_cvt_f32_f16_e32 v108, v102
	v_cvt_f32_f16_sdwa v109, v102 dst_sel:DWORD dst_unused:UNUSED_PAD src0_sel:WORD_1
	v_cvt_f32_f16_e32 v102, v103
	v_cvt_f32_f16_sdwa v103, v103 dst_sel:DWORD dst_unused:UNUSED_PAD src0_sel:WORD_1
	v_cvt_pk_f16_f32 v48, v46, v47
	v_cvt_pk_f16_f32 v47, v56, v57
	v_cvt_pk_f16_f32 v46, v54, v55
	global_store_dwordx4 v[168:169], v[58:61], off
	global_store_dwordx4 v[114:115], v[46:49], off offset:64
	v_pk_fma_f32 v[32:33], v[32:33], 0.5, v[100:101] op_sel_hi:[1,0,1]
	v_pk_fma_f32 v[30:31], v[30:31], 0.5, v[106:107] op_sel_hi:[1,0,1]
	v_pk_fma_f32 v[28:29], v[28:29], 0.5, v[102:103] op_sel_hi:[1,0,1]
	v_pk_fma_f32 v[26:27], v[26:27], 0.5, v[108:109] op_sel_hi:[1,0,1]
	v_cvt_pk_f16_f32 v29, v28, v29
	v_cvt_pk_f16_f32 v28, v26, v27
	v_cvt_pk_f16_f32 v27, v32, v33
	s_waitcnt vmcnt(8)
	v_cvt_f32_f16_e32 v46, v86
	v_cvt_f32_f16_sdwa v47, v86 dst_sel:DWORD dst_unused:UNUSED_PAD src0_sel:WORD_1
	v_cvt_f32_f16_e32 v48, v87
	v_cvt_f32_f16_sdwa v49, v87 dst_sel:DWORD dst_unused:UNUSED_PAD src0_sel:WORD_1
	v_cvt_f32_f16_e32 v54, v88
	v_cvt_f32_f16_sdwa v55, v88 dst_sel:DWORD dst_unused:UNUSED_PAD src0_sel:WORD_1
	v_cvt_f32_f16_e32 v56, v89
	v_cvt_f32_f16_sdwa v57, v89 dst_sel:DWORD dst_unused:UNUSED_PAD src0_sel:WORD_1
	s_waitcnt vmcnt(6)
	v_cvt_f32_f16_e32 v58, v82
	v_cvt_f32_f16_sdwa v59, v82 dst_sel:DWORD dst_unused:UNUSED_PAD src0_sel:WORD_1
	v_cvt_f32_f16_e32 v60, v83
	v_cvt_f32_f16_sdwa v61, v83 dst_sel:DWORD dst_unused:UNUSED_PAD src0_sel:WORD_1
	v_cvt_f32_f16_e32 v62, v84
	v_cvt_f32_f16_sdwa v63, v84 dst_sel:DWORD dst_unused:UNUSED_PAD src0_sel:WORD_1
	v_cvt_f32_f16_e32 v64, v85
	v_cvt_f32_f16_sdwa v65, v85 dst_sel:DWORD dst_unused:UNUSED_PAD src0_sel:WORD_1
	v_cvt_pk_f16_f32 v26, v30, v31
	global_store_dwordx4 v[98:99], v[26:29], off offset:64
	v_pk_fma_f32 v[30:31], v[38:39], 0.5, v[46:47] op_sel_hi:[1,0,1]
	v_pk_fma_f32 v[32:33], v[34:35], 0.5, v[54:55] op_sel_hi:[1,0,1]
	v_pk_fma_f32 v[26:27], v[40:41], 0.5, v[48:49] op_sel_hi:[1,0,1]
	v_pk_fma_f32 v[28:29], v[36:37], 0.5, v[56:57] op_sel_hi:[1,0,1]
	v_pk_fma_f32 v[24:25], v[24:25], 0.5, v[60:61] op_sel_hi:[1,0,1]
	v_pk_fma_f32 v[22:23], v[22:23], 0.5, v[58:59] op_sel_hi:[1,0,1]
	v_pk_fma_f32 v[20:21], v[20:21], 0.5, v[64:65] op_sel_hi:[1,0,1]
	v_pk_fma_f32 v[18:19], v[18:19], 0.5, v[62:63] op_sel_hi:[1,0,1]
	v_cvt_pk_f16_f32 v29, v28, v29
	v_cvt_pk_f16_f32 v28, v32, v33
	v_cvt_pk_f16_f32 v27, v26, v27
	v_cvt_pk_f16_f32 v26, v30, v31
	v_cvt_pk_f16_f32 v21, v20, v21
	v_cvt_pk_f16_f32 v20, v18, v19
	v_cvt_pk_f16_f32 v19, v24, v25
	v_cvt_pk_f16_f32 v18, v22, v23
	global_store_dwordx4 v[94:95], v[26:29], off
	global_store_dwordx4 v[94:95], v[18:21], off offset:64
	s_waitcnt vmcnt(5)
	v_cvt_f32_f16_e32 v22, v70
	v_cvt_f32_f16_sdwa v23, v70 dst_sel:DWORD dst_unused:UNUSED_PAD src0_sel:WORD_1
	v_cvt_f32_f16_e32 v18, v72
	v_cvt_f32_f16_sdwa v19, v72 dst_sel:DWORD dst_unused:UNUSED_PAD src0_sel:WORD_1
	v_cvt_f32_f16_e32 v20, v73
	v_cvt_f32_f16_sdwa v21, v73 dst_sel:DWORD dst_unused:UNUSED_PAD src0_sel:WORD_1
	v_cvt_f32_f16_e32 v24, v71
	v_cvt_f32_f16_sdwa v25, v71 dst_sel:DWORD dst_unused:UNUSED_PAD src0_sel:WORD_1
	v_cvt_f32_f16_e32 v26, v68
	v_cvt_f32_f16_e32 v28, v69
	v_cvt_f32_f16_e32 v30, v66
	v_cvt_f32_f16_e32 v32, v67
	v_cvt_f32_f16_sdwa v33, v67 dst_sel:DWORD dst_unused:UNUSED_PAD src0_sel:WORD_1
	v_cvt_f32_f16_sdwa v31, v66 dst_sel:DWORD dst_unused:UNUSED_PAD src0_sel:WORD_1
	v_cvt_f32_f16_sdwa v29, v69 dst_sel:DWORD dst_unused:UNUSED_PAD src0_sel:WORD_1
	v_cvt_f32_f16_sdwa v27, v68 dst_sel:DWORD dst_unused:UNUSED_PAD src0_sel:WORD_1
	v_pk_fma_f32 v[52:53], v[52:53], 0.5, v[76:77] op_sel_hi:[1,0,1]
	v_pk_fma_f32 v[50:51], v[50:51], 0.5, v[74:75] op_sel_hi:[1,0,1]
	v_pk_fma_f32 v[44:45], v[44:45], 0.5, v[80:81] op_sel_hi:[1,0,1]
	v_pk_fma_f32 v[42:43], v[42:43], 0.5, v[78:79] op_sel_hi:[1,0,1]
	v_pk_fma_f32 v[16:17], v[16:17], 0.5, v[32:33] op_sel_hi:[1,0,1]
	v_pk_fma_f32 v[14:15], v[14:15], 0.5, v[30:31] op_sel_hi:[1,0,1]
	v_pk_fma_f32 v[12:13], v[12:13], 0.5, v[28:29] op_sel_hi:[1,0,1]
	v_pk_fma_f32 v[10:11], v[10:11], 0.5, v[26:27] op_sel_hi:[1,0,1]
	v_pk_fma_f32 v[8:9], v[8:9], 0.5, v[24:25] op_sel_hi:[1,0,1]
	v_pk_fma_f32 v[6:7], v[6:7], 0.5, v[22:23] op_sel_hi:[1,0,1]
	v_pk_fma_f32 v[4:5], v[4:5], 0.5, v[20:21] op_sel_hi:[1,0,1]
	v_pk_fma_f32 v[2:3], v[2:3], 0.5, v[18:19] op_sel_hi:[1,0,1]
	v_cvt_pk_f16_f32 v45, v44, v45
	v_cvt_pk_f16_f32 v44, v42, v43
	v_cvt_pk_f16_f32 v43, v52, v53
	v_cvt_pk_f16_f32 v42, v50, v51
	v_cvt_pk_f16_f32 v13, v12, v13
	v_cvt_pk_f16_f32 v12, v10, v11
	v_cvt_pk_f16_f32 v11, v16, v17
	v_cvt_pk_f16_f32 v10, v14, v15
	v_cvt_pk_f16_f32 v5, v4, v5
	v_cvt_pk_f16_f32 v4, v2, v3
	v_cvt_pk_f16_f32 v3, v8, v9
	v_cvt_pk_f16_f32 v2, v6, v7
	s_mov_b64 s[0:1], -1
	global_store_dwordx4 v[98:99], v[42:45], off
	global_store_dwordx4 v[104:105], v[10:13], off
	global_store_dwordx4 v[104:105], v[2:5], off offset:64
	s_cbranch_vccnz .LBB0_2077
	s_andn2_b64 vcc, exec, s[8:9]
	s_cbranch_vccnz .LBB0_2076
	s_barrier
	s_branch .LBB0_2076

.LBB0_2928:
	s_lshl_b32 s1, s1, 5
	s_mov_b64 s[24:25], 0x80
	s_and_b32 s1, s1, 0x60
	s_add_i32 m0, s33, 0x18000
	v_lshl_add_u64 v[8:9], v[8:9], 0, s[24:25]
	s_lshl_b32 s34, s0, 13
	s_lshl_b32 s35, s1, 7
	s_waitcnt vmcnt(2)
	s_barrier
	global_load_lds_dwordx4 v[8:9], off
	v_lshl_add_u64 v[4:5], v[4:5], 0, s[24:25]
	s_add_i32 m0, s33, 0x1a000
	s_add_i32 s55, s33, 0x8000
	s_add_i32 s56, s33, 0xa000
	global_load_lds_dwordx4 v[4:5], off
	v_lshl_add_u64 v[2:3], v[2:3], 0, s[24:25]
	s_mov_b32 m0, s55
	s_add_u32 s26, s68, 0x80080
	global_load_lds_dwordx4 v[2:3], off
	v_lshl_add_u64 v[2:3], v[6:7], 0, s[24:25]
	s_mov_b32 m0, s56
	s_addc_u32 s27, s69, 0
	global_load_lds_dwordx4 v[2:3], off
	s_add_i32 m0, s33, 0x1c000
	v_lshl_add_u64 v[2:3], s[26:27], 0, v[144:145]
	global_load_lds_dwordx4 v[2:3], off
	v_lshl_add_u64 v[2:3], s[26:27], 0, v[148:149]
	s_add_i32 m0, s33, 0x1e000
	v_lshlrev_b32_e32 v4, 2, v0
	global_load_lds_dwordx4 v[2:3], off
	v_and_b32_e32 v2, 15, v0
	v_lshl_or_b32 v1, s0, 6, v2
	v_lshlrev_b32_e32 v3, 1, v13
	v_lshlrev_b32_e32 v5, 6, v0
	s_movk_i32 s0, 0x3c0
	v_lshl_or_b32 v2, v2, 6, v3
	v_and_b32_e32 v4, 32, v4
	v_and_or_b32 v3, v5, s0, v3
	v_bitop3_b32 v172, s35, v3, v4 bitop3:0xf6
	v_add_u32_e32 v172, s35, v172
	v_lshlrev_b32_e32 v3, 9, v0
	v_bitop3_b32 v2, v2, s34, v4 bitop3:0xde
	v_and_b32_e32 v3, 0x30000, v3
	v_lshlrev_b32_e32 v4, 12, v12
	v_or3_b32 v3, v10, v3, v4
	v_add_u32_e32 v150, v3, v11
	v_lshlrev_b32_e32 v3, 5, v14
	s_waitcnt vmcnt(6)
	s_cmpk_lt_u32 s3, 0x100
	v_and_b32_e32 v3, 0x70000, v3
	s_cselect_b64 s[26:27], -1, 0
	v_or3_b32 v3, v10, v3, v4
	s_add_i32 s58, 0, 0x10000
	s_add_i32 s59, 0, 0x14000
	s_sext_i32_i8 s61, s2
	s_ashr_i32 s57, s11, 31
	v_lshl_or_b32 v173, s1, 1, v13
	v_mov_b32_e32 v151, v145
	v_add_u32_e32 v152, v3, v11
	v_mov_b32_e32 v153, v145
	v_mov_b64_e32 v[154:155], 0x100
	v_mov_b64_e32 v[156:157], 0xff
	v_add_u32_e32 v174, s58, v172
	v_add_u32_e32 v175, 0x11000, v172
	v_add_u32_e32 v176, 0, v2
	s_mov_b32 s60, 0x80000
	s_barrier
	s_branch .LBB0_2931

.LBB0_2938:
	ds_read_b128 v[130:133], v174
	ds_read_b128 v[134:137], v174 offset:1024
	ds_read_b128 v[138:141], v174 offset:2048
	ds_read_b128 v[158:161], v174 offset:3072
	ds_read_b128 v[162:165], v175
	ds_read_b128 v[166:169], v175 offset:1024
	ds_read_b128 v[178:181], v175 offset:2048
	ds_read_b128 v[182:185], v175 offset:3072
	s_add_u32 s34, s46, 0xfff80080
	s_addc_u32 s35, s47, -1
	s_cmp_eq_u32 s72, 28
	s_cselect_b32 s69, s0, s35
	s_cselect_b32 s68, s1, s34
	s_cselect_b32 s35, s37, s71
	s_cselect_b32 s34, s39, s70
	v_lshl_add_u64 v[170:171], s[46:47], 0, v[150:151]
	s_add_i32 m0, s33, 0xc000
	ds_read_b128 v[186:189], v176
	ds_read_b128 v[190:193], v176 offset:1024
	ds_read_b128 v[194:197], v176 offset:2048
	ds_read_b128 v[198:201], v176 offset:3072
	ds_read_b128 v[202:205], v176 offset:4096
	ds_read_b128 v[206:209], v176 offset:5120
	ds_read_b128 v[210:213], v176 offset:6144
	ds_read_b128 v[218:221], v176 offset:7168
	global_load_lds_dwordx4 v[170:171], off
	v_lshl_add_u64 v[170:171], s[46:47], 0, v[152:153]
	s_add_i32 m0, s33, 0xe000
	s_nop 0
	global_load_lds_dwordx4 v[170:171], off
	s_waitcnt vmcnt(8)
	s_waitcnt lgkmcnt(0)
	s_barrier
	s_setprio 1
	s_waitcnt lgkmcnt(0)
	v_mfma_f32_16x16x32_bf16 v[126:129], v[130:133], v[186:189], v[126:129]
	v_mfma_f32_16x16x32_bf16 v[122:125], v[138:141], v[186:189], v[122:125]
	v_mfma_f32_16x16x32_bf16 v[110:113], v[130:133], v[194:197], v[110:113]
	v_mfma_f32_16x16x32_bf16 v[106:109], v[138:141], v[194:197], v[106:109]
	v_mfma_f32_16x16x32_bf16 v[94:97], v[130:133], v[202:205], v[94:97]
	v_mfma_f32_16x16x32_bf16 v[90:93], v[138:141], v[202:205], v[90:93]
	v_mfma_f32_16x16x32_bf16 v[78:81], v[130:133], v[210:213], v[78:81]
	v_mfma_f32_16x16x32_bf16 v[74:77], v[138:141], v[210:213], v[74:77]
	v_mfma_f32_16x16x32_bf16 v[126:129], v[134:137], v[190:193], v[126:129]
	v_mfma_f32_16x16x32_bf16 v[122:125], v[158:161], v[190:193], v[122:125]
	v_mfma_f32_16x16x32_bf16 v[110:113], v[134:137], v[198:201], v[110:113]
	v_mfma_f32_16x16x32_bf16 v[106:109], v[158:161], v[198:201], v[106:109]
	v_mfma_f32_16x16x32_bf16 v[94:97], v[134:137], v[206:209], v[94:97]
	v_mfma_f32_16x16x32_bf16 v[90:93], v[158:161], v[206:209], v[90:93]
	v_mfma_f32_16x16x32_bf16 v[78:81], v[134:137], v[218:221], v[78:81]
	v_mfma_f32_16x16x32_bf16 v[74:77], v[158:161], v[218:221], v[74:77]
	s_setprio 0
	s_setprio 1
	v_mfma_f32_16x16x32_bf16 v[118:121], v[162:165], v[186:189], v[118:121]
	v_mfma_f32_16x16x32_bf16 v[114:117], v[178:181], v[186:189], v[114:117]
	v_mfma_f32_16x16x32_bf16 v[102:105], v[162:165], v[194:197], v[102:105]
	v_mfma_f32_16x16x32_bf16 v[98:101], v[178:181], v[194:197], v[98:101]
	v_mfma_f32_16x16x32_bf16 v[86:89], v[162:165], v[202:205], v[86:89]
	v_mfma_f32_16x16x32_bf16 v[82:85], v[178:181], v[202:205], v[82:85]
	v_mfma_f32_16x16x32_bf16 v[70:73], v[162:165], v[210:213], v[70:73]
	v_mfma_f32_16x16x32_bf16 v[66:69], v[178:181], v[210:213], v[66:69]
	v_mfma_f32_16x16x32_bf16 v[118:121], v[166:169], v[190:193], v[118:121]
	v_mfma_f32_16x16x32_bf16 v[114:117], v[182:185], v[190:193], v[114:117]
	v_mfma_f32_16x16x32_bf16 v[102:105], v[166:169], v[198:201], v[102:105]
	v_mfma_f32_16x16x32_bf16 v[98:101], v[182:185], v[198:201], v[98:101]
	v_mfma_f32_16x16x32_bf16 v[86:89], v[166:169], v[206:209], v[86:89]
	v_mfma_f32_16x16x32_bf16 v[82:85], v[182:185], v[206:209], v[82:85]
	v_mfma_f32_16x16x32_bf16 v[70:73], v[166:169], v[218:221], v[70:73]
	v_mfma_f32_16x16x32_bf16 v[66:69], v[182:185], v[218:221], v[66:69]
	s_setprio 0
	s_barrier
	s_add_i32 s62, s58, s31
	v_lshl_add_u64 v[170:171], s[34:35], 0, v[144:145]
	s_mov_b32 m0, s62
	ds_read_b128 v[186:189], v176 offset:16384
	ds_read_b128 v[190:193], v176 offset:17408
	ds_read_b128 v[194:197], v176 offset:18432
	ds_read_b128 v[198:201], v176 offset:19456
	ds_read_b128 v[202:205], v176 offset:20480
	ds_read_b128 v[206:209], v176 offset:21504
	ds_read_b128 v[210:213], v176 offset:22528
	ds_read_b128 v[218:221], v176 offset:23552
	global_load_lds_dwordx4 v[170:171], off
	s_add_i32 m0, s62, 0x2000
	s_add_u32 s62, s34, 0x80000
	v_lshl_add_u64 v[214:215], s[34:35], 0, v[148:149]
	s_addc_u32 s63, s35, 0
	s_add_i32 s66, s59, s31
	global_load_lds_dwordx4 v[214:215], off
	v_lshl_add_u64 v[222:223], s[62:63], 0, v[144:145]
	s_mov_b32 m0, s66
	v_lshl_add_u64 v[224:225], s[68:69], 0, v[146:147]
	global_load_lds_dwordx4 v[222:223], off
	v_lshl_add_u64 v[222:223], s[62:63], 0, v[148:149]
	s_add_i32 m0, s66, 0x2000
	s_nop 0
	global_load_lds_dwordx4 v[222:223], off
	v_lshl_add_u64 v[222:223], s[68:69], 0, v[142:143]
	s_mov_b32 m0, s33
	s_nop 0
	global_load_lds_dwordx4 v[222:223], off
	s_mov_b32 m0, s45
	s_nop 0
	global_load_lds_dwordx4 v[224:225], off
	s_waitcnt vmcnt(8)
	s_waitcnt lgkmcnt(0)
	s_barrier
	s_setprio 1
	s_waitcnt lgkmcnt(0)
	v_mfma_f32_16x16x32_bf16 v[62:65], v[130:133], v[186:189], v[62:65]
	v_mfma_f32_16x16x32_bf16 v[58:61], v[138:141], v[186:189], v[58:61]
	v_mfma_f32_16x16x32_bf16 v[50:53], v[130:133], v[194:197], v[50:53]
	v_mfma_f32_16x16x32_bf16 v[42:45], v[138:141], v[194:197], v[42:45]
	v_mfma_f32_16x16x32_bf16 v[38:41], v[130:133], v[202:205], v[38:41]
	v_mfma_f32_16x16x32_bf16 v[34:37], v[138:141], v[202:205], v[34:37]
	v_mfma_f32_16x16x32_bf16 v[14:17], v[130:133], v[210:213], v[14:17]
	v_mfma_f32_16x16x32_bf16 v[10:13], v[138:141], v[210:213], v[10:13]
	v_mfma_f32_16x16x32_bf16 v[62:65], v[134:137], v[190:193], v[62:65]
	v_mfma_f32_16x16x32_bf16 v[58:61], v[158:161], v[190:193], v[58:61]
	v_mfma_f32_16x16x32_bf16 v[50:53], v[134:137], v[198:201], v[50:53]
	v_mfma_f32_16x16x32_bf16 v[42:45], v[158:161], v[198:201], v[42:45]
	v_mfma_f32_16x16x32_bf16 v[38:41], v[134:137], v[206:209], v[38:41]
	v_mfma_f32_16x16x32_bf16 v[34:37], v[158:161], v[206:209], v[34:37]
	v_mfma_f32_16x16x32_bf16 v[14:17], v[134:137], v[218:221], v[14:17]
	v_mfma_f32_16x16x32_bf16 v[10:13], v[158:161], v[218:221], v[10:13]
	s_setprio 0
	s_setprio 1
	v_mfma_f32_16x16x32_bf16 v[54:57], v[162:165], v[186:189], v[54:57]
	v_mfma_f32_16x16x32_bf16 v[46:49], v[178:181], v[186:189], v[46:49]
	v_mfma_f32_16x16x32_bf16 v[30:33], v[162:165], v[194:197], v[30:33]
	v_mfma_f32_16x16x32_bf16 v[26:29], v[178:181], v[194:197], v[26:29]
	v_mfma_f32_16x16x32_bf16 v[22:25], v[162:165], v[202:205], v[22:25]
	v_mfma_f32_16x16x32_bf16 v[18:21], v[178:181], v[202:205], v[18:21]
	v_mfma_f32_16x16x32_bf16 v[6:9], v[162:165], v[210:213], v[6:9]
	v_mfma_f32_16x16x32_bf16 v[2:5], v[178:181], v[210:213], v[2:5]
	v_mfma_f32_16x16x32_bf16 v[54:57], v[166:169], v[190:193], v[54:57]
	v_mfma_f32_16x16x32_bf16 v[46:49], v[182:185], v[190:193], v[46:49]
	v_mfma_f32_16x16x32_bf16 v[30:33], v[166:169], v[198:201], v[30:33]
	v_mfma_f32_16x16x32_bf16 v[26:29], v[182:185], v[198:201], v[26:29]
	v_mfma_f32_16x16x32_bf16 v[22:25], v[166:169], v[206:209], v[22:25]
	v_mfma_f32_16x16x32_bf16 v[18:21], v[182:185], v[206:209], v[18:21]
	v_mfma_f32_16x16x32_bf16 v[6:9], v[166:169], v[218:221], v[6:9]
	v_mfma_f32_16x16x32_bf16 v[2:5], v[182:185], v[218:221], v[2:5]
	s_setprio 0
	s_barrier
	s_add_i32 s66, 0, 0x18000
	s_add_i32 s67, 0, 0x1c000
	v_add_u32_e32 v158, s66, v172
	v_add_u32_e32 v177, 0x19000, v172
	ds_read_b128 v[130:133], v158
	ds_read_b128 v[134:137], v158 offset:1024
	ds_read_b128 v[138:141], v158 offset:2048
	ds_read_b128 v[158:161], v158 offset:3072
	ds_read_b128 v[162:165], v177
	ds_read_b128 v[166:169], v177 offset:1024
	ds_read_b128 v[178:181], v177 offset:2048
	ds_read_b128 v[182:185], v177 offset:3072
	s_add_u32 s62, s68, 0x80000
	s_addc_u32 s63, s69, 0
	s_mov_b32 m0, s52
	v_lshl_add_u64 v[226:227], s[62:63], 0, v[142:143]
	ds_read_b128 v[186:189], v176 offset:32768
	ds_read_b128 v[190:193], v176 offset:33792
	ds_read_b128 v[194:197], v176 offset:34816
	ds_read_b128 v[198:201], v176 offset:35840
	ds_read_b128 v[202:205], v176 offset:36864
	ds_read_b128 v[206:209], v176 offset:37888
	ds_read_b128 v[210:213], v176 offset:38912
	ds_read_b128 v[218:221], v176 offset:39936
	global_load_lds_dwordx4 v[226:227], off
	v_lshl_add_u64 v[226:227], s[62:63], 0, v[146:147]
	s_mov_b32 m0, s53
	s_nop 0
	global_load_lds_dwordx4 v[226:227], off
	s_waitcnt vmcnt(8)
	s_waitcnt lgkmcnt(0)
	s_barrier
	s_setprio 1
	s_waitcnt lgkmcnt(0)
	v_mfma_f32_16x16x32_bf16 v[126:129], v[130:133], v[186:189], v[126:129]
	v_mfma_f32_16x16x32_bf16 v[122:125], v[138:141], v[186:189], v[122:125]
	v_mfma_f32_16x16x32_bf16 v[110:113], v[130:133], v[194:197], v[110:113]
	v_mfma_f32_16x16x32_bf16 v[106:109], v[138:141], v[194:197], v[106:109]
	v_mfma_f32_16x16x32_bf16 v[94:97], v[130:133], v[202:205], v[94:97]
	v_mfma_f32_16x16x32_bf16 v[90:93], v[138:141], v[202:205], v[90:93]
	v_mfma_f32_16x16x32_bf16 v[78:81], v[130:133], v[210:213], v[78:81]
	v_mfma_f32_16x16x32_bf16 v[74:77], v[138:141], v[210:213], v[74:77]
	v_mfma_f32_16x16x32_bf16 v[126:129], v[134:137], v[190:193], v[126:129]
	v_mfma_f32_16x16x32_bf16 v[122:125], v[158:161], v[190:193], v[122:125]
	v_mfma_f32_16x16x32_bf16 v[110:113], v[134:137], v[198:201], v[110:113]
	v_mfma_f32_16x16x32_bf16 v[106:109], v[158:161], v[198:201], v[106:109]
	v_mfma_f32_16x16x32_bf16 v[94:97], v[134:137], v[206:209], v[94:97]
	v_mfma_f32_16x16x32_bf16 v[90:93], v[158:161], v[206:209], v[90:93]
	v_mfma_f32_16x16x32_bf16 v[78:81], v[134:137], v[218:221], v[78:81]
	v_mfma_f32_16x16x32_bf16 v[74:77], v[158:161], v[218:221], v[74:77]
	s_setprio 0
	s_setprio 1
	v_mfma_f32_16x16x32_bf16 v[118:121], v[162:165], v[186:189], v[118:121]
	v_mfma_f32_16x16x32_bf16 v[114:117], v[178:181], v[186:189], v[114:117]
	v_mfma_f32_16x16x32_bf16 v[102:105], v[162:165], v[194:197], v[102:105]
	v_mfma_f32_16x16x32_bf16 v[98:101], v[178:181], v[194:197], v[98:101]
	v_mfma_f32_16x16x32_bf16 v[86:89], v[162:165], v[202:205], v[86:89]
	v_mfma_f32_16x16x32_bf16 v[82:85], v[178:181], v[202:205], v[82:85]
	v_mfma_f32_16x16x32_bf16 v[70:73], v[162:165], v[210:213], v[70:73]
	v_mfma_f32_16x16x32_bf16 v[66:69], v[178:181], v[210:213], v[66:69]
	v_mfma_f32_16x16x32_bf16 v[118:121], v[166:169], v[190:193], v[118:121]
	v_mfma_f32_16x16x32_bf16 v[114:117], v[182:185], v[190:193], v[114:117]
	v_mfma_f32_16x16x32_bf16 v[102:105], v[166:169], v[198:201], v[102:105]
	v_mfma_f32_16x16x32_bf16 v[98:101], v[182:185], v[198:201], v[98:101]
	v_mfma_f32_16x16x32_bf16 v[86:89], v[166:169], v[206:209], v[86:89]
	v_mfma_f32_16x16x32_bf16 v[82:85], v[182:185], v[206:209], v[82:85]
	v_mfma_f32_16x16x32_bf16 v[70:73], v[166:169], v[218:221], v[70:73]
	v_mfma_f32_16x16x32_bf16 v[66:69], v[182:185], v[218:221], v[66:69]
	s_setprio 0
	s_barrier
	s_add_i32 s62, s66, s31
	v_lshl_add_u64 v[170:171], v[170:171], 0, s[24:25]
	s_mov_b32 m0, s62
	ds_read_b128 v[186:189], v176 offset:49152
	ds_read_b128 v[190:193], v176 offset:50176
	ds_read_b128 v[194:197], v176 offset:51200
	ds_read_b128 v[198:201], v176 offset:52224
	ds_read_b128 v[202:205], v176 offset:53248
	ds_read_b128 v[206:209], v176 offset:54272
	ds_read_b128 v[210:213], v176 offset:55296
	ds_read_b128 v[218:221], v176 offset:56320
	global_load_lds_dwordx4 v[170:171], off
	s_add_i32 m0, s62, 0x2000
	s_add_u32 s34, s34, 0x80080
	v_lshl_add_u64 v[170:171], v[214:215], 0, s[24:25]
	s_addc_u32 s35, s35, 0
	s_add_i32 s62, s67, s31
	global_load_lds_dwordx4 v[170:171], off
	v_lshl_add_u64 v[170:171], s[34:35], 0, v[144:145]
	s_mov_b32 m0, s62
	s_nop 0
	global_load_lds_dwordx4 v[170:171], off
	v_lshl_add_u64 v[170:171], s[34:35], 0, v[148:149]
	s_add_i32 m0, s62, 0x2000
	s_nop 0
	global_load_lds_dwordx4 v[170:171], off
	v_lshl_add_u64 v[170:171], v[222:223], 0, s[24:25]
	s_mov_b32 m0, s55
	s_nop 0
	global_load_lds_dwordx4 v[170:171], off
	v_lshl_add_u64 v[170:171], v[224:225], 0, s[24:25]
	s_mov_b32 m0, s56
	s_nop 0
	global_load_lds_dwordx4 v[170:171], off
	s_waitcnt vmcnt(8)
	s_waitcnt lgkmcnt(0)
	s_barrier
	s_setprio 1
	s_waitcnt lgkmcnt(0)
	v_mfma_f32_16x16x32_bf16 v[62:65], v[130:133], v[186:189], v[62:65]
	v_mfma_f32_16x16x32_bf16 v[58:61], v[138:141], v[186:189], v[58:61]
	v_mfma_f32_16x16x32_bf16 v[50:53], v[130:133], v[194:197], v[50:53]
	v_mfma_f32_16x16x32_bf16 v[42:45], v[138:141], v[194:197], v[42:45]
	v_mfma_f32_16x16x32_bf16 v[38:41], v[130:133], v[202:205], v[38:41]
	v_mfma_f32_16x16x32_bf16 v[34:37], v[138:141], v[202:205], v[34:37]
	v_mfma_f32_16x16x32_bf16 v[14:17], v[130:133], v[210:213], v[14:17]
	v_mfma_f32_16x16x32_bf16 v[10:13], v[138:141], v[210:213], v[10:13]
	v_mfma_f32_16x16x32_bf16 v[62:65], v[134:137], v[190:193], v[62:65]
	v_mfma_f32_16x16x32_bf16 v[58:61], v[158:161], v[190:193], v[58:61]
	v_mfma_f32_16x16x32_bf16 v[50:53], v[134:137], v[198:201], v[50:53]
	v_mfma_f32_16x16x32_bf16 v[42:45], v[158:161], v[198:201], v[42:45]
	v_mfma_f32_16x16x32_bf16 v[38:41], v[134:137], v[206:209], v[38:41]
	v_mfma_f32_16x16x32_bf16 v[34:37], v[158:161], v[206:209], v[34:37]
	v_mfma_f32_16x16x32_bf16 v[14:17], v[134:137], v[218:221], v[14:17]
	v_mfma_f32_16x16x32_bf16 v[10:13], v[158:161], v[218:221], v[10:13]
	s_setprio 0
	s_setprio 1
	v_mfma_f32_16x16x32_bf16 v[54:57], v[162:165], v[186:189], v[54:57]
	v_mfma_f32_16x16x32_bf16 v[46:49], v[178:181], v[186:189], v[46:49]
	v_mfma_f32_16x16x32_bf16 v[30:33], v[162:165], v[194:197], v[30:33]
	v_mfma_f32_16x16x32_bf16 v[26:29], v[178:181], v[194:197], v[26:29]
	v_mfma_f32_16x16x32_bf16 v[22:25], v[162:165], v[202:205], v[22:25]
	v_mfma_f32_16x16x32_bf16 v[18:21], v[178:181], v[202:205], v[18:21]
	v_mfma_f32_16x16x32_bf16 v[6:9], v[162:165], v[210:213], v[6:9]
	v_mfma_f32_16x16x32_bf16 v[2:5], v[178:181], v[210:213], v[2:5]
	v_mfma_f32_16x16x32_bf16 v[54:57], v[166:169], v[190:193], v[54:57]
	v_mfma_f32_16x16x32_bf16 v[46:49], v[182:185], v[190:193], v[46:49]
	v_mfma_f32_16x16x32_bf16 v[30:33], v[166:169], v[198:201], v[30:33]
	v_mfma_f32_16x16x32_bf16 v[26:29], v[182:185], v[198:201], v[26:29]
	v_mfma_f32_16x16x32_bf16 v[22:25], v[166:169], v[206:209], v[22:25]
	v_mfma_f32_16x16x32_bf16 v[18:21], v[182:185], v[206:209], v[18:21]
	v_mfma_f32_16x16x32_bf16 v[6:9], v[166:169], v[218:221], v[6:9]
	v_mfma_f32_16x16x32_bf16 v[2:5], v[182:185], v[218:221], v[2:5]
	s_setprio 0
	s_barrier
	s_add_i32 s72, s72, 2
	s_add_u32 s46, s46, 0x100
	s_addc_u32 s47, s47, 0
	s_add_u32 s70, s70, 0x100
	s_addc_u32 s71, s71, 0
	s_cmp_gt_u32 s72, 29
	s_cbranch_scc0 .LBB0_2938
	s_and_b64 vcc, exec, s[26:27]
	s_cbranch_vccz .LBB0_2941
	s_barrier
.LBB0_2941:
	v_lshl_or_b32 v130, s61, 8, v173
	v_lshl_add_u32 v158, s44, 8, v1
	v_ashrrev_i32_e32 v131, 31, v130
	v_lshlrev_b64 v[160:161], 1, v[130:131]
	v_or_b32_e32 v130, 16, v158
	v_ashrrev_i32_e32 v159, 31, v158
	v_ashrrev_i32_e32 v131, 31, v130
	v_lshlrev_b64 v[132:133], 12, v[158:159]
	v_lshlrev_b64 v[130:131], 12, v[130:131]
	v_lshl_add_u64 v[132:133], s[64:65], 0, v[132:133]
	v_lshl_add_u64 v[130:131], s[64:65], 0, v[130:131]
	v_lshl_add_u64 v[170:171], v[132:133], 0, v[160:161]
	v_lshl_add_u64 v[168:169], v[130:131], 0, v[160:161]
	global_load_dwordx4 v[134:137], v[170:171], off
	global_load_dwordx4 v[138:141], v[170:171], off offset:64
	global_load_dwordx4 v[178:181], v[168:169], off
	global_load_dwordx4 v[182:185], v[168:169], off offset:64
	v_or_b32_e32 v130, 32, v158
	v_ashrrev_i32_e32 v131, 31, v130
	v_lshlrev_b64 v[130:131], 12, v[130:131]
	v_lshl_add_u64 v[130:131], s[64:65], 0, v[130:131]
	v_lshl_add_u64 v[162:163], v[130:131], 0, v[160:161]
	global_load_dwordx4 v[186:189], v[162:163], off
	global_load_dwordx4 v[190:193], v[162:163], off offset:64
	v_or_b32_e32 v130, 48, v158
	v_ashrrev_i32_e32 v131, 31, v130
	v_lshlrev_b64 v[130:131], 12, v[130:131]
	v_lshl_add_u64 v[130:131], s[64:65], 0, v[130:131]
	v_lshl_add_u64 v[166:167], v[130:131], 0, v[160:161]
	v_add_co_u32_e32 v164, vcc, s60, v170
	s_mov_b64 s[0:1], -1
	s_nop 0
	v_addc_co_u32_e32 v165, vcc, 0, v171, vcc
	global_load_dwordx4 v[194:197], v[166:167], off
	global_load_dwordx4 v[198:201], v[166:167], off offset:64
	global_load_dwordx4 v[130:133], v[164:165], off
	s_andn2_b64 vcc, exec, s[2:3]
	s_waitcnt vmcnt(0)
	v_cvt_f32_f16_e32 v202, v134
	v_cvt_f32_f16_e32 v210, v178
	v_cvt_f32_f16_sdwa v211, v178 dst_sel:DWORD dst_unused:UNUSED_PAD src0_sel:WORD_1
	v_cvt_f32_f16_e32 v212, v180
	v_cvt_f32_f16_sdwa v213, v180 dst_sel:DWORD dst_unused:UNUSED_PAD src0_sel:WORD_1
	v_cvt_f32_f16_e32 v180, v181
	v_cvt_f32_f16_sdwa v181, v181 dst_sel:DWORD dst_unused:UNUSED_PAD src0_sel:WORD_1
	v_cvt_f32_f16_e32 v218, v184
	v_cvt_f32_f16_sdwa v219, v184 dst_sel:DWORD dst_unused:UNUSED_PAD src0_sel:WORD_1
	v_cvt_f32_f16_e32 v214, v182
	v_cvt_f32_f16_sdwa v215, v182 dst_sel:DWORD dst_unused:UNUSED_PAD src0_sel:WORD_1
	v_cvt_f32_f16_sdwa v203, v134 dst_sel:DWORD dst_unused:UNUSED_PAD src0_sel:WORD_1
	v_cvt_f32_f16_e32 v134, v135
	v_cvt_f32_f16_sdwa v135, v135 dst_sel:DWORD dst_unused:UNUSED_PAD src0_sel:WORD_1
	v_cvt_f32_f16_e32 v204, v136
	v_cvt_f32_f16_sdwa v205, v136 dst_sel:DWORD dst_unused:UNUSED_PAD src0_sel:WORD_1
	v_cvt_f32_f16_e32 v136, v137
	v_cvt_f32_f16_sdwa v137, v137 dst_sel:DWORD dst_unused:UNUSED_PAD src0_sel:WORD_1
	v_cvt_f32_f16_e32 v206, v138
	v_cvt_f32_f16_sdwa v207, v138 dst_sel:DWORD dst_unused:UNUSED_PAD src0_sel:WORD_1
	v_cvt_f32_f16_e32 v138, v139
	v_cvt_f32_f16_sdwa v139, v139 dst_sel:DWORD dst_unused:UNUSED_PAD src0_sel:WORD_1
	v_cvt_f32_f16_e32 v208, v140
	v_cvt_f32_f16_sdwa v209, v140 dst_sel:DWORD dst_unused:UNUSED_PAD src0_sel:WORD_1
	v_cvt_f32_f16_e32 v140, v141
	v_cvt_f32_f16_sdwa v141, v141 dst_sel:DWORD dst_unused:UNUSED_PAD src0_sel:WORD_1
	v_cvt_f32_f16_e32 v178, v179
	v_cvt_f32_f16_sdwa v179, v179 dst_sel:DWORD dst_unused:UNUSED_PAD src0_sel:WORD_1
	v_pk_add_f32 v[110:111], v[110:111], v[210:211]
	v_pk_add_f32 v[108:109], v[108:109], v[180:181]
	v_pk_add_f32 v[106:107], v[106:107], v[212:213]
	v_pk_add_f32 v[98:99], v[98:99], v[218:219]
	v_cvt_pk_f16_f32 v109, v108, v109
	v_cvt_pk_f16_f32 v108, v106, v107
	v_cvt_pk_f16_f32 v106, v110, v111
	v_pk_add_f32 v[110:111], v[102:103], v[214:215]
	v_cvt_pk_f16_f32 v102, v98, v99
	v_add_u32_e32 v98, 0x90, v158
	v_cvt_f32_f16_e32 v182, v183
	v_cvt_f32_f16_sdwa v183, v183 dst_sel:DWORD dst_unused:UNUSED_PAD src0_sel:WORD_1
	v_ashrrev_i32_e32 v99, 31, v98
	v_pk_add_f32 v[128:129], v[128:129], v[134:135]
	v_pk_add_f32 v[126:127], v[126:127], v[202:203]
	v_pk_add_f32 v[124:125], v[124:125], v[136:137]
	v_pk_add_f32 v[122:123], v[122:123], v[204:205]
	v_lshlrev_b64 v[98:99], 12, v[98:99]
	v_pk_add_f32 v[134:135], v[120:121], v[138:139]
	v_pk_add_f32 v[136:137], v[118:119], v[206:207]
	v_pk_add_f32 v[118:119], v[116:117], v[140:141]
	v_pk_add_f32 v[138:139], v[114:115], v[208:209]
	v_cvt_pk_f16_f32 v117, v124, v125
	v_cvt_pk_f16_f32 v116, v122, v123
	v_cvt_pk_f16_f32 v115, v128, v129
	v_cvt_pk_f16_f32 v114, v126, v127
	v_pk_add_f32 v[112:113], v[112:113], v[178:179]
	v_lshl_add_u64 v[98:99], s[64:65], 0, v[98:99]
	v_cvt_pk_f16_f32 v121, v118, v119
	v_cvt_pk_f16_f32 v120, v138, v139
	v_cvt_pk_f16_f32 v119, v134, v135
	v_cvt_pk_f16_f32 v118, v136, v137
	global_store_dwordx4 v[170:171], v[114:117], off
	global_store_dwordx4 v[170:171], v[118:121], off offset:64
	v_cvt_pk_f16_f32 v107, v112, v113
	v_lshl_add_u64 v[98:99], v[98:99], 0, v[160:161]
	global_store_dwordx4 v[168:169], v[106:109], off
	v_cvt_f32_f16_e32 v184, v185
	v_cvt_f32_f16_sdwa v185, v185 dst_sel:DWORD dst_unused:UNUSED_PAD src0_sel:WORD_1
	v_pk_add_f32 v[108:109], v[104:105], v[182:183]
	global_load_dwordx4 v[104:107], v[98:99], off
	v_cvt_f32_f16_e32 v126, v192
	v_cvt_f32_f16_sdwa v127, v192 dst_sel:DWORD dst_unused:UNUSED_PAD src0_sel:WORD_1
	v_cvt_f32_f16_e32 v128, v193
	v_cvt_f32_f16_sdwa v129, v193 dst_sel:DWORD dst_unused:UNUSED_PAD src0_sel:WORD_1
	v_cvt_f32_f16_e32 v220, v186
	v_cvt_f32_f16_sdwa v221, v186 dst_sel:DWORD dst_unused:UNUSED_PAD src0_sel:WORD_1
	v_cvt_f32_f16_e32 v186, v187
	v_cvt_f32_f16_sdwa v187, v187 dst_sel:DWORD dst_unused:UNUSED_PAD src0_sel:WORD_1
	v_cvt_f32_f16_e32 v222, v188
	v_cvt_f32_f16_sdwa v223, v188 dst_sel:DWORD dst_unused:UNUSED_PAD src0_sel:WORD_1
	v_cvt_f32_f16_e32 v120, v189
	v_cvt_f32_f16_sdwa v121, v189 dst_sel:DWORD dst_unused:UNUSED_PAD src0_sel:WORD_1
	v_lshl_add_u64 v[114:115], v[170:171], 0, s[6:7]
	v_pk_add_f32 v[100:101], v[100:101], v[184:185]
	v_cvt_f32_f16_e32 v122, v190
	v_cvt_f32_f16_sdwa v123, v190 dst_sel:DWORD dst_unused:UNUSED_PAD src0_sel:WORD_1
	v_cvt_f32_f16_e32 v124, v191
	global_load_dwordx4 v[116:119], v[114:115], off offset:64
	v_cvt_f32_f16_sdwa v125, v191 dst_sel:DWORD dst_unused:UNUSED_PAD src0_sel:WORD_1
	v_cvt_pk_f16_f32 v103, v100, v101
	v_cvt_pk_f16_f32 v101, v108, v109
	v_cvt_pk_f16_f32 v100, v110, v111
	v_pk_add_f32 v[84:85], v[84:85], v[128:129]
	v_pk_add_f32 v[82:83], v[82:83], v[126:127]
	global_store_dwordx4 v[168:169], v[100:103], off offset:64
	v_cvt_f32_f16_e32 v136, v198
	v_cvt_f32_f16_sdwa v137, v198 dst_sel:DWORD dst_unused:UNUSED_PAD src0_sel:WORD_1
	v_cvt_f32_f16_e32 v138, v199
	v_cvt_f32_f16_sdwa v139, v199 dst_sel:DWORD dst_unused:UNUSED_PAD src0_sel:WORD_1
	v_cvt_f32_f16_e32 v140, v200
	v_cvt_f32_f16_sdwa v141, v200 dst_sel:DWORD dst_unused:UNUSED_PAD src0_sel:WORD_1
	v_cvt_f32_f16_e32 v168, v201
	v_cvt_f32_f16_sdwa v169, v201 dst_sel:DWORD dst_unused:UNUSED_PAD src0_sel:WORD_1
	v_cvt_pk_f16_f32 v85, v84, v85
	v_cvt_pk_f16_f32 v84, v82, v83
	v_add_u32_e32 v82, 0xa0, v158
	v_pk_add_f32 v[96:97], v[96:97], v[186:187]
	v_pk_add_f32 v[94:95], v[94:95], v[220:221]
	v_pk_add_f32 v[92:93], v[92:93], v[120:121]
	v_pk_add_f32 v[90:91], v[90:91], v[222:223]
	v_ashrrev_i32_e32 v83, 31, v82
	v_cvt_pk_f16_f32 v93, v92, v93
	v_cvt_pk_f16_f32 v92, v90, v91
	v_cvt_pk_f16_f32 v91, v96, v97
	v_cvt_pk_f16_f32 v90, v94, v95
	v_lshlrev_b64 v[82:83], 12, v[82:83]
	global_load_dwordx4 v[100:103], v[98:99], off offset:64
	v_lshl_add_u64 v[82:83], s[64:65], 0, v[82:83]
	global_store_dwordx4 v[162:163], v[90:93], off
	v_cvt_f32_f16_e32 v108, v194
	v_cvt_f32_f16_sdwa v109, v194 dst_sel:DWORD dst_unused:UNUSED_PAD src0_sel:WORD_1
	v_pk_add_f32 v[90:91], v[88:89], v[124:125]
	v_pk_add_f32 v[92:93], v[86:87], v[122:123]
	v_cvt_f32_f16_e32 v110, v195
	v_cvt_f32_f16_sdwa v111, v195 dst_sel:DWORD dst_unused:UNUSED_PAD src0_sel:WORD_1
	v_cvt_f32_f16_e32 v112, v196
	v_cvt_f32_f16_sdwa v113, v196 dst_sel:DWORD dst_unused:UNUSED_PAD src0_sel:WORD_1
	v_cvt_f32_f16_e32 v134, v197
	v_cvt_f32_f16_sdwa v135, v197 dst_sel:DWORD dst_unused:UNUSED_PAD src0_sel:WORD_1
	v_lshl_add_u64 v[94:95], v[82:83], 0, v[160:161]
	v_cvt_pk_f16_f32 v83, v90, v91
	v_cvt_pk_f16_f32 v82, v92, v93
	v_pk_add_f32 v[72:73], v[72:73], v[138:139]
	v_pk_add_f32 v[70:71], v[70:71], v[136:137]
	v_pk_add_f32 v[68:69], v[68:69], v[168:169]
	v_pk_add_f32 v[66:67], v[66:67], v[140:141]
	global_load_dwordx4 v[86:89], v[94:95], off
	v_cvt_pk_f16_f32 v69, v68, v69
	global_store_dwordx4 v[162:163], v[82:85], off offset:64
	global_load_dwordx4 v[82:85], v[94:95], off offset:64
	v_cvt_pk_f16_f32 v68, v66, v67
	v_cvt_pk_f16_f32 v67, v72, v73
	v_cvt_pk_f16_f32 v66, v70, v71
	global_store_dwordx4 v[166:167], v[66:69], off offset:64
	v_pk_add_f32 v[80:81], v[80:81], v[110:111]
	v_pk_add_f32 v[78:79], v[78:79], v[108:109]
	v_add_u32_e32 v66, 0xb0, v158
	v_ashrrev_i32_e32 v67, 31, v66
	v_pk_add_f32 v[76:77], v[76:77], v[134:135]
	v_pk_add_f32 v[74:75], v[74:75], v[112:113]
	v_lshlrev_b64 v[66:67], 12, v[66:67]
	v_cvt_pk_f16_f32 v77, v76, v77
	v_cvt_pk_f16_f32 v76, v74, v75
	v_cvt_pk_f16_f32 v75, v80, v81
	v_cvt_pk_f16_f32 v74, v78, v79
	v_lshl_add_u64 v[66:67], s[64:65], 0, v[66:67]
	global_store_dwordx4 v[166:167], v[74:77], off
	v_cvt_f32_f16_e32 v90, v130
	v_cvt_f32_f16_sdwa v91, v130 dst_sel:DWORD dst_unused:UNUSED_PAD src0_sel:WORD_1
	s_waitcnt vmcnt(9)
	v_cvt_f32_f16_e32 v74, v104
	v_cvt_f32_f16_sdwa v75, v104 dst_sel:DWORD dst_unused:UNUSED_PAD src0_sel:WORD_1
	v_cvt_f32_f16_e32 v76, v105
	v_cvt_f32_f16_sdwa v77, v105 dst_sel:DWORD dst_unused:UNUSED_PAD src0_sel:WORD_1
	v_lshl_add_u64 v[104:105], v[66:67], 0, v[160:161]
	global_load_dwordx4 v[66:69], v[104:105], off
	global_load_dwordx4 v[70:73], v[104:105], off offset:64
	v_cvt_f32_f16_e32 v92, v131
	v_cvt_f32_f16_sdwa v93, v131 dst_sel:DWORD dst_unused:UNUSED_PAD src0_sel:WORD_1
	v_cvt_f32_f16_e32 v96, v132
	v_cvt_f32_f16_sdwa v97, v132 dst_sel:DWORD dst_unused:UNUSED_PAD src0_sel:WORD_1
	v_cvt_f32_f16_e32 v120, v133
	v_cvt_f32_f16_sdwa v121, v133 dst_sel:DWORD dst_unused:UNUSED_PAD src0_sel:WORD_1
	s_waitcnt vmcnt(10)
	v_cvt_f32_f16_e32 v122, v116
	v_cvt_f32_f16_sdwa v123, v116 dst_sel:DWORD dst_unused:UNUSED_PAD src0_sel:WORD_1
	v_cvt_f32_f16_e32 v116, v117
	v_cvt_f32_f16_sdwa v117, v117 dst_sel:DWORD dst_unused:UNUSED_PAD src0_sel:WORD_1
	v_cvt_f32_f16_e32 v124, v118
	v_cvt_f32_f16_sdwa v125, v118 dst_sel:DWORD dst_unused:UNUSED_PAD src0_sel:WORD_1
	v_cvt_f32_f16_e32 v118, v119
	v_cvt_f32_f16_sdwa v119, v119 dst_sel:DWORD dst_unused:UNUSED_PAD src0_sel:WORD_1
	v_cvt_f32_f16_e32 v78, v106
	v_cvt_f32_f16_sdwa v79, v106 dst_sel:DWORD dst_unused:UNUSED_PAD src0_sel:WORD_1
	v_cvt_f32_f16_e32 v80, v107
	v_cvt_f32_f16_sdwa v81, v107 dst_sel:DWORD dst_unused:UNUSED_PAD src0_sel:WORD_1
	v_pk_add_f32 v[64:65], v[64:65], v[92:93]
	v_pk_add_f32 v[62:63], v[62:63], v[90:91]
	v_pk_add_f32 v[60:61], v[60:61], v[120:121]
	v_pk_add_f32 v[58:59], v[58:59], v[96:97]
	v_pk_add_f32 v[56:57], v[56:57], v[116:117]
	v_pk_add_f32 v[54:55], v[54:55], v[122:123]
	v_pk_add_f32 v[48:49], v[48:49], v[118:119]
	v_pk_add_f32 v[46:47], v[46:47], v[124:125]
	v_cvt_pk_f16_f32 v61, v60, v61
	v_cvt_pk_f16_f32 v60, v58, v59
	v_cvt_pk_f16_f32 v59, v64, v65
	v_cvt_pk_f16_f32 v58, v62, v63
	v_cvt_pk_f16_f32 v49, v48, v49
	s_waitcnt vmcnt(8)
	v_cvt_f32_f16_e32 v106, v100
	v_cvt_f32_f16_sdwa v107, v100 dst_sel:DWORD dst_unused:UNUSED_PAD src0_sel:WORD_1
	v_cvt_f32_f16_e32 v100, v101
	v_cvt_f32_f16_sdwa v101, v101 dst_sel:DWORD dst_unused:UNUSED_PAD src0_sel:WORD_1
	v_cvt_f32_f16_e32 v108, v102
	v_cvt_f32_f16_sdwa v109, v102 dst_sel:DWORD dst_unused:UNUSED_PAD src0_sel:WORD_1
	v_cvt_f32_f16_e32 v102, v103
	v_cvt_f32_f16_sdwa v103, v103 dst_sel:DWORD dst_unused:UNUSED_PAD src0_sel:WORD_1
	v_cvt_pk_f16_f32 v48, v46, v47
	v_cvt_pk_f16_f32 v47, v56, v57
	v_cvt_pk_f16_f32 v46, v54, v55
	global_store_dwordx4 v[164:165], v[58:61], off
	global_store_dwordx4 v[114:115], v[46:49], off offset:64
	v_pk_add_f32 v[32:33], v[32:33], v[100:101]
	v_pk_add_f32 v[30:31], v[30:31], v[106:107]
	v_pk_add_f32 v[28:29], v[28:29], v[102:103]
	v_pk_add_f32 v[26:27], v[26:27], v[108:109]
	v_cvt_pk_f16_f32 v29, v28, v29
	v_cvt_pk_f16_f32 v28, v26, v27
	v_cvt_pk_f16_f32 v27, v32, v33
	s_waitcnt vmcnt(8)
	v_cvt_f32_f16_e32 v46, v86
	v_cvt_f32_f16_sdwa v47, v86 dst_sel:DWORD dst_unused:UNUSED_PAD src0_sel:WORD_1
	v_cvt_f32_f16_e32 v48, v87
	v_cvt_f32_f16_sdwa v49, v87 dst_sel:DWORD dst_unused:UNUSED_PAD src0_sel:WORD_1
	v_cvt_f32_f16_e32 v54, v88
	v_cvt_f32_f16_sdwa v55, v88 dst_sel:DWORD dst_unused:UNUSED_PAD src0_sel:WORD_1
	v_cvt_f32_f16_e32 v56, v89
	v_cvt_f32_f16_sdwa v57, v89 dst_sel:DWORD dst_unused:UNUSED_PAD src0_sel:WORD_1
	s_waitcnt vmcnt(6)
	v_cvt_f32_f16_e32 v58, v82
	v_cvt_f32_f16_sdwa v59, v82 dst_sel:DWORD dst_unused:UNUSED_PAD src0_sel:WORD_1
	v_cvt_f32_f16_e32 v60, v83
	v_cvt_f32_f16_sdwa v61, v83 dst_sel:DWORD dst_unused:UNUSED_PAD src0_sel:WORD_1
	v_cvt_f32_f16_e32 v62, v84
	v_cvt_f32_f16_sdwa v63, v84 dst_sel:DWORD dst_unused:UNUSED_PAD src0_sel:WORD_1
	v_cvt_f32_f16_e32 v64, v85
	v_cvt_f32_f16_sdwa v65, v85 dst_sel:DWORD dst_unused:UNUSED_PAD src0_sel:WORD_1
	v_cvt_pk_f16_f32 v26, v30, v31
	global_store_dwordx4 v[98:99], v[26:29], off offset:64
	v_pk_add_f32 v[30:31], v[38:39], v[46:47]
	v_pk_add_f32 v[32:33], v[34:35], v[54:55]
	v_pk_add_f32 v[26:27], v[40:41], v[48:49]
	v_pk_add_f32 v[28:29], v[36:37], v[56:57]
	v_pk_add_f32 v[24:25], v[24:25], v[60:61]
	v_pk_add_f32 v[22:23], v[22:23], v[58:59]
	v_pk_add_f32 v[20:21], v[20:21], v[64:65]
	v_pk_add_f32 v[18:19], v[18:19], v[62:63]
	v_cvt_pk_f16_f32 v29, v28, v29
	v_cvt_pk_f16_f32 v28, v32, v33
	v_cvt_pk_f16_f32 v27, v26, v27
	v_cvt_pk_f16_f32 v26, v30, v31
	v_cvt_pk_f16_f32 v21, v20, v21
	v_cvt_pk_f16_f32 v20, v18, v19
	v_cvt_pk_f16_f32 v19, v24, v25
	v_cvt_pk_f16_f32 v18, v22, v23
	global_store_dwordx4 v[94:95], v[26:29], off
	global_store_dwordx4 v[94:95], v[18:21], off offset:64
	s_waitcnt vmcnt(5)
	v_cvt_f32_f16_e32 v22, v70
	v_cvt_f32_f16_sdwa v23, v70 dst_sel:DWORD dst_unused:UNUSED_PAD src0_sel:WORD_1
	v_cvt_f32_f16_e32 v18, v72
	v_cvt_f32_f16_sdwa v19, v72 dst_sel:DWORD dst_unused:UNUSED_PAD src0_sel:WORD_1
	v_cvt_f32_f16_e32 v20, v73
	v_cvt_f32_f16_sdwa v21, v73 dst_sel:DWORD dst_unused:UNUSED_PAD src0_sel:WORD_1
	v_cvt_f32_f16_e32 v24, v71
	v_cvt_f32_f16_sdwa v25, v71 dst_sel:DWORD dst_unused:UNUSED_PAD src0_sel:WORD_1
	v_cvt_f32_f16_e32 v26, v68
	v_cvt_f32_f16_e32 v28, v69
	v_cvt_f32_f16_e32 v30, v66
	v_cvt_f32_f16_e32 v32, v67
	v_cvt_f32_f16_sdwa v33, v67 dst_sel:DWORD dst_unused:UNUSED_PAD src0_sel:WORD_1
	v_cvt_f32_f16_sdwa v31, v66 dst_sel:DWORD dst_unused:UNUSED_PAD src0_sel:WORD_1
	v_cvt_f32_f16_sdwa v29, v69 dst_sel:DWORD dst_unused:UNUSED_PAD src0_sel:WORD_1
	v_cvt_f32_f16_sdwa v27, v68 dst_sel:DWORD dst_unused:UNUSED_PAD src0_sel:WORD_1
	v_pk_add_f32 v[52:53], v[52:53], v[76:77]
	v_pk_add_f32 v[50:51], v[50:51], v[74:75]
	v_pk_add_f32 v[44:45], v[44:45], v[80:81]
	v_pk_add_f32 v[42:43], v[42:43], v[78:79]
	v_pk_add_f32 v[16:17], v[16:17], v[32:33]
	v_pk_add_f32 v[14:15], v[14:15], v[30:31]
	v_pk_add_f32 v[12:13], v[12:13], v[28:29]
	v_pk_add_f32 v[10:11], v[10:11], v[26:27]
	v_pk_add_f32 v[8:9], v[8:9], v[24:25]
	v_pk_add_f32 v[6:7], v[6:7], v[22:23]
	v_pk_add_f32 v[4:5], v[4:5], v[20:21]
	v_pk_add_f32 v[2:3], v[2:3], v[18:19]
	v_cvt_pk_f16_f32 v45, v44, v45
	v_cvt_pk_f16_f32 v44, v42, v43
	v_cvt_pk_f16_f32 v43, v52, v53
	v_cvt_pk_f16_f32 v42, v50, v51
	v_cvt_pk_f16_f32 v13, v12, v13
	v_cvt_pk_f16_f32 v12, v10, v11
	v_cvt_pk_f16_f32 v11, v16, v17
	v_cvt_pk_f16_f32 v10, v14, v15
	v_cvt_pk_f16_f32 v5, v4, v5
	v_cvt_pk_f16_f32 v4, v2, v3
	v_cvt_pk_f16_f32 v3, v8, v9
	v_cvt_pk_f16_f32 v2, v6, v7
	global_store_dwordx4 v[98:99], v[42:45], off
	global_store_dwordx4 v[104:105], v[10:13], off
	global_store_dwordx4 v[104:105], v[2:5], off offset:64
	s_cbranch_vccnz .LBB0_2930
	s_andn2_b64 vcc, exec, s[8:9]
	s_cbranch_vccnz .LBB0_2929
	s_barrier
	s_branch .LBB0_2929

.LBB0_3166:
	s_lshl_b32 s1, s1, 5
	s_mov_b64 s[24:25], 0x80
	s_and_b32 s1, s1, 0x60
	s_add_i32 m0, s33, 0x18000
	v_lshl_add_u64 v[8:9], v[8:9], 0, s[24:25]
	s_lshl_b32 s26, s0, 13
	s_lshl_b32 s27, s1, 7
	s_waitcnt vmcnt(2)
	s_barrier
	global_load_lds_dwordx4 v[8:9], off
	v_lshl_add_u64 v[6:7], v[6:7], 0, s[24:25]
	s_add_i32 m0, s33, 0x1a000
	s_add_i32 s48, s33, 0x8000
	s_add_i32 s49, s33, 0xa000
	global_load_lds_dwordx4 v[6:7], off
	v_lshl_add_u64 v[2:3], v[2:3], 0, s[24:25]
	s_mov_b32 m0, s48
	s_add_u32 s4, s42, 0x160080
	global_load_lds_dwordx4 v[2:3], off
	v_lshl_add_u64 v[2:3], v[4:5], 0, s[24:25]
	s_mov_b32 m0, s49
	s_addc_u32 s5, s43, 0
	global_load_lds_dwordx4 v[2:3], off
	s_add_i32 m0, s33, 0x1c000
	v_lshl_add_u64 v[2:3], s[4:5], 0, v[144:145]
	global_load_lds_dwordx4 v[2:3], off
	v_lshl_add_u64 v[2:3], s[4:5], 0, v[148:149]
	s_add_i32 m0, s33, 0x1e000
	v_lshlrev_b32_e32 v4, 2, v0
	global_load_lds_dwordx4 v[2:3], off
	v_and_b32_e32 v2, 15, v0
	v_lshl_or_b32 v1, s0, 6, v2
	v_lshlrev_b32_e32 v3, 1, v12
	v_lshlrev_b32_e32 v5, 6, v0
	s_movk_i32 s0, 0x3c0
	v_lshl_or_b32 v2, v2, 6, v3
	v_and_b32_e32 v4, 32, v4
	v_and_or_b32 v3, v5, s0, v3
	v_bitop3_b32 v172, s27, v3, v4 bitop3:0xf6
	v_add_u32_e32 v172, s27, v172
	s_waitcnt vmcnt(6)
	s_cmpk_lt_u32 s2, 0x100
	v_add_u16_e32 v3, v10, v11
	v_bitop3_b32 v2, v2, s26, v4 bitop3:0xde
	s_cselect_b64 s[26:27], -1, 0
	v_lshrrev_b16_e32 v3, 1, v3
	s_add_i32 s53, 0, 0x10000
	s_add_i32 s54, 0, 0x14000
	s_sext_i32_i8 s59, s3
	s_ashr_i32 s52, s11, 31
	v_lshl_or_b32 v173, s1, 1, v12
	v_add_lshl_u32 v150, v13, v3, 1
	v_mov_b32_e32 v151, v145
	v_add_lshl_u32 v152, v14, v3, 1
	v_mov_b32_e32 v153, v145
	v_mov_b64_e32 v[154:155], 0x100
	v_mov_b64_e32 v[156:157], 0xff
	v_add_u32_e32 v174, s53, v172
	v_add_u32_e32 v175, 0x11000, v172
	v_add_u32_e32 v176, 0, v2
	s_mov_b64 s[36:37], 0x80000
	s_mov_b32 s55, 0x80000
	s_barrier
	s_branch .LBB0_3169

.LBB0_3180:
	ds_read_b128 v[130:133], v174
	ds_read_b128 v[134:137], v174 offset:1024
	ds_read_b128 v[138:141], v174 offset:2048
	ds_read_b128 v[158:161], v174 offset:3072
	ds_read_b128 v[162:165], v175
	ds_read_b128 v[166:169], v175 offset:1024
	ds_read_b128 v[178:181], v175 offset:2048
	ds_read_b128 v[182:185], v175 offset:3072
	s_add_u32 s34, s40, 0xffea0080
	s_addc_u32 s35, s41, -1
	s_cmpk_eq_i32 s60, 0x54
	s_cselect_b32 s43, s5, s35
	s_cselect_b32 s42, s4, s34
	s_cselect_b32 s35, s39, s1
	s_cselect_b32 s34, s38, s0
	v_lshl_add_u64 v[170:171], s[40:41], 0, v[150:151]
	s_add_i32 m0, s33, 0xc000
	ds_read_b128 v[186:189], v176
	ds_read_b128 v[190:193], v176 offset:1024
	ds_read_b128 v[194:197], v176 offset:2048
	ds_read_b128 v[198:201], v176 offset:3072
	ds_read_b128 v[202:205], v176 offset:4096
	ds_read_b128 v[206:209], v176 offset:5120
	ds_read_b128 v[210:213], v176 offset:6144
	ds_read_b128 v[218:221], v176 offset:7168
	global_load_lds_dwordx4 v[170:171], off
	v_lshl_add_u64 v[170:171], s[40:41], 0, v[152:153]
	s_add_i32 m0, s33, 0xe000
	s_nop 0
	global_load_lds_dwordx4 v[170:171], off
	s_waitcnt vmcnt(8)
	s_waitcnt lgkmcnt(0)
	s_barrier
	s_setprio 1
	s_waitcnt lgkmcnt(0)
	v_mfma_f32_16x16x32_bf16 v[126:129], v[130:133], v[186:189], v[126:129]
	v_mfma_f32_16x16x32_bf16 v[122:125], v[138:141], v[186:189], v[122:125]
	v_mfma_f32_16x16x32_bf16 v[110:113], v[130:133], v[194:197], v[110:113]
	v_mfma_f32_16x16x32_bf16 v[106:109], v[138:141], v[194:197], v[106:109]
	v_mfma_f32_16x16x32_bf16 v[94:97], v[130:133], v[202:205], v[94:97]
	v_mfma_f32_16x16x32_bf16 v[90:93], v[138:141], v[202:205], v[90:93]
	v_mfma_f32_16x16x32_bf16 v[78:81], v[130:133], v[210:213], v[78:81]
	v_mfma_f32_16x16x32_bf16 v[74:77], v[138:141], v[210:213], v[74:77]
	v_mfma_f32_16x16x32_bf16 v[126:129], v[134:137], v[190:193], v[126:129]
	v_mfma_f32_16x16x32_bf16 v[122:125], v[158:161], v[190:193], v[122:125]
	v_mfma_f32_16x16x32_bf16 v[110:113], v[134:137], v[198:201], v[110:113]
	v_mfma_f32_16x16x32_bf16 v[106:109], v[158:161], v[198:201], v[106:109]
	v_mfma_f32_16x16x32_bf16 v[94:97], v[134:137], v[206:209], v[94:97]
	v_mfma_f32_16x16x32_bf16 v[90:93], v[158:161], v[206:209], v[90:93]
	v_mfma_f32_16x16x32_bf16 v[78:81], v[134:137], v[218:221], v[78:81]
	v_mfma_f32_16x16x32_bf16 v[74:77], v[158:161], v[218:221], v[74:77]
	s_setprio 0
	s_setprio 1
	v_mfma_f32_16x16x32_bf16 v[118:121], v[162:165], v[186:189], v[118:121]
	v_mfma_f32_16x16x32_bf16 v[114:117], v[178:181], v[186:189], v[114:117]
	v_mfma_f32_16x16x32_bf16 v[102:105], v[162:165], v[194:197], v[102:105]
	v_mfma_f32_16x16x32_bf16 v[98:101], v[178:181], v[194:197], v[98:101]
	v_mfma_f32_16x16x32_bf16 v[86:89], v[162:165], v[202:205], v[86:89]
	v_mfma_f32_16x16x32_bf16 v[82:85], v[178:181], v[202:205], v[82:85]
	v_mfma_f32_16x16x32_bf16 v[70:73], v[162:165], v[210:213], v[70:73]
	v_mfma_f32_16x16x32_bf16 v[66:69], v[178:181], v[210:213], v[66:69]
	v_mfma_f32_16x16x32_bf16 v[118:121], v[166:169], v[190:193], v[118:121]
	v_mfma_f32_16x16x32_bf16 v[114:117], v[182:185], v[190:193], v[114:117]
	v_mfma_f32_16x16x32_bf16 v[102:105], v[166:169], v[198:201], v[102:105]
	v_mfma_f32_16x16x32_bf16 v[98:101], v[182:185], v[198:201], v[98:101]
	v_mfma_f32_16x16x32_bf16 v[86:89], v[166:169], v[206:209], v[86:89]
	v_mfma_f32_16x16x32_bf16 v[82:85], v[182:185], v[206:209], v[82:85]
	v_mfma_f32_16x16x32_bf16 v[70:73], v[166:169], v[218:221], v[70:73]
	v_mfma_f32_16x16x32_bf16 v[66:69], v[182:185], v[218:221], v[66:69]
	s_setprio 0
	s_barrier
	s_add_i32 s61, s53, s31
	v_lshl_add_u64 v[170:171], s[34:35], 0, v[144:145]
	s_mov_b32 m0, s61
	ds_read_b128 v[186:189], v176 offset:16384
	ds_read_b128 v[190:193], v176 offset:17408
	ds_read_b128 v[194:197], v176 offset:18432
	ds_read_b128 v[198:201], v176 offset:19456
	ds_read_b128 v[202:205], v176 offset:20480
	ds_read_b128 v[206:209], v176 offset:21504
	ds_read_b128 v[210:213], v176 offset:22528
	ds_read_b128 v[218:221], v176 offset:23552
	global_load_lds_dwordx4 v[170:171], off
	s_add_i32 m0, s61, 0x2000
	s_add_u32 s62, s34, 0x160000
	v_lshl_add_u64 v[214:215], s[34:35], 0, v[148:149]
	s_addc_u32 s63, s35, 0
	s_add_i32 s61, s54, s31
	global_load_lds_dwordx4 v[214:215], off
	v_lshl_add_u64 v[222:223], s[62:63], 0, v[144:145]
	s_mov_b32 m0, s61
	v_lshl_add_u64 v[224:225], s[42:43], 0, v[146:147]
	global_load_lds_dwordx4 v[222:223], off
	v_lshl_add_u64 v[222:223], s[62:63], 0, v[148:149]
	s_add_i32 m0, s61, 0x2000
	s_nop 0
	global_load_lds_dwordx4 v[222:223], off
	v_lshl_add_u64 v[222:223], s[42:43], 0, v[142:143]
	s_mov_b32 m0, s33
	s_nop 0
	global_load_lds_dwordx4 v[222:223], off
	s_mov_b32 m0, s44
	s_nop 0
	global_load_lds_dwordx4 v[224:225], off
	s_waitcnt vmcnt(8)
	s_waitcnt lgkmcnt(0)
	s_barrier
	s_setprio 1
	s_waitcnt lgkmcnt(0)
	v_mfma_f32_16x16x32_bf16 v[62:65], v[130:133], v[186:189], v[62:65]
	v_mfma_f32_16x16x32_bf16 v[58:61], v[138:141], v[186:189], v[58:61]
	v_mfma_f32_16x16x32_bf16 v[50:53], v[130:133], v[194:197], v[50:53]
	v_mfma_f32_16x16x32_bf16 v[42:45], v[138:141], v[194:197], v[42:45]
	v_mfma_f32_16x16x32_bf16 v[38:41], v[130:133], v[202:205], v[38:41]
	v_mfma_f32_16x16x32_bf16 v[34:37], v[138:141], v[202:205], v[34:37]
	v_mfma_f32_16x16x32_bf16 v[14:17], v[130:133], v[210:213], v[14:17]
	v_mfma_f32_16x16x32_bf16 v[10:13], v[138:141], v[210:213], v[10:13]
	v_mfma_f32_16x16x32_bf16 v[62:65], v[134:137], v[190:193], v[62:65]
	v_mfma_f32_16x16x32_bf16 v[58:61], v[158:161], v[190:193], v[58:61]
	v_mfma_f32_16x16x32_bf16 v[50:53], v[134:137], v[198:201], v[50:53]
	v_mfma_f32_16x16x32_bf16 v[42:45], v[158:161], v[198:201], v[42:45]
	v_mfma_f32_16x16x32_bf16 v[38:41], v[134:137], v[206:209], v[38:41]
	v_mfma_f32_16x16x32_bf16 v[34:37], v[158:161], v[206:209], v[34:37]
	v_mfma_f32_16x16x32_bf16 v[14:17], v[134:137], v[218:221], v[14:17]
	v_mfma_f32_16x16x32_bf16 v[10:13], v[158:161], v[218:221], v[10:13]
	s_setprio 0
	s_setprio 1
	v_mfma_f32_16x16x32_bf16 v[54:57], v[162:165], v[186:189], v[54:57]
	v_mfma_f32_16x16x32_bf16 v[46:49], v[178:181], v[186:189], v[46:49]
	v_mfma_f32_16x16x32_bf16 v[30:33], v[162:165], v[194:197], v[30:33]
	v_mfma_f32_16x16x32_bf16 v[26:29], v[178:181], v[194:197], v[26:29]
	v_mfma_f32_16x16x32_bf16 v[22:25], v[162:165], v[202:205], v[22:25]
	v_mfma_f32_16x16x32_bf16 v[18:21], v[178:181], v[202:205], v[18:21]
	v_mfma_f32_16x16x32_bf16 v[6:9], v[162:165], v[210:213], v[6:9]
	v_mfma_f32_16x16x32_bf16 v[2:5], v[178:181], v[210:213], v[2:5]
	v_mfma_f32_16x16x32_bf16 v[54:57], v[166:169], v[190:193], v[54:57]
	v_mfma_f32_16x16x32_bf16 v[46:49], v[182:185], v[190:193], v[46:49]
	v_mfma_f32_16x16x32_bf16 v[30:33], v[166:169], v[198:201], v[30:33]
	v_mfma_f32_16x16x32_bf16 v[26:29], v[182:185], v[198:201], v[26:29]
	v_mfma_f32_16x16x32_bf16 v[22:25], v[166:169], v[206:209], v[22:25]
	v_mfma_f32_16x16x32_bf16 v[18:21], v[182:185], v[206:209], v[18:21]
	v_mfma_f32_16x16x32_bf16 v[6:9], v[166:169], v[218:221], v[6:9]
	v_mfma_f32_16x16x32_bf16 v[2:5], v[182:185], v[218:221], v[2:5]
	s_setprio 0
	s_barrier
	s_add_i32 s61, 0, 0x18000
	s_add_i32 s62, 0, 0x1c000
	v_add_u32_e32 v158, s61, v172
	v_add_u32_e32 v177, 0x19000, v172
	ds_read_b128 v[130:133], v158
	ds_read_b128 v[134:137], v158 offset:1024
	ds_read_b128 v[138:141], v158 offset:2048
	ds_read_b128 v[158:161], v158 offset:3072
	ds_read_b128 v[162:165], v177
	ds_read_b128 v[166:169], v177 offset:1024
	ds_read_b128 v[178:181], v177 offset:2048
	ds_read_b128 v[182:185], v177 offset:3072
	s_add_u32 s42, s42, 0x160000
	s_addc_u32 s43, s43, 0
	s_mov_b32 m0, s45
	v_lshl_add_u64 v[226:227], s[42:43], 0, v[142:143]
	ds_read_b128 v[186:189], v176 offset:32768
	ds_read_b128 v[190:193], v176 offset:33792
	ds_read_b128 v[194:197], v176 offset:34816
	ds_read_b128 v[198:201], v176 offset:35840
	ds_read_b128 v[202:205], v176 offset:36864
	ds_read_b128 v[206:209], v176 offset:37888
	ds_read_b128 v[210:213], v176 offset:38912
	ds_read_b128 v[218:221], v176 offset:39936
	global_load_lds_dwordx4 v[226:227], off
	v_lshl_add_u64 v[226:227], s[42:43], 0, v[146:147]
	s_mov_b32 m0, s46
	s_nop 0
	global_load_lds_dwordx4 v[226:227], off
	s_waitcnt vmcnt(8)
	s_waitcnt lgkmcnt(0)
	s_barrier
	s_setprio 1
	s_waitcnt lgkmcnt(0)
	v_mfma_f32_16x16x32_bf16 v[126:129], v[130:133], v[186:189], v[126:129]
	v_mfma_f32_16x16x32_bf16 v[122:125], v[138:141], v[186:189], v[122:125]
	v_mfma_f32_16x16x32_bf16 v[110:113], v[130:133], v[194:197], v[110:113]
	v_mfma_f32_16x16x32_bf16 v[106:109], v[138:141], v[194:197], v[106:109]
	v_mfma_f32_16x16x32_bf16 v[94:97], v[130:133], v[202:205], v[94:97]
	v_mfma_f32_16x16x32_bf16 v[90:93], v[138:141], v[202:205], v[90:93]
	v_mfma_f32_16x16x32_bf16 v[78:81], v[130:133], v[210:213], v[78:81]
	v_mfma_f32_16x16x32_bf16 v[74:77], v[138:141], v[210:213], v[74:77]
	v_mfma_f32_16x16x32_bf16 v[126:129], v[134:137], v[190:193], v[126:129]
	v_mfma_f32_16x16x32_bf16 v[122:125], v[158:161], v[190:193], v[122:125]
	v_mfma_f32_16x16x32_bf16 v[110:113], v[134:137], v[198:201], v[110:113]
	v_mfma_f32_16x16x32_bf16 v[106:109], v[158:161], v[198:201], v[106:109]
	v_mfma_f32_16x16x32_bf16 v[94:97], v[134:137], v[206:209], v[94:97]
	v_mfma_f32_16x16x32_bf16 v[90:93], v[158:161], v[206:209], v[90:93]
	v_mfma_f32_16x16x32_bf16 v[78:81], v[134:137], v[218:221], v[78:81]
	v_mfma_f32_16x16x32_bf16 v[74:77], v[158:161], v[218:221], v[74:77]
	s_setprio 0
	s_setprio 1
	v_mfma_f32_16x16x32_bf16 v[118:121], v[162:165], v[186:189], v[118:121]
	v_mfma_f32_16x16x32_bf16 v[114:117], v[178:181], v[186:189], v[114:117]
	v_mfma_f32_16x16x32_bf16 v[102:105], v[162:165], v[194:197], v[102:105]
	v_mfma_f32_16x16x32_bf16 v[98:101], v[178:181], v[194:197], v[98:101]
	v_mfma_f32_16x16x32_bf16 v[86:89], v[162:165], v[202:205], v[86:89]
	v_mfma_f32_16x16x32_bf16 v[82:85], v[178:181], v[202:205], v[82:85]
	v_mfma_f32_16x16x32_bf16 v[70:73], v[162:165], v[210:213], v[70:73]
	v_mfma_f32_16x16x32_bf16 v[66:69], v[178:181], v[210:213], v[66:69]
	v_mfma_f32_16x16x32_bf16 v[118:121], v[166:169], v[190:193], v[118:121]
	v_mfma_f32_16x16x32_bf16 v[114:117], v[182:185], v[190:193], v[114:117]
	v_mfma_f32_16x16x32_bf16 v[102:105], v[166:169], v[198:201], v[102:105]
	v_mfma_f32_16x16x32_bf16 v[98:101], v[182:185], v[198:201], v[98:101]
	v_mfma_f32_16x16x32_bf16 v[86:89], v[166:169], v[206:209], v[86:89]
	v_mfma_f32_16x16x32_bf16 v[82:85], v[182:185], v[206:209], v[82:85]
	v_mfma_f32_16x16x32_bf16 v[70:73], v[166:169], v[218:221], v[70:73]
	v_mfma_f32_16x16x32_bf16 v[66:69], v[182:185], v[218:221], v[66:69]
	s_setprio 0
	s_barrier
	s_add_i32 s42, s61, s31
	v_lshl_add_u64 v[170:171], v[170:171], 0, s[24:25]
	s_mov_b32 m0, s42
	ds_read_b128 v[186:189], v176 offset:49152
	ds_read_b128 v[190:193], v176 offset:50176
	ds_read_b128 v[194:197], v176 offset:51200
	ds_read_b128 v[198:201], v176 offset:52224
	ds_read_b128 v[202:205], v176 offset:53248
	ds_read_b128 v[206:209], v176 offset:54272
	ds_read_b128 v[210:213], v176 offset:55296
	ds_read_b128 v[218:221], v176 offset:56320
	global_load_lds_dwordx4 v[170:171], off
	s_add_i32 m0, s42, 0x2000
	s_add_u32 s34, s34, 0x160080
	v_lshl_add_u64 v[170:171], v[214:215], 0, s[24:25]
	s_addc_u32 s35, s35, 0
	s_add_i32 s42, s62, s31
	global_load_lds_dwordx4 v[170:171], off
	v_lshl_add_u64 v[170:171], s[34:35], 0, v[144:145]
	s_mov_b32 m0, s42
	s_nop 0
	global_load_lds_dwordx4 v[170:171], off
	v_lshl_add_u64 v[170:171], s[34:35], 0, v[148:149]
	s_add_i32 m0, s42, 0x2000
	s_nop 0
	global_load_lds_dwordx4 v[170:171], off
	v_lshl_add_u64 v[170:171], v[222:223], 0, s[24:25]
	s_mov_b32 m0, s48
	s_nop 0
	global_load_lds_dwordx4 v[170:171], off
	v_lshl_add_u64 v[170:171], v[224:225], 0, s[24:25]
	s_mov_b32 m0, s49
	s_nop 0
	global_load_lds_dwordx4 v[170:171], off
	s_waitcnt vmcnt(8)
	s_waitcnt lgkmcnt(0)
	s_barrier
	s_setprio 1
	s_waitcnt lgkmcnt(0)
	v_mfma_f32_16x16x32_bf16 v[62:65], v[130:133], v[186:189], v[62:65]
	v_mfma_f32_16x16x32_bf16 v[58:61], v[138:141], v[186:189], v[58:61]
	v_mfma_f32_16x16x32_bf16 v[50:53], v[130:133], v[194:197], v[50:53]
	v_mfma_f32_16x16x32_bf16 v[42:45], v[138:141], v[194:197], v[42:45]
	v_mfma_f32_16x16x32_bf16 v[38:41], v[130:133], v[202:205], v[38:41]
	v_mfma_f32_16x16x32_bf16 v[34:37], v[138:141], v[202:205], v[34:37]
	v_mfma_f32_16x16x32_bf16 v[14:17], v[130:133], v[210:213], v[14:17]
	v_mfma_f32_16x16x32_bf16 v[10:13], v[138:141], v[210:213], v[10:13]
	v_mfma_f32_16x16x32_bf16 v[62:65], v[134:137], v[190:193], v[62:65]
	v_mfma_f32_16x16x32_bf16 v[58:61], v[158:161], v[190:193], v[58:61]
	v_mfma_f32_16x16x32_bf16 v[50:53], v[134:137], v[198:201], v[50:53]
	v_mfma_f32_16x16x32_bf16 v[42:45], v[158:161], v[198:201], v[42:45]
	v_mfma_f32_16x16x32_bf16 v[38:41], v[134:137], v[206:209], v[38:41]
	v_mfma_f32_16x16x32_bf16 v[34:37], v[158:161], v[206:209], v[34:37]
	v_mfma_f32_16x16x32_bf16 v[14:17], v[134:137], v[218:221], v[14:17]
	v_mfma_f32_16x16x32_bf16 v[10:13], v[158:161], v[218:221], v[10:13]
	s_setprio 0
	s_setprio 1
	v_mfma_f32_16x16x32_bf16 v[54:57], v[162:165], v[186:189], v[54:57]
	v_mfma_f32_16x16x32_bf16 v[46:49], v[178:181], v[186:189], v[46:49]
	v_mfma_f32_16x16x32_bf16 v[30:33], v[162:165], v[194:197], v[30:33]
	v_mfma_f32_16x16x32_bf16 v[26:29], v[178:181], v[194:197], v[26:29]
	v_mfma_f32_16x16x32_bf16 v[22:25], v[162:165], v[202:205], v[22:25]
	v_mfma_f32_16x16x32_bf16 v[18:21], v[178:181], v[202:205], v[18:21]
	v_mfma_f32_16x16x32_bf16 v[6:9], v[162:165], v[210:213], v[6:9]
	v_mfma_f32_16x16x32_bf16 v[2:5], v[178:181], v[210:213], v[2:5]
	v_mfma_f32_16x16x32_bf16 v[54:57], v[166:169], v[190:193], v[54:57]
	v_mfma_f32_16x16x32_bf16 v[46:49], v[182:185], v[190:193], v[46:49]
	v_mfma_f32_16x16x32_bf16 v[30:33], v[166:169], v[198:201], v[30:33]
	v_mfma_f32_16x16x32_bf16 v[26:29], v[182:185], v[198:201], v[26:29]
	v_mfma_f32_16x16x32_bf16 v[22:25], v[166:169], v[206:209], v[22:25]
	v_mfma_f32_16x16x32_bf16 v[18:21], v[182:185], v[206:209], v[18:21]
	v_mfma_f32_16x16x32_bf16 v[6:9], v[166:169], v[218:221], v[6:9]
	v_mfma_f32_16x16x32_bf16 v[2:5], v[182:185], v[218:221], v[2:5]
	s_setprio 0
	s_barrier
	s_add_i32 s60, s60, 2
	s_add_u32 s40, s40, 0x100
	s_addc_u32 s41, s41, 0
	s_add_u32 s0, s0, 0x100
	s_addc_u32 s1, s1, 0
	s_cmpk_gt_u32 s60, 0x55
	s_cbranch_scc0 .LBB0_3180
	s_and_b64 vcc, exec, s[26:27]
	s_cbranch_vccz .LBB0_3183
	s_barrier
.LBB0_3183:
	v_lshl_or_b32 v130, s59, 8, v173
	v_lshl_add_u32 v158, s58, 8, v1
	v_ashrrev_i32_e32 v131, 31, v130
	v_lshlrev_b64 v[160:161], 1, v[130:131]
	v_or_b32_e32 v130, 16, v158
	v_ashrrev_i32_e32 v159, 31, v158
	v_ashrrev_i32_e32 v131, 31, v130
	v_lshlrev_b64 v[132:133], 12, v[158:159]
	v_lshlrev_b64 v[130:131], 12, v[130:131]
	v_lshl_add_u64 v[132:133], s[64:65], 0, v[132:133]
	v_lshl_add_u64 v[130:131], s[64:65], 0, v[130:131]
	v_lshl_add_u64 v[170:171], v[132:133], 0, v[160:161]
	v_lshl_add_u64 v[168:169], v[130:131], 0, v[160:161]
	global_load_dwordx4 v[134:137], v[170:171], off
	global_load_dwordx4 v[138:141], v[170:171], off offset:64
	global_load_dwordx4 v[178:181], v[168:169], off
	global_load_dwordx4 v[182:185], v[168:169], off offset:64
	v_or_b32_e32 v130, 32, v158
	v_ashrrev_i32_e32 v131, 31, v130
	v_lshlrev_b64 v[130:131], 12, v[130:131]
	v_lshl_add_u64 v[130:131], s[64:65], 0, v[130:131]
	v_lshl_add_u64 v[162:163], v[130:131], 0, v[160:161]
	global_load_dwordx4 v[186:189], v[162:163], off
	global_load_dwordx4 v[190:193], v[162:163], off offset:64
	v_or_b32_e32 v130, 48, v158
	v_ashrrev_i32_e32 v131, 31, v130
	v_lshlrev_b64 v[130:131], 12, v[130:131]
	v_lshl_add_u64 v[130:131], s[64:65], 0, v[130:131]
	v_lshl_add_u64 v[166:167], v[130:131], 0, v[160:161]
	v_add_co_u32_e32 v164, vcc, s55, v170
	s_mov_b64 s[0:1], -1
	s_nop 0
	v_addc_co_u32_e32 v165, vcc, 0, v171, vcc
	global_load_dwordx4 v[194:197], v[166:167], off
	global_load_dwordx4 v[198:201], v[166:167], off offset:64
	global_load_dwordx4 v[130:133], v[164:165], off
	s_and_b64 vcc, exec, s[2:3]
	s_waitcnt vmcnt(0)
	v_cvt_f32_f16_e32 v202, v134
	v_cvt_f32_f16_e32 v210, v178
	v_cvt_f32_f16_sdwa v211, v178 dst_sel:DWORD dst_unused:UNUSED_PAD src0_sel:WORD_1
	v_cvt_f32_f16_e32 v212, v180
	v_cvt_f32_f16_sdwa v213, v180 dst_sel:DWORD dst_unused:UNUSED_PAD src0_sel:WORD_1
	v_cvt_f32_f16_e32 v180, v181
	v_cvt_f32_f16_sdwa v181, v181 dst_sel:DWORD dst_unused:UNUSED_PAD src0_sel:WORD_1
	v_cvt_f32_f16_e32 v218, v184
	v_cvt_f32_f16_sdwa v219, v184 dst_sel:DWORD dst_unused:UNUSED_PAD src0_sel:WORD_1
	v_cvt_f32_f16_e32 v214, v182
	v_cvt_f32_f16_sdwa v215, v182 dst_sel:DWORD dst_unused:UNUSED_PAD src0_sel:WORD_1
	v_cvt_f32_f16_sdwa v203, v134 dst_sel:DWORD dst_unused:UNUSED_PAD src0_sel:WORD_1
	v_cvt_f32_f16_e32 v134, v135
	v_cvt_f32_f16_sdwa v135, v135 dst_sel:DWORD dst_unused:UNUSED_PAD src0_sel:WORD_1
	v_cvt_f32_f16_e32 v204, v136
	v_cvt_f32_f16_sdwa v205, v136 dst_sel:DWORD dst_unused:UNUSED_PAD src0_sel:WORD_1
	v_cvt_f32_f16_e32 v136, v137
	v_cvt_f32_f16_sdwa v137, v137 dst_sel:DWORD dst_unused:UNUSED_PAD src0_sel:WORD_1
	v_cvt_f32_f16_e32 v206, v138
	v_cvt_f32_f16_sdwa v207, v138 dst_sel:DWORD dst_unused:UNUSED_PAD src0_sel:WORD_1
	v_cvt_f32_f16_e32 v138, v139
	v_cvt_f32_f16_sdwa v139, v139 dst_sel:DWORD dst_unused:UNUSED_PAD src0_sel:WORD_1
	v_cvt_f32_f16_e32 v208, v140
	v_cvt_f32_f16_sdwa v209, v140 dst_sel:DWORD dst_unused:UNUSED_PAD src0_sel:WORD_1
	v_cvt_f32_f16_e32 v140, v141
	v_cvt_f32_f16_sdwa v141, v141 dst_sel:DWORD dst_unused:UNUSED_PAD src0_sel:WORD_1
	v_cvt_f32_f16_e32 v178, v179
	v_cvt_f32_f16_sdwa v179, v179 dst_sel:DWORD dst_unused:UNUSED_PAD src0_sel:WORD_1
	v_pk_fma_f32 v[110:111], v[110:111], 0.5, v[210:211] op_sel_hi:[1,0,1]
	v_pk_fma_f32 v[108:109], v[108:109], 0.5, v[180:181] op_sel_hi:[1,0,1]
	v_pk_fma_f32 v[106:107], v[106:107], 0.5, v[212:213] op_sel_hi:[1,0,1]
	v_pk_fma_f32 v[98:99], v[98:99], 0.5, v[218:219] op_sel_hi:[1,0,1]
	v_cvt_pk_f16_f32 v109, v108, v109
	v_cvt_pk_f16_f32 v108, v106, v107
	v_cvt_pk_f16_f32 v106, v110, v111
	v_pk_fma_f32 v[110:111], v[102:103], 0.5, v[214:215] op_sel_hi:[1,0,1]
	v_cvt_pk_f16_f32 v102, v98, v99
	v_add_u32_e32 v98, 0x90, v158
	v_cvt_f32_f16_e32 v182, v183
	v_cvt_f32_f16_sdwa v183, v183 dst_sel:DWORD dst_unused:UNUSED_PAD src0_sel:WORD_1
	v_ashrrev_i32_e32 v99, 31, v98
	v_pk_fma_f32 v[128:129], v[128:129], 0.5, v[134:135] op_sel_hi:[1,0,1]
	v_pk_fma_f32 v[126:127], v[126:127], 0.5, v[202:203] op_sel_hi:[1,0,1]
	v_pk_fma_f32 v[124:125], v[124:125], 0.5, v[136:137] op_sel_hi:[1,0,1]
	v_pk_fma_f32 v[122:123], v[122:123], 0.5, v[204:205] op_sel_hi:[1,0,1]
	v_lshlrev_b64 v[98:99], 12, v[98:99]
	v_pk_fma_f32 v[134:135], v[120:121], 0.5, v[138:139] op_sel_hi:[1,0,1]
	v_pk_fma_f32 v[136:137], v[118:119], 0.5, v[206:207] op_sel_hi:[1,0,1]
	v_pk_fma_f32 v[118:119], v[116:117], 0.5, v[140:141] op_sel_hi:[1,0,1]
	v_pk_fma_f32 v[138:139], v[114:115], 0.5, v[208:209] op_sel_hi:[1,0,1]
	v_cvt_pk_f16_f32 v117, v124, v125
	v_cvt_pk_f16_f32 v116, v122, v123
	v_cvt_pk_f16_f32 v115, v128, v129
	v_cvt_pk_f16_f32 v114, v126, v127
	v_pk_fma_f32 v[112:113], v[112:113], 0.5, v[178:179] op_sel_hi:[1,0,1]
	v_lshl_add_u64 v[98:99], s[64:65], 0, v[98:99]
	v_cvt_pk_f16_f32 v121, v118, v119
	v_cvt_pk_f16_f32 v120, v138, v139
	v_cvt_pk_f16_f32 v119, v134, v135
	v_cvt_pk_f16_f32 v118, v136, v137
	global_store_dwordx4 v[170:171], v[114:117], off
	global_store_dwordx4 v[170:171], v[118:121], off offset:64
	v_cvt_pk_f16_f32 v107, v112, v113
	v_lshl_add_u64 v[98:99], v[98:99], 0, v[160:161]
	global_store_dwordx4 v[168:169], v[106:109], off
	v_cvt_f32_f16_e32 v184, v185
	v_cvt_f32_f16_sdwa v185, v185 dst_sel:DWORD dst_unused:UNUSED_PAD src0_sel:WORD_1
	v_pk_fma_f32 v[108:109], v[104:105], 0.5, v[182:183] op_sel_hi:[1,0,1]
	global_load_dwordx4 v[104:107], v[98:99], off
	v_cvt_f32_f16_e32 v126, v192
	v_cvt_f32_f16_sdwa v127, v192 dst_sel:DWORD dst_unused:UNUSED_PAD src0_sel:WORD_1
	v_cvt_f32_f16_e32 v128, v193
	v_cvt_f32_f16_sdwa v129, v193 dst_sel:DWORD dst_unused:UNUSED_PAD src0_sel:WORD_1
	v_cvt_f32_f16_e32 v220, v186
	v_cvt_f32_f16_sdwa v221, v186 dst_sel:DWORD dst_unused:UNUSED_PAD src0_sel:WORD_1
	v_cvt_f32_f16_e32 v186, v187
	v_cvt_f32_f16_sdwa v187, v187 dst_sel:DWORD dst_unused:UNUSED_PAD src0_sel:WORD_1
	v_cvt_f32_f16_e32 v222, v188
	v_cvt_f32_f16_sdwa v223, v188 dst_sel:DWORD dst_unused:UNUSED_PAD src0_sel:WORD_1
	v_cvt_f32_f16_e32 v120, v189
	v_cvt_f32_f16_sdwa v121, v189 dst_sel:DWORD dst_unused:UNUSED_PAD src0_sel:WORD_1
	v_lshl_add_u64 v[114:115], v[170:171], 0, s[36:37]
	v_pk_fma_f32 v[100:101], v[100:101], 0.5, v[184:185] op_sel_hi:[1,0,1]
	v_cvt_f32_f16_e32 v122, v190
	v_cvt_f32_f16_sdwa v123, v190 dst_sel:DWORD dst_unused:UNUSED_PAD src0_sel:WORD_1
	v_cvt_f32_f16_e32 v124, v191
	global_load_dwordx4 v[116:119], v[114:115], off offset:64
	v_cvt_f32_f16_sdwa v125, v191 dst_sel:DWORD dst_unused:UNUSED_PAD src0_sel:WORD_1
	v_cvt_pk_f16_f32 v103, v100, v101
	v_cvt_pk_f16_f32 v101, v108, v109
	v_cvt_pk_f16_f32 v100, v110, v111
	v_pk_fma_f32 v[84:85], v[84:85], 0.5, v[128:129] op_sel_hi:[1,0,1]
	v_pk_fma_f32 v[82:83], v[82:83], 0.5, v[126:127] op_sel_hi:[1,0,1]
	global_store_dwordx4 v[168:169], v[100:103], off offset:64
	v_cvt_f32_f16_e32 v136, v198
	v_cvt_f32_f16_sdwa v137, v198 dst_sel:DWORD dst_unused:UNUSED_PAD src0_sel:WORD_1
	v_cvt_f32_f16_e32 v138, v199
	v_cvt_f32_f16_sdwa v139, v199 dst_sel:DWORD dst_unused:UNUSED_PAD src0_sel:WORD_1
	v_cvt_f32_f16_e32 v140, v200
	v_cvt_f32_f16_sdwa v141, v200 dst_sel:DWORD dst_unused:UNUSED_PAD src0_sel:WORD_1
	v_cvt_f32_f16_e32 v168, v201
	v_cvt_f32_f16_sdwa v169, v201 dst_sel:DWORD dst_unused:UNUSED_PAD src0_sel:WORD_1
	v_cvt_pk_f16_f32 v85, v84, v85
	v_cvt_pk_f16_f32 v84, v82, v83
	v_add_u32_e32 v82, 0xa0, v158
	v_pk_fma_f32 v[96:97], v[96:97], 0.5, v[186:187] op_sel_hi:[1,0,1]
	v_pk_fma_f32 v[94:95], v[94:95], 0.5, v[220:221] op_sel_hi:[1,0,1]
	v_pk_fma_f32 v[92:93], v[92:93], 0.5, v[120:121] op_sel_hi:[1,0,1]
	v_pk_fma_f32 v[90:91], v[90:91], 0.5, v[222:223] op_sel_hi:[1,0,1]
	v_ashrrev_i32_e32 v83, 31, v82
	v_cvt_pk_f16_f32 v93, v92, v93
	v_cvt_pk_f16_f32 v92, v90, v91
	v_cvt_pk_f16_f32 v91, v96, v97
	v_cvt_pk_f16_f32 v90, v94, v95
	v_lshlrev_b64 v[82:83], 12, v[82:83]
	global_load_dwordx4 v[100:103], v[98:99], off offset:64
	v_lshl_add_u64 v[82:83], s[64:65], 0, v[82:83]
	global_store_dwordx4 v[162:163], v[90:93], off
	v_cvt_f32_f16_e32 v108, v194
	v_cvt_f32_f16_sdwa v109, v194 dst_sel:DWORD dst_unused:UNUSED_PAD src0_sel:WORD_1
	v_pk_fma_f32 v[90:91], v[88:89], 0.5, v[124:125] op_sel_hi:[1,0,1]
	v_pk_fma_f32 v[92:93], v[86:87], 0.5, v[122:123] op_sel_hi:[1,0,1]
	v_cvt_f32_f16_e32 v110, v195
	v_cvt_f32_f16_sdwa v111, v195 dst_sel:DWORD dst_unused:UNUSED_PAD src0_sel:WORD_1
	v_cvt_f32_f16_e32 v112, v196
	v_cvt_f32_f16_sdwa v113, v196 dst_sel:DWORD dst_unused:UNUSED_PAD src0_sel:WORD_1
	v_cvt_f32_f16_e32 v134, v197
	v_cvt_f32_f16_sdwa v135, v197 dst_sel:DWORD dst_unused:UNUSED_PAD src0_sel:WORD_1
	v_lshl_add_u64 v[94:95], v[82:83], 0, v[160:161]
	v_cvt_pk_f16_f32 v83, v90, v91
	v_cvt_pk_f16_f32 v82, v92, v93
	v_pk_fma_f32 v[72:73], v[72:73], 0.5, v[138:139] op_sel_hi:[1,0,1]
	v_pk_fma_f32 v[70:71], v[70:71], 0.5, v[136:137] op_sel_hi:[1,0,1]
	v_pk_fma_f32 v[68:69], v[68:69], 0.5, v[168:169] op_sel_hi:[1,0,1]
	v_pk_fma_f32 v[66:67], v[66:67], 0.5, v[140:141] op_sel_hi:[1,0,1]
	global_load_dwordx4 v[86:89], v[94:95], off
	v_cvt_pk_f16_f32 v69, v68, v69
	global_store_dwordx4 v[162:163], v[82:85], off offset:64
	global_load_dwordx4 v[82:85], v[94:95], off offset:64
	v_cvt_pk_f16_f32 v68, v66, v67
	v_cvt_pk_f16_f32 v67, v72, v73
	v_cvt_pk_f16_f32 v66, v70, v71
	global_store_dwordx4 v[166:167], v[66:69], off offset:64
	v_pk_fma_f32 v[80:81], v[80:81], 0.5, v[110:111] op_sel_hi:[1,0,1]
	v_pk_fma_f32 v[78:79], v[78:79], 0.5, v[108:109] op_sel_hi:[1,0,1]
	v_add_u32_e32 v66, 0xb0, v158
	v_ashrrev_i32_e32 v67, 31, v66
	v_pk_fma_f32 v[76:77], v[76:77], 0.5, v[134:135] op_sel_hi:[1,0,1]
	v_pk_fma_f32 v[74:75], v[74:75], 0.5, v[112:113] op_sel_hi:[1,0,1]
	v_lshlrev_b64 v[66:67], 12, v[66:67]
	v_cvt_pk_f16_f32 v77, v76, v77
	v_cvt_pk_f16_f32 v76, v74, v75
	v_cvt_pk_f16_f32 v75, v80, v81
	v_cvt_pk_f16_f32 v74, v78, v79
	v_lshl_add_u64 v[66:67], s[64:65], 0, v[66:67]
	global_store_dwordx4 v[166:167], v[74:77], off
	v_cvt_f32_f16_e32 v90, v130
	v_cvt_f32_f16_sdwa v91, v130 dst_sel:DWORD dst_unused:UNUSED_PAD src0_sel:WORD_1
	s_waitcnt vmcnt(9)
	v_cvt_f32_f16_e32 v74, v104
	v_cvt_f32_f16_sdwa v75, v104 dst_sel:DWORD dst_unused:UNUSED_PAD src0_sel:WORD_1
	v_cvt_f32_f16_e32 v76, v105
	v_cvt_f32_f16_sdwa v77, v105 dst_sel:DWORD dst_unused:UNUSED_PAD src0_sel:WORD_1
	v_lshl_add_u64 v[104:105], v[66:67], 0, v[160:161]
	global_load_dwordx4 v[66:69], v[104:105], off
	global_load_dwordx4 v[70:73], v[104:105], off offset:64
	v_cvt_f32_f16_e32 v92, v131
	v_cvt_f32_f16_sdwa v93, v131 dst_sel:DWORD dst_unused:UNUSED_PAD src0_sel:WORD_1
	v_cvt_f32_f16_e32 v96, v132
	v_cvt_f32_f16_sdwa v97, v132 dst_sel:DWORD dst_unused:UNUSED_PAD src0_sel:WORD_1
	v_cvt_f32_f16_e32 v120, v133
	v_cvt_f32_f16_sdwa v121, v133 dst_sel:DWORD dst_unused:UNUSED_PAD src0_sel:WORD_1
	s_waitcnt vmcnt(10)
	v_cvt_f32_f16_e32 v122, v116
	v_cvt_f32_f16_sdwa v123, v116 dst_sel:DWORD dst_unused:UNUSED_PAD src0_sel:WORD_1
	v_cvt_f32_f16_e32 v116, v117
	v_cvt_f32_f16_sdwa v117, v117 dst_sel:DWORD dst_unused:UNUSED_PAD src0_sel:WORD_1
	v_cvt_f32_f16_e32 v124, v118
	v_cvt_f32_f16_sdwa v125, v118 dst_sel:DWORD dst_unused:UNUSED_PAD src0_sel:WORD_1
	v_cvt_f32_f16_e32 v118, v119
	v_cvt_f32_f16_sdwa v119, v119 dst_sel:DWORD dst_unused:UNUSED_PAD src0_sel:WORD_1
	v_cvt_f32_f16_e32 v78, v106
	v_cvt_f32_f16_sdwa v79, v106 dst_sel:DWORD dst_unused:UNUSED_PAD src0_sel:WORD_1
	v_cvt_f32_f16_e32 v80, v107
	v_cvt_f32_f16_sdwa v81, v107 dst_sel:DWORD dst_unused:UNUSED_PAD src0_sel:WORD_1
	v_pk_fma_f32 v[64:65], v[64:65], 0.5, v[92:93] op_sel_hi:[1,0,1]
	v_pk_fma_f32 v[62:63], v[62:63], 0.5, v[90:91] op_sel_hi:[1,0,1]
	v_pk_fma_f32 v[60:61], v[60:61], 0.5, v[120:121] op_sel_hi:[1,0,1]
	v_pk_fma_f32 v[58:59], v[58:59], 0.5, v[96:97] op_sel_hi:[1,0,1]
	v_pk_fma_f32 v[56:57], v[56:57], 0.5, v[116:117] op_sel_hi:[1,0,1]
	v_pk_fma_f32 v[54:55], v[54:55], 0.5, v[122:123] op_sel_hi:[1,0,1]
	v_pk_fma_f32 v[48:49], v[48:49], 0.5, v[118:119] op_sel_hi:[1,0,1]
	v_pk_fma_f32 v[46:47], v[46:47], 0.5, v[124:125] op_sel_hi:[1,0,1]
	v_cvt_pk_f16_f32 v61, v60, v61
	v_cvt_pk_f16_f32 v60, v58, v59
	v_cvt_pk_f16_f32 v59, v64, v65
	v_cvt_pk_f16_f32 v58, v62, v63
	v_cvt_pk_f16_f32 v49, v48, v49
	s_waitcnt vmcnt(8)
	v_cvt_f32_f16_e32 v106, v100
	v_cvt_f32_f16_sdwa v107, v100 dst_sel:DWORD dst_unused:UNUSED_PAD src0_sel:WORD_1
	v_cvt_f32_f16_e32 v100, v101
	v_cvt_f32_f16_sdwa v101, v101 dst_sel:DWORD dst_unused:UNUSED_PAD src0_sel:WORD_1
	v_cvt_f32_f16_e32 v108, v102
	v_cvt_f32_f16_sdwa v109, v102 dst_sel:DWORD dst_unused:UNUSED_PAD src0_sel:WORD_1
	v_cvt_f32_f16_e32 v102, v103
	v_cvt_f32_f16_sdwa v103, v103 dst_sel:DWORD dst_unused:UNUSED_PAD src0_sel:WORD_1
	v_cvt_pk_f16_f32 v48, v46, v47
	v_cvt_pk_f16_f32 v47, v56, v57
	v_cvt_pk_f16_f32 v46, v54, v55
	global_store_dwordx4 v[164:165], v[58:61], off
	global_store_dwordx4 v[114:115], v[46:49], off offset:64
	v_pk_fma_f32 v[32:33], v[32:33], 0.5, v[100:101] op_sel_hi:[1,0,1]
	v_pk_fma_f32 v[30:31], v[30:31], 0.5, v[106:107] op_sel_hi:[1,0,1]
	v_pk_fma_f32 v[28:29], v[28:29], 0.5, v[102:103] op_sel_hi:[1,0,1]
	v_pk_fma_f32 v[26:27], v[26:27], 0.5, v[108:109] op_sel_hi:[1,0,1]
	v_cvt_pk_f16_f32 v29, v28, v29
	v_cvt_pk_f16_f32 v28, v26, v27
	v_cvt_pk_f16_f32 v27, v32, v33
	s_waitcnt vmcnt(8)
	v_cvt_f32_f16_e32 v46, v86
	v_cvt_f32_f16_sdwa v47, v86 dst_sel:DWORD dst_unused:UNUSED_PAD src0_sel:WORD_1
	v_cvt_f32_f16_e32 v48, v87
	v_cvt_f32_f16_sdwa v49, v87 dst_sel:DWORD dst_unused:UNUSED_PAD src0_sel:WORD_1
	v_cvt_f32_f16_e32 v54, v88
	v_cvt_f32_f16_sdwa v55, v88 dst_sel:DWORD dst_unused:UNUSED_PAD src0_sel:WORD_1
	v_cvt_f32_f16_e32 v56, v89
	v_cvt_f32_f16_sdwa v57, v89 dst_sel:DWORD dst_unused:UNUSED_PAD src0_sel:WORD_1
	s_waitcnt vmcnt(6)
	v_cvt_f32_f16_e32 v58, v82
	v_cvt_f32_f16_sdwa v59, v82 dst_sel:DWORD dst_unused:UNUSED_PAD src0_sel:WORD_1
	v_cvt_f32_f16_e32 v60, v83
	v_cvt_f32_f16_sdwa v61, v83 dst_sel:DWORD dst_unused:UNUSED_PAD src0_sel:WORD_1
	v_cvt_f32_f16_e32 v62, v84
	v_cvt_f32_f16_sdwa v63, v84 dst_sel:DWORD dst_unused:UNUSED_PAD src0_sel:WORD_1
	v_cvt_f32_f16_e32 v64, v85
	v_cvt_f32_f16_sdwa v65, v85 dst_sel:DWORD dst_unused:UNUSED_PAD src0_sel:WORD_1
	v_cvt_pk_f16_f32 v26, v30, v31
	global_store_dwordx4 v[98:99], v[26:29], off offset:64
	v_pk_fma_f32 v[30:31], v[38:39], 0.5, v[46:47] op_sel_hi:[1,0,1]
	v_pk_fma_f32 v[32:33], v[34:35], 0.5, v[54:55] op_sel_hi:[1,0,1]
	v_pk_fma_f32 v[26:27], v[40:41], 0.5, v[48:49] op_sel_hi:[1,0,1]
	v_pk_fma_f32 v[28:29], v[36:37], 0.5, v[56:57] op_sel_hi:[1,0,1]
	v_pk_fma_f32 v[24:25], v[24:25], 0.5, v[60:61] op_sel_hi:[1,0,1]
	v_pk_fma_f32 v[22:23], v[22:23], 0.5, v[58:59] op_sel_hi:[1,0,1]
	v_pk_fma_f32 v[20:21], v[20:21], 0.5, v[64:65] op_sel_hi:[1,0,1]
	v_pk_fma_f32 v[18:19], v[18:19], 0.5, v[62:63] op_sel_hi:[1,0,1]
	v_cvt_pk_f16_f32 v29, v28, v29
	v_cvt_pk_f16_f32 v28, v32, v33
	v_cvt_pk_f16_f32 v27, v26, v27
	v_cvt_pk_f16_f32 v26, v30, v31
	v_cvt_pk_f16_f32 v21, v20, v21
	v_cvt_pk_f16_f32 v20, v18, v19
	v_cvt_pk_f16_f32 v19, v24, v25
	v_cvt_pk_f16_f32 v18, v22, v23
	global_store_dwordx4 v[94:95], v[26:29], off
	global_store_dwordx4 v[94:95], v[18:21], off offset:64
	s_waitcnt vmcnt(5)
	v_cvt_f32_f16_e32 v22, v70
	v_cvt_f32_f16_sdwa v23, v70 dst_sel:DWORD dst_unused:UNUSED_PAD src0_sel:WORD_1
	v_cvt_f32_f16_e32 v18, v72
	v_cvt_f32_f16_sdwa v19, v72 dst_sel:DWORD dst_unused:UNUSED_PAD src0_sel:WORD_1
	v_cvt_f32_f16_e32 v20, v73
	v_cvt_f32_f16_sdwa v21, v73 dst_sel:DWORD dst_unused:UNUSED_PAD src0_sel:WORD_1
	v_cvt_f32_f16_e32 v24, v71
	v_cvt_f32_f16_sdwa v25, v71 dst_sel:DWORD dst_unused:UNUSED_PAD src0_sel:WORD_1
	v_cvt_f32_f16_e32 v26, v68
	v_cvt_f32_f16_e32 v28, v69
	v_cvt_f32_f16_e32 v30, v66
	v_cvt_f32_f16_e32 v32, v67
	v_cvt_f32_f16_sdwa v33, v67 dst_sel:DWORD dst_unused:UNUSED_PAD src0_sel:WORD_1
	v_cvt_f32_f16_sdwa v31, v66 dst_sel:DWORD dst_unused:UNUSED_PAD src0_sel:WORD_1
	v_cvt_f32_f16_sdwa v29, v69 dst_sel:DWORD dst_unused:UNUSED_PAD src0_sel:WORD_1
	v_cvt_f32_f16_sdwa v27, v68 dst_sel:DWORD dst_unused:UNUSED_PAD src0_sel:WORD_1
	v_pk_fma_f32 v[52:53], v[52:53], 0.5, v[76:77] op_sel_hi:[1,0,1]
	v_pk_fma_f32 v[50:51], v[50:51], 0.5, v[74:75] op_sel_hi:[1,0,1]
	v_pk_fma_f32 v[44:45], v[44:45], 0.5, v[80:81] op_sel_hi:[1,0,1]
	v_pk_fma_f32 v[42:43], v[42:43], 0.5, v[78:79] op_sel_hi:[1,0,1]
	v_pk_fma_f32 v[16:17], v[16:17], 0.5, v[32:33] op_sel_hi:[1,0,1]
	v_pk_fma_f32 v[14:15], v[14:15], 0.5, v[30:31] op_sel_hi:[1,0,1]
	v_pk_fma_f32 v[12:13], v[12:13], 0.5, v[28:29] op_sel_hi:[1,0,1]
	v_pk_fma_f32 v[10:11], v[10:11], 0.5, v[26:27] op_sel_hi:[1,0,1]
	v_pk_fma_f32 v[8:9], v[8:9], 0.5, v[24:25] op_sel_hi:[1,0,1]
	v_pk_fma_f32 v[6:7], v[6:7], 0.5, v[22:23] op_sel_hi:[1,0,1]
	v_pk_fma_f32 v[4:5], v[4:5], 0.5, v[20:21] op_sel_hi:[1,0,1]
	v_pk_fma_f32 v[2:3], v[2:3], 0.5, v[18:19] op_sel_hi:[1,0,1]
	v_cvt_pk_f16_f32 v45, v44, v45
	v_cvt_pk_f16_f32 v44, v42, v43
	v_cvt_pk_f16_f32 v43, v52, v53
	v_cvt_pk_f16_f32 v42, v50, v51
	v_cvt_pk_f16_f32 v13, v12, v13
	v_cvt_pk_f16_f32 v12, v10, v11
	v_cvt_pk_f16_f32 v11, v16, v17
	v_cvt_pk_f16_f32 v10, v14, v15
	v_cvt_pk_f16_f32 v5, v4, v5
	v_cvt_pk_f16_f32 v4, v2, v3
	v_cvt_pk_f16_f32 v3, v8, v9
	v_cvt_pk_f16_f32 v2, v6, v7
	global_store_dwordx4 v[98:99], v[42:45], off
	global_store_dwordx4 v[104:105], v[10:13], off
	global_store_dwordx4 v[104:105], v[2:5], off offset:64
	s_cbranch_vccnz .LBB0_3168
	s_andn2_b64 vcc, exec, s[8:9]
	s_cbranch_vccnz .LBB0_3167
	s_barrier
	s_branch .LBB0_3167

.LBB0_3696:
	s_lshl_b32 s1, s1, 5
	s_mov_b64 s[12:13], 0x80
	s_and_b32 s1, s1, 0x60
	s_add_i32 m0, s41, 0x18000
	v_lshl_add_u64 v[8:9], v[8:9], 0, s[12:13]
	s_lshl_b32 s24, s0, 13
	s_lshl_b32 s25, s1, 7
	s_waitcnt vmcnt(2)
	s_barrier
	global_load_lds_dwordx4 v[8:9], off
	v_lshl_add_u64 v[4:5], v[4:5], 0, s[12:13]
	s_add_i32 m0, s41, 0x1a000
	s_add_i32 s51, s41, 0x8000
	s_add_i32 s52, s41, 0xa000
	global_load_lds_dwordx4 v[4:5], off
	v_lshl_add_u64 v[2:3], v[2:3], 0, s[12:13]
	s_mov_b32 m0, s51
	s_add_u32 s14, s44, 0x80080
	global_load_lds_dwordx4 v[2:3], off
	v_lshl_add_u64 v[2:3], v[6:7], 0, s[12:13]
	s_mov_b32 m0, s52
	s_addc_u32 s15, s45, 0
	global_load_lds_dwordx4 v[2:3], off
	s_add_i32 m0, s41, 0x1c000
	v_lshl_add_u64 v[2:3], s[14:15], 0, v[144:145]
	global_load_lds_dwordx4 v[2:3], off
	v_lshl_add_u64 v[2:3], s[14:15], 0, v[148:149]
	s_add_i32 m0, s41, 0x1e000
	v_lshlrev_b32_e32 v4, 2, v0
	global_load_lds_dwordx4 v[2:3], off
	v_and_b32_e32 v2, 15, v0
	v_lshl_or_b32 v1, s0, 6, v2
	v_lshlrev_b32_e32 v3, 1, v13
	v_lshlrev_b32_e32 v5, 6, v0
	s_movk_i32 s0, 0x3c0
	v_lshl_or_b32 v2, v2, 6, v3
	v_and_b32_e32 v4, 32, v4
	v_and_or_b32 v3, v5, s0, v3
	v_bitop3_b32 v172, s25, v3, v4 bitop3:0xf6
	v_add_u32_e32 v172, s25, v172
	v_lshlrev_b32_e32 v3, 9, v0
	v_bitop3_b32 v2, v2, s24, v4 bitop3:0xde
	v_and_b32_e32 v3, 0x30000, v3
	v_lshlrev_b32_e32 v4, 12, v12
	v_or3_b32 v3, v10, v3, v4
	v_add_u32_e32 v150, v3, v11
	v_lshlrev_b32_e32 v3, 5, v14
	s_waitcnt vmcnt(6)
	s_cmpk_lt_u32 s3, 0x100
	v_and_b32_e32 v3, 0x70000, v3
	s_cselect_b64 s[14:15], -1, 0
	v_or3_b32 v3, v10, v3, v4
	s_add_i32 s54, 0, 0x10000
	s_add_i32 s55, 0, 0x14000
	s_sext_i32_i8 s57, s2
	s_ashr_i32 s53, s11, 31
	v_lshl_or_b32 v173, s1, 1, v13
	v_mov_b32_e32 v151, v145
	v_add_u32_e32 v152, v3, v11
	v_mov_b32_e32 v153, v145
	v_mov_b64_e32 v[154:155], 0x100
	v_mov_b64_e32 v[156:157], 0xff
	v_add_u32_e32 v174, s54, v172
	v_add_u32_e32 v175, 0x11000, v172
	v_add_u32_e32 v176, 0, v2
	s_mov_b32 s56, 0x80000
	s_barrier
	s_branch .LBB0_3699

.LBB0_3706:
	ds_read_b128 v[130:133], v174
	ds_read_b128 v[134:137], v174 offset:1024
	ds_read_b128 v[138:141], v174 offset:2048
	ds_read_b128 v[158:161], v174 offset:3072
	ds_read_b128 v[162:165], v175
	ds_read_b128 v[166:169], v175 offset:1024
	ds_read_b128 v[178:181], v175 offset:2048
	ds_read_b128 v[182:185], v175 offset:3072
	s_add_u32 s34, s42, 0xfff80080
	s_addc_u32 s35, s43, -1
	s_cmp_eq_u32 s60, 28
	s_cselect_b32 s45, s0, s35
	s_cselect_b32 s44, s1, s34
	s_cselect_b32 s35, s25, s59
	s_cselect_b32 s34, s27, s58
	v_lshl_add_u64 v[170:171], s[42:43], 0, v[150:151]
	s_add_i32 m0, s41, 0xc000
	ds_read_b128 v[186:189], v176
	ds_read_b128 v[190:193], v176 offset:1024
	ds_read_b128 v[194:197], v176 offset:2048
	ds_read_b128 v[198:201], v176 offset:3072
	ds_read_b128 v[202:205], v176 offset:4096
	ds_read_b128 v[206:209], v176 offset:5120
	ds_read_b128 v[210:213], v176 offset:6144
	ds_read_b128 v[218:221], v176 offset:7168
	global_load_lds_dwordx4 v[170:171], off
	v_lshl_add_u64 v[170:171], s[42:43], 0, v[152:153]
	s_add_i32 m0, s41, 0xe000
	s_nop 0
	global_load_lds_dwordx4 v[170:171], off
	s_waitcnt vmcnt(8)
	s_waitcnt lgkmcnt(0)
	s_barrier
	s_setprio 1
	s_waitcnt lgkmcnt(0)
	v_mfma_f32_16x16x32_bf16 v[126:129], v[130:133], v[186:189], v[126:129]
	v_mfma_f32_16x16x32_bf16 v[122:125], v[138:141], v[186:189], v[122:125]
	v_mfma_f32_16x16x32_bf16 v[110:113], v[130:133], v[194:197], v[110:113]
	v_mfma_f32_16x16x32_bf16 v[106:109], v[138:141], v[194:197], v[106:109]
	v_mfma_f32_16x16x32_bf16 v[94:97], v[130:133], v[202:205], v[94:97]
	v_mfma_f32_16x16x32_bf16 v[90:93], v[138:141], v[202:205], v[90:93]
	v_mfma_f32_16x16x32_bf16 v[78:81], v[130:133], v[210:213], v[78:81]
	v_mfma_f32_16x16x32_bf16 v[74:77], v[138:141], v[210:213], v[74:77]
	v_mfma_f32_16x16x32_bf16 v[126:129], v[134:137], v[190:193], v[126:129]
	v_mfma_f32_16x16x32_bf16 v[122:125], v[158:161], v[190:193], v[122:125]
	v_mfma_f32_16x16x32_bf16 v[110:113], v[134:137], v[198:201], v[110:113]
	v_mfma_f32_16x16x32_bf16 v[106:109], v[158:161], v[198:201], v[106:109]
	v_mfma_f32_16x16x32_bf16 v[94:97], v[134:137], v[206:209], v[94:97]
	v_mfma_f32_16x16x32_bf16 v[90:93], v[158:161], v[206:209], v[90:93]
	v_mfma_f32_16x16x32_bf16 v[78:81], v[134:137], v[218:221], v[78:81]
	v_mfma_f32_16x16x32_bf16 v[74:77], v[158:161], v[218:221], v[74:77]
	s_setprio 0
	s_setprio 1
	v_mfma_f32_16x16x32_bf16 v[118:121], v[162:165], v[186:189], v[118:121]
	v_mfma_f32_16x16x32_bf16 v[114:117], v[178:181], v[186:189], v[114:117]
	v_mfma_f32_16x16x32_bf16 v[102:105], v[162:165], v[194:197], v[102:105]
	v_mfma_f32_16x16x32_bf16 v[98:101], v[178:181], v[194:197], v[98:101]
	v_mfma_f32_16x16x32_bf16 v[86:89], v[162:165], v[202:205], v[86:89]
	v_mfma_f32_16x16x32_bf16 v[82:85], v[178:181], v[202:205], v[82:85]
	v_mfma_f32_16x16x32_bf16 v[70:73], v[162:165], v[210:213], v[70:73]
	v_mfma_f32_16x16x32_bf16 v[66:69], v[178:181], v[210:213], v[66:69]
	v_mfma_f32_16x16x32_bf16 v[118:121], v[166:169], v[190:193], v[118:121]
	v_mfma_f32_16x16x32_bf16 v[114:117], v[182:185], v[190:193], v[114:117]
	v_mfma_f32_16x16x32_bf16 v[102:105], v[166:169], v[198:201], v[102:105]
	v_mfma_f32_16x16x32_bf16 v[98:101], v[182:185], v[198:201], v[98:101]
	v_mfma_f32_16x16x32_bf16 v[86:89], v[166:169], v[206:209], v[86:89]
	v_mfma_f32_16x16x32_bf16 v[82:85], v[182:185], v[206:209], v[82:85]
	v_mfma_f32_16x16x32_bf16 v[70:73], v[166:169], v[218:221], v[70:73]
	v_mfma_f32_16x16x32_bf16 v[66:69], v[182:185], v[218:221], v[66:69]
	s_setprio 0
	s_barrier
	s_add_i32 s61, s54, s46
	v_lshl_add_u64 v[170:171], s[34:35], 0, v[144:145]
	s_mov_b32 m0, s61
	ds_read_b128 v[186:189], v176 offset:16384
	ds_read_b128 v[190:193], v176 offset:17408
	ds_read_b128 v[194:197], v176 offset:18432
	ds_read_b128 v[198:201], v176 offset:19456
	ds_read_b128 v[202:205], v176 offset:20480
	ds_read_b128 v[206:209], v176 offset:21504
	ds_read_b128 v[210:213], v176 offset:22528
	ds_read_b128 v[218:221], v176 offset:23552
	global_load_lds_dwordx4 v[170:171], off
	s_add_i32 m0, s61, 0x2000
	s_add_u32 s62, s34, 0x80000
	v_lshl_add_u64 v[214:215], s[34:35], 0, v[148:149]
	s_addc_u32 s63, s35, 0
	s_add_i32 s61, s55, s46
	global_load_lds_dwordx4 v[214:215], off
	v_lshl_add_u64 v[222:223], s[62:63], 0, v[144:145]
	s_mov_b32 m0, s61
	v_lshl_add_u64 v[224:225], s[44:45], 0, v[146:147]
	global_load_lds_dwordx4 v[222:223], off
	v_lshl_add_u64 v[222:223], s[62:63], 0, v[148:149]
	s_add_i32 m0, s61, 0x2000
	s_nop 0
	global_load_lds_dwordx4 v[222:223], off
	v_lshl_add_u64 v[222:223], s[44:45], 0, v[142:143]
	s_mov_b32 m0, s41
	s_nop 0
	global_load_lds_dwordx4 v[222:223], off
	s_mov_b32 m0, s47
	s_nop 0
	global_load_lds_dwordx4 v[224:225], off
	s_waitcnt vmcnt(8)
	s_waitcnt lgkmcnt(0)
	s_barrier
	s_setprio 1
	s_waitcnt lgkmcnt(0)
	v_mfma_f32_16x16x32_bf16 v[62:65], v[130:133], v[186:189], v[62:65]
	v_mfma_f32_16x16x32_bf16 v[58:61], v[138:141], v[186:189], v[58:61]
	v_mfma_f32_16x16x32_bf16 v[50:53], v[130:133], v[194:197], v[50:53]
	v_mfma_f32_16x16x32_bf16 v[42:45], v[138:141], v[194:197], v[42:45]
	v_mfma_f32_16x16x32_bf16 v[38:41], v[130:133], v[202:205], v[38:41]
	v_mfma_f32_16x16x32_bf16 v[34:37], v[138:141], v[202:205], v[34:37]
	v_mfma_f32_16x16x32_bf16 v[14:17], v[130:133], v[210:213], v[14:17]
	v_mfma_f32_16x16x32_bf16 v[10:13], v[138:141], v[210:213], v[10:13]
	v_mfma_f32_16x16x32_bf16 v[62:65], v[134:137], v[190:193], v[62:65]
	v_mfma_f32_16x16x32_bf16 v[58:61], v[158:161], v[190:193], v[58:61]
	v_mfma_f32_16x16x32_bf16 v[50:53], v[134:137], v[198:201], v[50:53]
	v_mfma_f32_16x16x32_bf16 v[42:45], v[158:161], v[198:201], v[42:45]
	v_mfma_f32_16x16x32_bf16 v[38:41], v[134:137], v[206:209], v[38:41]
	v_mfma_f32_16x16x32_bf16 v[34:37], v[158:161], v[206:209], v[34:37]
	v_mfma_f32_16x16x32_bf16 v[14:17], v[134:137], v[218:221], v[14:17]
	v_mfma_f32_16x16x32_bf16 v[10:13], v[158:161], v[218:221], v[10:13]
	s_setprio 0
	s_setprio 1
	v_mfma_f32_16x16x32_bf16 v[54:57], v[162:165], v[186:189], v[54:57]
	v_mfma_f32_16x16x32_bf16 v[46:49], v[178:181], v[186:189], v[46:49]
	v_mfma_f32_16x16x32_bf16 v[30:33], v[162:165], v[194:197], v[30:33]
	v_mfma_f32_16x16x32_bf16 v[26:29], v[178:181], v[194:197], v[26:29]
	v_mfma_f32_16x16x32_bf16 v[22:25], v[162:165], v[202:205], v[22:25]
	v_mfma_f32_16x16x32_bf16 v[18:21], v[178:181], v[202:205], v[18:21]
	v_mfma_f32_16x16x32_bf16 v[6:9], v[162:165], v[210:213], v[6:9]
	v_mfma_f32_16x16x32_bf16 v[2:5], v[178:181], v[210:213], v[2:5]
	v_mfma_f32_16x16x32_bf16 v[54:57], v[166:169], v[190:193], v[54:57]
	v_mfma_f32_16x16x32_bf16 v[46:49], v[182:185], v[190:193], v[46:49]
	v_mfma_f32_16x16x32_bf16 v[30:33], v[166:169], v[198:201], v[30:33]
	v_mfma_f32_16x16x32_bf16 v[26:29], v[182:185], v[198:201], v[26:29]
	v_mfma_f32_16x16x32_bf16 v[22:25], v[166:169], v[206:209], v[22:25]
	v_mfma_f32_16x16x32_bf16 v[18:21], v[182:185], v[206:209], v[18:21]
	v_mfma_f32_16x16x32_bf16 v[6:9], v[166:169], v[218:221], v[6:9]
	v_mfma_f32_16x16x32_bf16 v[2:5], v[182:185], v[218:221], v[2:5]
	s_setprio 0
	s_barrier
	s_add_i32 s61, 0, 0x18000
	s_add_i32 s62, 0, 0x1c000
	v_add_u32_e32 v158, s61, v172
	v_add_u32_e32 v177, 0x19000, v172
	ds_read_b128 v[130:133], v158
	ds_read_b128 v[134:137], v158 offset:1024
	ds_read_b128 v[138:141], v158 offset:2048
	ds_read_b128 v[158:161], v158 offset:3072
	ds_read_b128 v[162:165], v177
	ds_read_b128 v[166:169], v177 offset:1024
	ds_read_b128 v[178:181], v177 offset:2048
	ds_read_b128 v[182:185], v177 offset:3072
	s_add_u32 s44, s44, 0x80000
	s_addc_u32 s45, s45, 0
	s_mov_b32 m0, s48
	v_lshl_add_u64 v[226:227], s[44:45], 0, v[142:143]
	ds_read_b128 v[186:189], v176 offset:32768
	ds_read_b128 v[190:193], v176 offset:33792
	ds_read_b128 v[194:197], v176 offset:34816
	ds_read_b128 v[198:201], v176 offset:35840
	ds_read_b128 v[202:205], v176 offset:36864
	ds_read_b128 v[206:209], v176 offset:37888
	ds_read_b128 v[210:213], v176 offset:38912
	ds_read_b128 v[218:221], v176 offset:39936
	global_load_lds_dwordx4 v[226:227], off
	v_lshl_add_u64 v[226:227], s[44:45], 0, v[146:147]
	s_mov_b32 m0, s49
	s_nop 0
	global_load_lds_dwordx4 v[226:227], off
	s_waitcnt vmcnt(8)
	s_waitcnt lgkmcnt(0)
	s_barrier
	s_setprio 1
	s_waitcnt lgkmcnt(0)
	v_mfma_f32_16x16x32_bf16 v[126:129], v[130:133], v[186:189], v[126:129]
	v_mfma_f32_16x16x32_bf16 v[122:125], v[138:141], v[186:189], v[122:125]
	v_mfma_f32_16x16x32_bf16 v[110:113], v[130:133], v[194:197], v[110:113]
	v_mfma_f32_16x16x32_bf16 v[106:109], v[138:141], v[194:197], v[106:109]
	v_mfma_f32_16x16x32_bf16 v[94:97], v[130:133], v[202:205], v[94:97]
	v_mfma_f32_16x16x32_bf16 v[90:93], v[138:141], v[202:205], v[90:93]
	v_mfma_f32_16x16x32_bf16 v[78:81], v[130:133], v[210:213], v[78:81]
	v_mfma_f32_16x16x32_bf16 v[74:77], v[138:141], v[210:213], v[74:77]
	v_mfma_f32_16x16x32_bf16 v[126:129], v[134:137], v[190:193], v[126:129]
	v_mfma_f32_16x16x32_bf16 v[122:125], v[158:161], v[190:193], v[122:125]
	v_mfma_f32_16x16x32_bf16 v[110:113], v[134:137], v[198:201], v[110:113]
	v_mfma_f32_16x16x32_bf16 v[106:109], v[158:161], v[198:201], v[106:109]
	v_mfma_f32_16x16x32_bf16 v[94:97], v[134:137], v[206:209], v[94:97]
	v_mfma_f32_16x16x32_bf16 v[90:93], v[158:161], v[206:209], v[90:93]
	v_mfma_f32_16x16x32_bf16 v[78:81], v[134:137], v[218:221], v[78:81]
	v_mfma_f32_16x16x32_bf16 v[74:77], v[158:161], v[218:221], v[74:77]
	s_setprio 0
	s_setprio 1
	v_mfma_f32_16x16x32_bf16 v[118:121], v[162:165], v[186:189], v[118:121]
	v_mfma_f32_16x16x32_bf16 v[114:117], v[178:181], v[186:189], v[114:117]
	v_mfma_f32_16x16x32_bf16 v[102:105], v[162:165], v[194:197], v[102:105]
	v_mfma_f32_16x16x32_bf16 v[98:101], v[178:181], v[194:197], v[98:101]
	v_mfma_f32_16x16x32_bf16 v[86:89], v[162:165], v[202:205], v[86:89]
	v_mfma_f32_16x16x32_bf16 v[82:85], v[178:181], v[202:205], v[82:85]
	v_mfma_f32_16x16x32_bf16 v[70:73], v[162:165], v[210:213], v[70:73]
	v_mfma_f32_16x16x32_bf16 v[66:69], v[178:181], v[210:213], v[66:69]
	v_mfma_f32_16x16x32_bf16 v[118:121], v[166:169], v[190:193], v[118:121]
	v_mfma_f32_16x16x32_bf16 v[114:117], v[182:185], v[190:193], v[114:117]
	v_mfma_f32_16x16x32_bf16 v[102:105], v[166:169], v[198:201], v[102:105]
	v_mfma_f32_16x16x32_bf16 v[98:101], v[182:185], v[198:201], v[98:101]
	v_mfma_f32_16x16x32_bf16 v[86:89], v[166:169], v[206:209], v[86:89]
	v_mfma_f32_16x16x32_bf16 v[82:85], v[182:185], v[206:209], v[82:85]
	v_mfma_f32_16x16x32_bf16 v[70:73], v[166:169], v[218:221], v[70:73]
	v_mfma_f32_16x16x32_bf16 v[66:69], v[182:185], v[218:221], v[66:69]
	s_setprio 0
	s_barrier
	s_add_i32 s44, s61, s46
	v_lshl_add_u64 v[170:171], v[170:171], 0, s[12:13]
	s_mov_b32 m0, s44
	ds_read_b128 v[186:189], v176 offset:49152
	ds_read_b128 v[190:193], v176 offset:50176
	ds_read_b128 v[194:197], v176 offset:51200
	ds_read_b128 v[198:201], v176 offset:52224
	ds_read_b128 v[202:205], v176 offset:53248
	ds_read_b128 v[206:209], v176 offset:54272
	ds_read_b128 v[210:213], v176 offset:55296
	ds_read_b128 v[218:221], v176 offset:56320
	global_load_lds_dwordx4 v[170:171], off
	s_add_i32 m0, s44, 0x2000
	s_add_u32 s34, s34, 0x80080
	v_lshl_add_u64 v[170:171], v[214:215], 0, s[12:13]
	s_addc_u32 s35, s35, 0
	s_add_i32 s44, s62, s46
	global_load_lds_dwordx4 v[170:171], off
	v_lshl_add_u64 v[170:171], s[34:35], 0, v[144:145]
	s_mov_b32 m0, s44
	s_nop 0
	global_load_lds_dwordx4 v[170:171], off
	v_lshl_add_u64 v[170:171], s[34:35], 0, v[148:149]
	s_add_i32 m0, s44, 0x2000
	s_nop 0
	global_load_lds_dwordx4 v[170:171], off
	v_lshl_add_u64 v[170:171], v[222:223], 0, s[12:13]
	s_mov_b32 m0, s51
	s_nop 0
	global_load_lds_dwordx4 v[170:171], off
	v_lshl_add_u64 v[170:171], v[224:225], 0, s[12:13]
	s_mov_b32 m0, s52
	s_nop 0
	global_load_lds_dwordx4 v[170:171], off
	s_waitcnt vmcnt(8)
	s_waitcnt lgkmcnt(0)
	s_barrier
	s_setprio 1
	s_waitcnt lgkmcnt(0)
	v_mfma_f32_16x16x32_bf16 v[62:65], v[130:133], v[186:189], v[62:65]
	v_mfma_f32_16x16x32_bf16 v[58:61], v[138:141], v[186:189], v[58:61]
	v_mfma_f32_16x16x32_bf16 v[50:53], v[130:133], v[194:197], v[50:53]
	v_mfma_f32_16x16x32_bf16 v[42:45], v[138:141], v[194:197], v[42:45]
	v_mfma_f32_16x16x32_bf16 v[38:41], v[130:133], v[202:205], v[38:41]
	v_mfma_f32_16x16x32_bf16 v[34:37], v[138:141], v[202:205], v[34:37]
	v_mfma_f32_16x16x32_bf16 v[14:17], v[130:133], v[210:213], v[14:17]
	v_mfma_f32_16x16x32_bf16 v[10:13], v[138:141], v[210:213], v[10:13]
	v_mfma_f32_16x16x32_bf16 v[62:65], v[134:137], v[190:193], v[62:65]
	v_mfma_f32_16x16x32_bf16 v[58:61], v[158:161], v[190:193], v[58:61]
	v_mfma_f32_16x16x32_bf16 v[50:53], v[134:137], v[198:201], v[50:53]
	v_mfma_f32_16x16x32_bf16 v[42:45], v[158:161], v[198:201], v[42:45]
	v_mfma_f32_16x16x32_bf16 v[38:41], v[134:137], v[206:209], v[38:41]
	v_mfma_f32_16x16x32_bf16 v[34:37], v[158:161], v[206:209], v[34:37]
	v_mfma_f32_16x16x32_bf16 v[14:17], v[134:137], v[218:221], v[14:17]
	v_mfma_f32_16x16x32_bf16 v[10:13], v[158:161], v[218:221], v[10:13]
	s_setprio 0
	s_setprio 1
	v_mfma_f32_16x16x32_bf16 v[54:57], v[162:165], v[186:189], v[54:57]
	v_mfma_f32_16x16x32_bf16 v[46:49], v[178:181], v[186:189], v[46:49]
	v_mfma_f32_16x16x32_bf16 v[30:33], v[162:165], v[194:197], v[30:33]
	v_mfma_f32_16x16x32_bf16 v[26:29], v[178:181], v[194:197], v[26:29]
	v_mfma_f32_16x16x32_bf16 v[22:25], v[162:165], v[202:205], v[22:25]
	v_mfma_f32_16x16x32_bf16 v[18:21], v[178:181], v[202:205], v[18:21]
	v_mfma_f32_16x16x32_bf16 v[6:9], v[162:165], v[210:213], v[6:9]
	v_mfma_f32_16x16x32_bf16 v[2:5], v[178:181], v[210:213], v[2:5]
	v_mfma_f32_16x16x32_bf16 v[54:57], v[166:169], v[190:193], v[54:57]
	v_mfma_f32_16x16x32_bf16 v[46:49], v[182:185], v[190:193], v[46:49]
	v_mfma_f32_16x16x32_bf16 v[30:33], v[166:169], v[198:201], v[30:33]
	v_mfma_f32_16x16x32_bf16 v[26:29], v[182:185], v[198:201], v[26:29]
	v_mfma_f32_16x16x32_bf16 v[22:25], v[166:169], v[206:209], v[22:25]
	v_mfma_f32_16x16x32_bf16 v[18:21], v[182:185], v[206:209], v[18:21]
	v_mfma_f32_16x16x32_bf16 v[6:9], v[166:169], v[218:221], v[6:9]
	v_mfma_f32_16x16x32_bf16 v[2:5], v[182:185], v[218:221], v[2:5]
	s_setprio 0
	s_barrier
	s_add_i32 s60, s60, 2
	s_add_u32 s42, s42, 0x100
	s_addc_u32 s43, s43, 0
	s_add_u32 s58, s58, 0x100
	s_addc_u32 s59, s59, 0
	s_cmp_gt_u32 s60, 29
	s_cbranch_scc0 .LBB0_3706
	s_and_b64 vcc, exec, s[14:15]
	s_cbranch_vccz .LBB0_3709
	s_barrier
.LBB0_3709:
	v_lshl_or_b32 v130, s57, 8, v173
	v_lshl_add_u32 v158, s40, 8, v1
	v_ashrrev_i32_e32 v131, 31, v130
	v_lshlrev_b64 v[160:161], 1, v[130:131]
	v_or_b32_e32 v130, 16, v158
	v_ashrrev_i32_e32 v159, 31, v158
	v_ashrrev_i32_e32 v131, 31, v130
	v_lshlrev_b64 v[132:133], 12, v[158:159]
	v_lshlrev_b64 v[130:131], 12, v[130:131]
	v_lshl_add_u64 v[132:133], s[64:65], 0, v[132:133]
	v_lshl_add_u64 v[130:131], s[64:65], 0, v[130:131]
	v_lshl_add_u64 v[170:171], v[132:133], 0, v[160:161]
	v_lshl_add_u64 v[168:169], v[130:131], 0, v[160:161]
	global_load_dwordx4 v[134:137], v[170:171], off
	global_load_dwordx4 v[138:141], v[170:171], off offset:64
	global_load_dwordx4 v[178:181], v[168:169], off
	global_load_dwordx4 v[182:185], v[168:169], off offset:64
	v_or_b32_e32 v130, 32, v158
	v_ashrrev_i32_e32 v131, 31, v130
	v_lshlrev_b64 v[130:131], 12, v[130:131]
	v_lshl_add_u64 v[130:131], s[64:65], 0, v[130:131]
	v_lshl_add_u64 v[162:163], v[130:131], 0, v[160:161]
	global_load_dwordx4 v[186:189], v[162:163], off
	global_load_dwordx4 v[190:193], v[162:163], off offset:64
	v_or_b32_e32 v130, 48, v158
	v_ashrrev_i32_e32 v131, 31, v130
	v_lshlrev_b64 v[130:131], 12, v[130:131]
	v_lshl_add_u64 v[130:131], s[64:65], 0, v[130:131]
	v_lshl_add_u64 v[166:167], v[130:131], 0, v[160:161]
	v_add_co_u32_e32 v164, vcc, s56, v170
	s_mov_b64 s[0:1], -1
	s_nop 0
	v_addc_co_u32_e32 v165, vcc, 0, v171, vcc
	global_load_dwordx4 v[194:197], v[166:167], off
	global_load_dwordx4 v[198:201], v[166:167], off offset:64
	global_load_dwordx4 v[130:133], v[164:165], off
	s_andn2_b64 vcc, exec, s[2:3]
	s_waitcnt vmcnt(0)
	v_cvt_f32_f16_e32 v202, v134
	v_cvt_f32_f16_e32 v210, v178
	v_cvt_f32_f16_sdwa v211, v178 dst_sel:DWORD dst_unused:UNUSED_PAD src0_sel:WORD_1
	v_cvt_f32_f16_e32 v212, v180
	v_cvt_f32_f16_sdwa v213, v180 dst_sel:DWORD dst_unused:UNUSED_PAD src0_sel:WORD_1
	v_cvt_f32_f16_e32 v180, v181
	v_cvt_f32_f16_sdwa v181, v181 dst_sel:DWORD dst_unused:UNUSED_PAD src0_sel:WORD_1
	v_cvt_f32_f16_e32 v218, v184
	v_cvt_f32_f16_sdwa v219, v184 dst_sel:DWORD dst_unused:UNUSED_PAD src0_sel:WORD_1
	v_cvt_f32_f16_e32 v214, v182
	v_cvt_f32_f16_sdwa v215, v182 dst_sel:DWORD dst_unused:UNUSED_PAD src0_sel:WORD_1
	v_cvt_f32_f16_sdwa v203, v134 dst_sel:DWORD dst_unused:UNUSED_PAD src0_sel:WORD_1
	v_cvt_f32_f16_e32 v134, v135
	v_cvt_f32_f16_sdwa v135, v135 dst_sel:DWORD dst_unused:UNUSED_PAD src0_sel:WORD_1
	v_cvt_f32_f16_e32 v204, v136
	v_cvt_f32_f16_sdwa v205, v136 dst_sel:DWORD dst_unused:UNUSED_PAD src0_sel:WORD_1
	v_cvt_f32_f16_e32 v136, v137
	v_cvt_f32_f16_sdwa v137, v137 dst_sel:DWORD dst_unused:UNUSED_PAD src0_sel:WORD_1
	v_cvt_f32_f16_e32 v206, v138
	v_cvt_f32_f16_sdwa v207, v138 dst_sel:DWORD dst_unused:UNUSED_PAD src0_sel:WORD_1
	v_cvt_f32_f16_e32 v138, v139
	v_cvt_f32_f16_sdwa v139, v139 dst_sel:DWORD dst_unused:UNUSED_PAD src0_sel:WORD_1
	v_cvt_f32_f16_e32 v208, v140
	v_cvt_f32_f16_sdwa v209, v140 dst_sel:DWORD dst_unused:UNUSED_PAD src0_sel:WORD_1
	v_cvt_f32_f16_e32 v140, v141
	v_cvt_f32_f16_sdwa v141, v141 dst_sel:DWORD dst_unused:UNUSED_PAD src0_sel:WORD_1
	v_cvt_f32_f16_e32 v178, v179
	v_cvt_f32_f16_sdwa v179, v179 dst_sel:DWORD dst_unused:UNUSED_PAD src0_sel:WORD_1
	v_pk_add_f32 v[110:111], v[110:111], v[210:211]
	v_pk_add_f32 v[108:109], v[108:109], v[180:181]
	v_pk_add_f32 v[106:107], v[106:107], v[212:213]
	v_pk_add_f32 v[98:99], v[98:99], v[218:219]
	v_cvt_pk_f16_f32 v109, v108, v109
	v_cvt_pk_f16_f32 v108, v106, v107
	v_cvt_pk_f16_f32 v106, v110, v111
	v_pk_add_f32 v[110:111], v[102:103], v[214:215]
	v_cvt_pk_f16_f32 v102, v98, v99
	v_add_u32_e32 v98, 0x90, v158
	v_cvt_f32_f16_e32 v182, v183
	v_cvt_f32_f16_sdwa v183, v183 dst_sel:DWORD dst_unused:UNUSED_PAD src0_sel:WORD_1
	v_ashrrev_i32_e32 v99, 31, v98
	v_pk_add_f32 v[128:129], v[128:129], v[134:135]
	v_pk_add_f32 v[126:127], v[126:127], v[202:203]
	v_pk_add_f32 v[124:125], v[124:125], v[136:137]
	v_pk_add_f32 v[122:123], v[122:123], v[204:205]
	v_lshlrev_b64 v[98:99], 12, v[98:99]
	v_pk_add_f32 v[134:135], v[120:121], v[138:139]
	v_pk_add_f32 v[136:137], v[118:119], v[206:207]
	v_pk_add_f32 v[118:119], v[116:117], v[140:141]
	v_pk_add_f32 v[138:139], v[114:115], v[208:209]
	v_cvt_pk_f16_f32 v117, v124, v125
	v_cvt_pk_f16_f32 v116, v122, v123
	v_cvt_pk_f16_f32 v115, v128, v129
	v_cvt_pk_f16_f32 v114, v126, v127
	v_pk_add_f32 v[112:113], v[112:113], v[178:179]
	v_lshl_add_u64 v[98:99], s[64:65], 0, v[98:99]
	v_cvt_pk_f16_f32 v121, v118, v119
	v_cvt_pk_f16_f32 v120, v138, v139
	v_cvt_pk_f16_f32 v119, v134, v135
	v_cvt_pk_f16_f32 v118, v136, v137
	global_store_dwordx4 v[170:171], v[114:117], off
	global_store_dwordx4 v[170:171], v[118:121], off offset:64
	v_cvt_pk_f16_f32 v107, v112, v113
	v_lshl_add_u64 v[98:99], v[98:99], 0, v[160:161]
	global_store_dwordx4 v[168:169], v[106:109], off
	v_cvt_f32_f16_e32 v184, v185
	v_cvt_f32_f16_sdwa v185, v185 dst_sel:DWORD dst_unused:UNUSED_PAD src0_sel:WORD_1
	v_pk_add_f32 v[108:109], v[104:105], v[182:183]
	global_load_dwordx4 v[104:107], v[98:99], off
	v_cvt_f32_f16_e32 v126, v192
	v_cvt_f32_f16_sdwa v127, v192 dst_sel:DWORD dst_unused:UNUSED_PAD src0_sel:WORD_1
	v_cvt_f32_f16_e32 v128, v193
	v_cvt_f32_f16_sdwa v129, v193 dst_sel:DWORD dst_unused:UNUSED_PAD src0_sel:WORD_1
	v_cvt_f32_f16_e32 v220, v186
	v_cvt_f32_f16_sdwa v221, v186 dst_sel:DWORD dst_unused:UNUSED_PAD src0_sel:WORD_1
	v_cvt_f32_f16_e32 v186, v187
	v_cvt_f32_f16_sdwa v187, v187 dst_sel:DWORD dst_unused:UNUSED_PAD src0_sel:WORD_1
	v_cvt_f32_f16_e32 v222, v188
	v_cvt_f32_f16_sdwa v223, v188 dst_sel:DWORD dst_unused:UNUSED_PAD src0_sel:WORD_1
	v_cvt_f32_f16_e32 v120, v189
	v_cvt_f32_f16_sdwa v121, v189 dst_sel:DWORD dst_unused:UNUSED_PAD src0_sel:WORD_1
	v_lshl_add_u64 v[114:115], v[170:171], 0, s[6:7]
	v_pk_add_f32 v[100:101], v[100:101], v[184:185]
	v_cvt_f32_f16_e32 v122, v190
	v_cvt_f32_f16_sdwa v123, v190 dst_sel:DWORD dst_unused:UNUSED_PAD src0_sel:WORD_1
	v_cvt_f32_f16_e32 v124, v191
	global_load_dwordx4 v[116:119], v[114:115], off offset:64
	v_cvt_f32_f16_sdwa v125, v191 dst_sel:DWORD dst_unused:UNUSED_PAD src0_sel:WORD_1
	v_cvt_pk_f16_f32 v103, v100, v101
	v_cvt_pk_f16_f32 v101, v108, v109
	v_cvt_pk_f16_f32 v100, v110, v111
	v_pk_add_f32 v[84:85], v[84:85], v[128:129]
	v_pk_add_f32 v[82:83], v[82:83], v[126:127]
	global_store_dwordx4 v[168:169], v[100:103], off offset:64
	v_cvt_f32_f16_e32 v136, v198
	v_cvt_f32_f16_sdwa v137, v198 dst_sel:DWORD dst_unused:UNUSED_PAD src0_sel:WORD_1
	v_cvt_f32_f16_e32 v138, v199
	v_cvt_f32_f16_sdwa v139, v199 dst_sel:DWORD dst_unused:UNUSED_PAD src0_sel:WORD_1
	v_cvt_f32_f16_e32 v140, v200
	v_cvt_f32_f16_sdwa v141, v200 dst_sel:DWORD dst_unused:UNUSED_PAD src0_sel:WORD_1
	v_cvt_f32_f16_e32 v168, v201
	v_cvt_f32_f16_sdwa v169, v201 dst_sel:DWORD dst_unused:UNUSED_PAD src0_sel:WORD_1
	v_cvt_pk_f16_f32 v85, v84, v85
	v_cvt_pk_f16_f32 v84, v82, v83
	v_add_u32_e32 v82, 0xa0, v158
	v_pk_add_f32 v[96:97], v[96:97], v[186:187]
	v_pk_add_f32 v[94:95], v[94:95], v[220:221]
	v_pk_add_f32 v[92:93], v[92:93], v[120:121]
	v_pk_add_f32 v[90:91], v[90:91], v[222:223]
	v_ashrrev_i32_e32 v83, 31, v82
	v_cvt_pk_f16_f32 v93, v92, v93
	v_cvt_pk_f16_f32 v92, v90, v91
	v_cvt_pk_f16_f32 v91, v96, v97
	v_cvt_pk_f16_f32 v90, v94, v95
	v_lshlrev_b64 v[82:83], 12, v[82:83]
	global_load_dwordx4 v[100:103], v[98:99], off offset:64
	v_lshl_add_u64 v[82:83], s[64:65], 0, v[82:83]
	global_store_dwordx4 v[162:163], v[90:93], off
	v_cvt_f32_f16_e32 v108, v194
	v_cvt_f32_f16_sdwa v109, v194 dst_sel:DWORD dst_unused:UNUSED_PAD src0_sel:WORD_1
	v_pk_add_f32 v[90:91], v[88:89], v[124:125]
	v_pk_add_f32 v[92:93], v[86:87], v[122:123]
	v_cvt_f32_f16_e32 v110, v195
	v_cvt_f32_f16_sdwa v111, v195 dst_sel:DWORD dst_unused:UNUSED_PAD src0_sel:WORD_1
	v_cvt_f32_f16_e32 v112, v196
	v_cvt_f32_f16_sdwa v113, v196 dst_sel:DWORD dst_unused:UNUSED_PAD src0_sel:WORD_1
	v_cvt_f32_f16_e32 v134, v197
	v_cvt_f32_f16_sdwa v135, v197 dst_sel:DWORD dst_unused:UNUSED_PAD src0_sel:WORD_1
	v_lshl_add_u64 v[94:95], v[82:83], 0, v[160:161]
	v_cvt_pk_f16_f32 v83, v90, v91
	v_cvt_pk_f16_f32 v82, v92, v93
	v_pk_add_f32 v[72:73], v[72:73], v[138:139]
	v_pk_add_f32 v[70:71], v[70:71], v[136:137]
	v_pk_add_f32 v[68:69], v[68:69], v[168:169]
	v_pk_add_f32 v[66:67], v[66:67], v[140:141]
	global_load_dwordx4 v[86:89], v[94:95], off
	v_cvt_pk_f16_f32 v69, v68, v69
	global_store_dwordx4 v[162:163], v[82:85], off offset:64
	global_load_dwordx4 v[82:85], v[94:95], off offset:64
	v_cvt_pk_f16_f32 v68, v66, v67
	v_cvt_pk_f16_f32 v67, v72, v73
	v_cvt_pk_f16_f32 v66, v70, v71
	global_store_dwordx4 v[166:167], v[66:69], off offset:64
	v_pk_add_f32 v[80:81], v[80:81], v[110:111]
	v_pk_add_f32 v[78:79], v[78:79], v[108:109]
	v_add_u32_e32 v66, 0xb0, v158
	v_ashrrev_i32_e32 v67, 31, v66
	v_pk_add_f32 v[76:77], v[76:77], v[134:135]
	v_pk_add_f32 v[74:75], v[74:75], v[112:113]
	v_lshlrev_b64 v[66:67], 12, v[66:67]
	v_cvt_pk_f16_f32 v77, v76, v77
	v_cvt_pk_f16_f32 v76, v74, v75
	v_cvt_pk_f16_f32 v75, v80, v81
	v_cvt_pk_f16_f32 v74, v78, v79
	v_lshl_add_u64 v[66:67], s[64:65], 0, v[66:67]
	global_store_dwordx4 v[166:167], v[74:77], off
	v_cvt_f32_f16_e32 v90, v130
	v_cvt_f32_f16_sdwa v91, v130 dst_sel:DWORD dst_unused:UNUSED_PAD src0_sel:WORD_1
	s_waitcnt vmcnt(9)
	v_cvt_f32_f16_e32 v74, v104
	v_cvt_f32_f16_sdwa v75, v104 dst_sel:DWORD dst_unused:UNUSED_PAD src0_sel:WORD_1
	v_cvt_f32_f16_e32 v76, v105
	v_cvt_f32_f16_sdwa v77, v105 dst_sel:DWORD dst_unused:UNUSED_PAD src0_sel:WORD_1
	v_lshl_add_u64 v[104:105], v[66:67], 0, v[160:161]
	global_load_dwordx4 v[66:69], v[104:105], off
	global_load_dwordx4 v[70:73], v[104:105], off offset:64
	v_cvt_f32_f16_e32 v92, v131
	v_cvt_f32_f16_sdwa v93, v131 dst_sel:DWORD dst_unused:UNUSED_PAD src0_sel:WORD_1
	v_cvt_f32_f16_e32 v96, v132
	v_cvt_f32_f16_sdwa v97, v132 dst_sel:DWORD dst_unused:UNUSED_PAD src0_sel:WORD_1
	v_cvt_f32_f16_e32 v120, v133
	v_cvt_f32_f16_sdwa v121, v133 dst_sel:DWORD dst_unused:UNUSED_PAD src0_sel:WORD_1
	s_waitcnt vmcnt(10)
	v_cvt_f32_f16_e32 v122, v116
	v_cvt_f32_f16_sdwa v123, v116 dst_sel:DWORD dst_unused:UNUSED_PAD src0_sel:WORD_1
	v_cvt_f32_f16_e32 v116, v117
	v_cvt_f32_f16_sdwa v117, v117 dst_sel:DWORD dst_unused:UNUSED_PAD src0_sel:WORD_1
	v_cvt_f32_f16_e32 v124, v118
	v_cvt_f32_f16_sdwa v125, v118 dst_sel:DWORD dst_unused:UNUSED_PAD src0_sel:WORD_1
	v_cvt_f32_f16_e32 v118, v119
	v_cvt_f32_f16_sdwa v119, v119 dst_sel:DWORD dst_unused:UNUSED_PAD src0_sel:WORD_1
	v_cvt_f32_f16_e32 v78, v106
	v_cvt_f32_f16_sdwa v79, v106 dst_sel:DWORD dst_unused:UNUSED_PAD src0_sel:WORD_1
	v_cvt_f32_f16_e32 v80, v107
	v_cvt_f32_f16_sdwa v81, v107 dst_sel:DWORD dst_unused:UNUSED_PAD src0_sel:WORD_1
	v_pk_add_f32 v[64:65], v[64:65], v[92:93]
	v_pk_add_f32 v[62:63], v[62:63], v[90:91]
	v_pk_add_f32 v[60:61], v[60:61], v[120:121]
	v_pk_add_f32 v[58:59], v[58:59], v[96:97]
	v_pk_add_f32 v[56:57], v[56:57], v[116:117]
	v_pk_add_f32 v[54:55], v[54:55], v[122:123]
	v_pk_add_f32 v[48:49], v[48:49], v[118:119]
	v_pk_add_f32 v[46:47], v[46:47], v[124:125]
	v_cvt_pk_f16_f32 v61, v60, v61
	v_cvt_pk_f16_f32 v60, v58, v59
	v_cvt_pk_f16_f32 v59, v64, v65
	v_cvt_pk_f16_f32 v58, v62, v63
	v_cvt_pk_f16_f32 v49, v48, v49
	s_waitcnt vmcnt(8)
	v_cvt_f32_f16_e32 v106, v100
	v_cvt_f32_f16_sdwa v107, v100 dst_sel:DWORD dst_unused:UNUSED_PAD src0_sel:WORD_1
	v_cvt_f32_f16_e32 v100, v101
	v_cvt_f32_f16_sdwa v101, v101 dst_sel:DWORD dst_unused:UNUSED_PAD src0_sel:WORD_1
	v_cvt_f32_f16_e32 v108, v102
	v_cvt_f32_f16_sdwa v109, v102 dst_sel:DWORD dst_unused:UNUSED_PAD src0_sel:WORD_1
	v_cvt_f32_f16_e32 v102, v103
	v_cvt_f32_f16_sdwa v103, v103 dst_sel:DWORD dst_unused:UNUSED_PAD src0_sel:WORD_1
	v_cvt_pk_f16_f32 v48, v46, v47
	v_cvt_pk_f16_f32 v47, v56, v57
	v_cvt_pk_f16_f32 v46, v54, v55
	global_store_dwordx4 v[164:165], v[58:61], off
	global_store_dwordx4 v[114:115], v[46:49], off offset:64
	v_pk_add_f32 v[32:33], v[32:33], v[100:101]
	v_pk_add_f32 v[30:31], v[30:31], v[106:107]
	v_pk_add_f32 v[28:29], v[28:29], v[102:103]
	v_pk_add_f32 v[26:27], v[26:27], v[108:109]
	v_cvt_pk_f16_f32 v29, v28, v29
	v_cvt_pk_f16_f32 v28, v26, v27
	v_cvt_pk_f16_f32 v27, v32, v33
	s_waitcnt vmcnt(8)
	v_cvt_f32_f16_e32 v46, v86
	v_cvt_f32_f16_sdwa v47, v86 dst_sel:DWORD dst_unused:UNUSED_PAD src0_sel:WORD_1
	v_cvt_f32_f16_e32 v48, v87
	v_cvt_f32_f16_sdwa v49, v87 dst_sel:DWORD dst_unused:UNUSED_PAD src0_sel:WORD_1
	v_cvt_f32_f16_e32 v54, v88
	v_cvt_f32_f16_sdwa v55, v88 dst_sel:DWORD dst_unused:UNUSED_PAD src0_sel:WORD_1
	v_cvt_f32_f16_e32 v56, v89
	v_cvt_f32_f16_sdwa v57, v89 dst_sel:DWORD dst_unused:UNUSED_PAD src0_sel:WORD_1
	s_waitcnt vmcnt(6)
	v_cvt_f32_f16_e32 v58, v82
	v_cvt_f32_f16_sdwa v59, v82 dst_sel:DWORD dst_unused:UNUSED_PAD src0_sel:WORD_1
	v_cvt_f32_f16_e32 v60, v83
	v_cvt_f32_f16_sdwa v61, v83 dst_sel:DWORD dst_unused:UNUSED_PAD src0_sel:WORD_1
	v_cvt_f32_f16_e32 v62, v84
	v_cvt_f32_f16_sdwa v63, v84 dst_sel:DWORD dst_unused:UNUSED_PAD src0_sel:WORD_1
	v_cvt_f32_f16_e32 v64, v85
	v_cvt_f32_f16_sdwa v65, v85 dst_sel:DWORD dst_unused:UNUSED_PAD src0_sel:WORD_1
	v_cvt_pk_f16_f32 v26, v30, v31
	global_store_dwordx4 v[98:99], v[26:29], off offset:64
	v_pk_add_f32 v[30:31], v[38:39], v[46:47]
	v_pk_add_f32 v[32:33], v[34:35], v[54:55]
	v_pk_add_f32 v[26:27], v[40:41], v[48:49]
	v_pk_add_f32 v[28:29], v[36:37], v[56:57]
	v_pk_add_f32 v[24:25], v[24:25], v[60:61]
	v_pk_add_f32 v[22:23], v[22:23], v[58:59]
	v_pk_add_f32 v[20:21], v[20:21], v[64:65]
	v_pk_add_f32 v[18:19], v[18:19], v[62:63]
	v_cvt_pk_f16_f32 v29, v28, v29
	v_cvt_pk_f16_f32 v28, v32, v33
	v_cvt_pk_f16_f32 v27, v26, v27
	v_cvt_pk_f16_f32 v26, v30, v31
	v_cvt_pk_f16_f32 v21, v20, v21
	v_cvt_pk_f16_f32 v20, v18, v19
	v_cvt_pk_f16_f32 v19, v24, v25
	v_cvt_pk_f16_f32 v18, v22, v23
	global_store_dwordx4 v[94:95], v[26:29], off
	global_store_dwordx4 v[94:95], v[18:21], off offset:64
	s_waitcnt vmcnt(5)
	v_cvt_f32_f16_e32 v22, v70
	v_cvt_f32_f16_sdwa v23, v70 dst_sel:DWORD dst_unused:UNUSED_PAD src0_sel:WORD_1
	v_cvt_f32_f16_e32 v18, v72
	v_cvt_f32_f16_sdwa v19, v72 dst_sel:DWORD dst_unused:UNUSED_PAD src0_sel:WORD_1
	v_cvt_f32_f16_e32 v20, v73
	v_cvt_f32_f16_sdwa v21, v73 dst_sel:DWORD dst_unused:UNUSED_PAD src0_sel:WORD_1
	v_cvt_f32_f16_e32 v24, v71
	v_cvt_f32_f16_sdwa v25, v71 dst_sel:DWORD dst_unused:UNUSED_PAD src0_sel:WORD_1
	v_cvt_f32_f16_e32 v26, v68
	v_cvt_f32_f16_e32 v28, v69
	v_cvt_f32_f16_e32 v30, v66
	v_cvt_f32_f16_e32 v32, v67
	v_cvt_f32_f16_sdwa v33, v67 dst_sel:DWORD dst_unused:UNUSED_PAD src0_sel:WORD_1
	v_cvt_f32_f16_sdwa v31, v66 dst_sel:DWORD dst_unused:UNUSED_PAD src0_sel:WORD_1
	v_cvt_f32_f16_sdwa v29, v69 dst_sel:DWORD dst_unused:UNUSED_PAD src0_sel:WORD_1
	v_cvt_f32_f16_sdwa v27, v68 dst_sel:DWORD dst_unused:UNUSED_PAD src0_sel:WORD_1
	v_pk_add_f32 v[52:53], v[52:53], v[76:77]
	v_pk_add_f32 v[50:51], v[50:51], v[74:75]
	v_pk_add_f32 v[44:45], v[44:45], v[80:81]
	v_pk_add_f32 v[42:43], v[42:43], v[78:79]
	v_pk_add_f32 v[16:17], v[16:17], v[32:33]
	v_pk_add_f32 v[14:15], v[14:15], v[30:31]
	v_pk_add_f32 v[12:13], v[12:13], v[28:29]
	v_pk_add_f32 v[10:11], v[10:11], v[26:27]
	v_pk_add_f32 v[8:9], v[8:9], v[24:25]
	v_pk_add_f32 v[6:7], v[6:7], v[22:23]
	v_pk_add_f32 v[4:5], v[4:5], v[20:21]
	v_pk_add_f32 v[2:3], v[2:3], v[18:19]
	v_cvt_pk_f16_f32 v45, v44, v45
	v_cvt_pk_f16_f32 v44, v42, v43
	v_cvt_pk_f16_f32 v43, v52, v53
	v_cvt_pk_f16_f32 v42, v50, v51
	v_cvt_pk_f16_f32 v13, v12, v13
	v_cvt_pk_f16_f32 v12, v10, v11
	v_cvt_pk_f16_f32 v11, v16, v17
	v_cvt_pk_f16_f32 v10, v14, v15
	v_cvt_pk_f16_f32 v5, v4, v5
	v_cvt_pk_f16_f32 v4, v2, v3
	v_cvt_pk_f16_f32 v3, v8, v9
	v_cvt_pk_f16_f32 v2, v6, v7
	global_store_dwordx4 v[98:99], v[42:45], off
	global_store_dwordx4 v[104:105], v[10:13], off
	global_store_dwordx4 v[104:105], v[2:5], off offset:64
	s_cbranch_vccnz .LBB0_3698
	s_andn2_b64 vcc, exec, s[8:9]
	s_cbranch_vccnz .LBB0_3697
	s_barrier
	s_branch .LBB0_3697
